# mid-block s_setprio 0/1 pairs removed from the MFMA blocks
# speedup vs baseline: 1.0046x; 1.0046x over previous
.LBB0_92:
	s_add_u32 s8, s6, 0xfffc0080
	s_addc_u32 s9, s7, -1
	s_add_i32 s35, 0, 0x10000
	s_cmp_eq_u32 s59, 12
	s_cselect_b32 s11, s5, s9
	s_cselect_b32 s10, s24, s8
	v_add_u32_e32 v140, s35, v165
	s_cselect_b32 s9, s47, s58
	s_cselect_b32 s8, s51, s53
	s_add_i32 s74, 0, 0x14000
	ds_read_b128 v[142:145], v140
	ds_read_b128 v[146:149], v140 offset:1024
	ds_read_b128 v[150:153], v140 offset:2048
	ds_read_b128 v[154:157], v140 offset:3072
	v_add_u32_e32 v140, s74, v165
	ds_read_b128 v[158:161], v140
	ds_read_b128 v[168:171], v140 offset:1024
	ds_read_b128 v[172:175], v140 offset:2048
	ds_read_b128 v[176:179], v140 offset:3072
	v_lshl_add_u64 v[162:163], s[6:7], 0, v[136:137]
	s_add_i32 m0, s27, 0xc000
	ds_read_b128 v[180:183], v166
	ds_read_b128 v[184:187], v166 offset:1024
	ds_read_b128 v[188:191], v166 offset:2048
	ds_read_b128 v[192:195], v166 offset:3072
	ds_read_b128 v[200:203], v166 offset:4096
	ds_read_b128 v[206:209], v166 offset:5120
	ds_read_b128 v[210:213], v166 offset:6144
	ds_read_b128 v[214:217], v166 offset:7168
	global_load_lds_dwordx4 v[162:163], off
	v_lshl_add_u64 v[162:163], s[6:7], 0, v[138:139]
	s_add_i32 m0, s27, 0xe000
	s_nop 0
	global_load_lds_dwordx4 v[162:163], off
	s_waitcnt vmcnt(8)
	s_waitcnt lgkmcnt(0)
	s_barrier
	s_setprio 1
	s_waitcnt lgkmcnt(0)
	v_mfma_f32_16x16x32_bf16 v[124:127], v[142:145], v[180:183], v[124:127]
	v_mfma_f32_16x16x32_bf16 v[120:123], v[150:153], v[180:183], v[120:123]
	v_mfma_f32_16x16x32_bf16 v[108:111], v[142:145], v[188:191], v[108:111]
	v_mfma_f32_16x16x32_bf16 v[104:107], v[150:153], v[188:191], v[104:107]
	v_mfma_f32_16x16x32_bf16 v[92:95], v[142:145], v[200:203], v[92:95]
	v_mfma_f32_16x16x32_bf16 v[88:91], v[150:153], v[200:203], v[88:91]
	v_mfma_f32_16x16x32_bf16 v[76:79], v[142:145], v[210:213], v[76:79]
	v_mfma_f32_16x16x32_bf16 v[72:75], v[150:153], v[210:213], v[72:75]
	v_mfma_f32_16x16x32_bf16 v[124:127], v[146:149], v[184:187], v[124:127]
	v_mfma_f32_16x16x32_bf16 v[120:123], v[154:157], v[184:187], v[120:123]
	v_mfma_f32_16x16x32_bf16 v[108:111], v[146:149], v[192:195], v[108:111]
	v_mfma_f32_16x16x32_bf16 v[104:107], v[154:157], v[192:195], v[104:107]
	v_mfma_f32_16x16x32_bf16 v[92:95], v[146:149], v[206:209], v[92:95]
	v_mfma_f32_16x16x32_bf16 v[88:91], v[154:157], v[206:209], v[88:91]
	v_mfma_f32_16x16x32_bf16 v[76:79], v[146:149], v[214:217], v[76:79]
	v_mfma_f32_16x16x32_bf16 v[72:75], v[154:157], v[214:217], v[72:75]
	v_mfma_f32_16x16x32_bf16 v[116:119], v[158:161], v[180:183], v[116:119]
	v_mfma_f32_16x16x32_bf16 v[112:115], v[172:175], v[180:183], v[112:115]
	v_mfma_f32_16x16x32_bf16 v[100:103], v[158:161], v[188:191], v[100:103]
	v_mfma_f32_16x16x32_bf16 v[96:99], v[172:175], v[188:191], v[96:99]
	v_mfma_f32_16x16x32_bf16 v[84:87], v[158:161], v[200:203], v[84:87]
	v_mfma_f32_16x16x32_bf16 v[80:83], v[172:175], v[200:203], v[80:83]
	v_mfma_f32_16x16x32_bf16 v[68:71], v[158:161], v[210:213], v[68:71]
	v_mfma_f32_16x16x32_bf16 v[64:67], v[172:175], v[210:213], v[64:67]
	v_mfma_f32_16x16x32_bf16 v[116:119], v[168:171], v[184:187], v[116:119]
	v_mfma_f32_16x16x32_bf16 v[112:115], v[176:179], v[184:187], v[112:115]
	v_mfma_f32_16x16x32_bf16 v[100:103], v[168:171], v[192:195], v[100:103]
	v_mfma_f32_16x16x32_bf16 v[96:99], v[176:179], v[192:195], v[96:99]
	v_mfma_f32_16x16x32_bf16 v[84:87], v[168:171], v[206:209], v[84:87]
	v_mfma_f32_16x16x32_bf16 v[80:83], v[176:179], v[206:209], v[80:83]
	v_mfma_f32_16x16x32_bf16 v[68:71], v[168:171], v[214:217], v[68:71]
	v_mfma_f32_16x16x32_bf16 v[64:67], v[176:179], v[214:217], v[64:67]
	s_setprio 0
	s_barrier
	s_add_i32 s35, s35, s13
	v_lshl_add_u64 v[162:163], s[8:9], 0, v[132:133]
	s_mov_b32 m0, s35
	ds_read_b128 v[180:183], v166 offset:16384
	ds_read_b128 v[184:187], v166 offset:17408
	ds_read_b128 v[188:191], v166 offset:18432
	ds_read_b128 v[192:195], v166 offset:19456
	ds_read_b128 v[200:203], v166 offset:20480
	ds_read_b128 v[206:209], v166 offset:21504
	ds_read_b128 v[210:213], v166 offset:22528
	ds_read_b128 v[214:217], v166 offset:23552
	global_load_lds_dwordx4 v[162:163], off
	s_add_i32 m0, s35, 0x2000
	s_add_u32 s60, s8, 0x40000
	v_lshl_add_u64 v[196:197], s[8:9], 0, v[128:129]
	s_addc_u32 s61, s9, 0
	s_add_i32 s35, s74, s13
	global_load_lds_dwordx4 v[196:197], off
	v_lshl_add_u64 v[198:199], s[60:61], 0, v[132:133]
	s_mov_b32 m0, s35
	v_lshl_add_u64 v[204:205], s[10:11], 0, v[130:131]
	global_load_lds_dwordx4 v[198:199], off
	v_lshl_add_u64 v[198:199], s[60:61], 0, v[128:129]
	s_add_i32 m0, s35, 0x2000
	s_nop 0
	global_load_lds_dwordx4 v[198:199], off
	v_lshl_add_u64 v[198:199], s[10:11], 0, v[134:135]
	s_mov_b32 m0, s27
	s_nop 0
	global_load_lds_dwordx4 v[198:199], off
	s_mov_b32 m0, s28
	s_nop 0
	global_load_lds_dwordx4 v[204:205], off
	s_waitcnt vmcnt(8)
	s_waitcnt lgkmcnt(0)
	s_barrier
	s_setprio 1
	s_waitcnt lgkmcnt(0)
	v_mfma_f32_16x16x32_bf16 v[60:63], v[142:145], v[180:183], v[60:63]
	v_mfma_f32_16x16x32_bf16 v[56:59], v[150:153], v[180:183], v[56:59]
	v_mfma_f32_16x16x32_bf16 v[44:47], v[142:145], v[188:191], v[44:47]
	v_mfma_f32_16x16x32_bf16 v[40:43], v[150:153], v[188:191], v[40:43]
	v_mfma_f32_16x16x32_bf16 v[28:31], v[142:145], v[200:203], v[28:31]
	v_mfma_f32_16x16x32_bf16 v[24:27], v[150:153], v[200:203], v[24:27]
	v_mfma_f32_16x16x32_bf16 v[12:15], v[142:145], v[210:213], v[12:15]
	v_mfma_f32_16x16x32_bf16 v[8:11], v[150:153], v[210:213], v[8:11]
	v_mfma_f32_16x16x32_bf16 v[60:63], v[146:149], v[184:187], v[60:63]
	v_mfma_f32_16x16x32_bf16 v[56:59], v[154:157], v[184:187], v[56:59]
	v_mfma_f32_16x16x32_bf16 v[44:47], v[146:149], v[192:195], v[44:47]
	v_mfma_f32_16x16x32_bf16 v[40:43], v[154:157], v[192:195], v[40:43]
	v_mfma_f32_16x16x32_bf16 v[28:31], v[146:149], v[206:209], v[28:31]
	v_mfma_f32_16x16x32_bf16 v[24:27], v[154:157], v[206:209], v[24:27]
	v_mfma_f32_16x16x32_bf16 v[12:15], v[146:149], v[214:217], v[12:15]
	v_mfma_f32_16x16x32_bf16 v[8:11], v[154:157], v[214:217], v[8:11]
	v_mfma_f32_16x16x32_bf16 v[52:55], v[158:161], v[180:183], v[52:55]
	v_mfma_f32_16x16x32_bf16 v[48:51], v[172:175], v[180:183], v[48:51]
	v_mfma_f32_16x16x32_bf16 v[36:39], v[158:161], v[188:191], v[36:39]
	v_mfma_f32_16x16x32_bf16 v[32:35], v[172:175], v[188:191], v[32:35]
	v_mfma_f32_16x16x32_bf16 v[20:23], v[158:161], v[200:203], v[20:23]
	v_mfma_f32_16x16x32_bf16 v[16:19], v[172:175], v[200:203], v[16:19]
	v_mfma_f32_16x16x32_bf16 v[4:7], v[158:161], v[210:213], v[4:7]
	v_mfma_f32_16x16x32_bf16 v[0:3], v[172:175], v[210:213], v[0:3]
	v_mfma_f32_16x16x32_bf16 v[52:55], v[168:171], v[184:187], v[52:55]
	v_mfma_f32_16x16x32_bf16 v[48:51], v[176:179], v[184:187], v[48:51]
	v_mfma_f32_16x16x32_bf16 v[36:39], v[168:171], v[192:195], v[36:39]
	v_mfma_f32_16x16x32_bf16 v[32:35], v[176:179], v[192:195], v[32:35]
	v_mfma_f32_16x16x32_bf16 v[20:23], v[168:171], v[206:209], v[20:23]
	v_mfma_f32_16x16x32_bf16 v[16:19], v[176:179], v[206:209], v[16:19]
	v_mfma_f32_16x16x32_bf16 v[4:7], v[168:171], v[214:217], v[4:7]
	v_mfma_f32_16x16x32_bf16 v[0:3], v[176:179], v[214:217], v[0:3]
	s_setprio 0
	s_barrier
	s_add_i32 s35, 0, 0x18000
	v_add_u32_e32 v140, s35, v165
	s_add_i32 s60, 0, 0x1c000
	ds_read_b128 v[142:145], v140
	ds_read_b128 v[146:149], v140 offset:1024
	ds_read_b128 v[150:153], v140 offset:2048
	ds_read_b128 v[154:157], v140 offset:3072
	v_add_u32_e32 v140, s60, v165
	ds_read_b128 v[158:161], v140
	ds_read_b128 v[168:171], v140 offset:1024
	ds_read_b128 v[172:175], v140 offset:2048
	ds_read_b128 v[176:179], v140 offset:3072
	s_add_u32 s10, s10, 0x40000
	s_addc_u32 s11, s11, 0
	s_mov_b32 m0, s29
	v_lshl_add_u64 v[218:219], s[10:11], 0, v[134:135]
	ds_read_b128 v[180:183], v166 offset:32768
	ds_read_b128 v[184:187], v166 offset:33792
	ds_read_b128 v[188:191], v166 offset:34816
	ds_read_b128 v[192:195], v166 offset:35840
	ds_read_b128 v[200:203], v166 offset:36864
	ds_read_b128 v[206:209], v166 offset:37888
	ds_read_b128 v[210:213], v166 offset:38912
	ds_read_b128 v[214:217], v166 offset:39936
	global_load_lds_dwordx4 v[218:219], off
	v_lshl_add_u64 v[218:219], s[10:11], 0, v[130:131]
	s_mov_b32 m0, s38
	s_nop 0
	global_load_lds_dwordx4 v[218:219], off
	s_waitcnt vmcnt(8)
	s_waitcnt lgkmcnt(0)
	s_barrier
	s_setprio 1
	s_waitcnt lgkmcnt(0)
	v_mfma_f32_16x16x32_bf16 v[124:127], v[142:145], v[180:183], v[124:127]
	v_mfma_f32_16x16x32_bf16 v[120:123], v[150:153], v[180:183], v[120:123]
	v_mfma_f32_16x16x32_bf16 v[108:111], v[142:145], v[188:191], v[108:111]
	v_mfma_f32_16x16x32_bf16 v[104:107], v[150:153], v[188:191], v[104:107]
	v_mfma_f32_16x16x32_bf16 v[92:95], v[142:145], v[200:203], v[92:95]
	v_mfma_f32_16x16x32_bf16 v[88:91], v[150:153], v[200:203], v[88:91]
	v_mfma_f32_16x16x32_bf16 v[76:79], v[142:145], v[210:213], v[76:79]
	v_mfma_f32_16x16x32_bf16 v[72:75], v[150:153], v[210:213], v[72:75]
	v_mfma_f32_16x16x32_bf16 v[124:127], v[146:149], v[184:187], v[124:127]
	v_mfma_f32_16x16x32_bf16 v[120:123], v[154:157], v[184:187], v[120:123]
	v_mfma_f32_16x16x32_bf16 v[108:111], v[146:149], v[192:195], v[108:111]
	v_mfma_f32_16x16x32_bf16 v[104:107], v[154:157], v[192:195], v[104:107]
	v_mfma_f32_16x16x32_bf16 v[92:95], v[146:149], v[206:209], v[92:95]
	v_mfma_f32_16x16x32_bf16 v[88:91], v[154:157], v[206:209], v[88:91]
	v_mfma_f32_16x16x32_bf16 v[76:79], v[146:149], v[214:217], v[76:79]
	v_mfma_f32_16x16x32_bf16 v[72:75], v[154:157], v[214:217], v[72:75]
	v_mfma_f32_16x16x32_bf16 v[116:119], v[158:161], v[180:183], v[116:119]
	v_mfma_f32_16x16x32_bf16 v[112:115], v[172:175], v[180:183], v[112:115]
	v_mfma_f32_16x16x32_bf16 v[100:103], v[158:161], v[188:191], v[100:103]
	v_mfma_f32_16x16x32_bf16 v[96:99], v[172:175], v[188:191], v[96:99]
	v_mfma_f32_16x16x32_bf16 v[84:87], v[158:161], v[200:203], v[84:87]
	v_mfma_f32_16x16x32_bf16 v[80:83], v[172:175], v[200:203], v[80:83]
	v_mfma_f32_16x16x32_bf16 v[68:71], v[158:161], v[210:213], v[68:71]
	v_mfma_f32_16x16x32_bf16 v[64:67], v[172:175], v[210:213], v[64:67]
	v_mfma_f32_16x16x32_bf16 v[116:119], v[168:171], v[184:187], v[116:119]
	v_mfma_f32_16x16x32_bf16 v[112:115], v[176:179], v[184:187], v[112:115]
	v_mfma_f32_16x16x32_bf16 v[100:103], v[168:171], v[192:195], v[100:103]
	v_mfma_f32_16x16x32_bf16 v[96:99], v[176:179], v[192:195], v[96:99]
	v_mfma_f32_16x16x32_bf16 v[84:87], v[168:171], v[206:209], v[84:87]
	v_mfma_f32_16x16x32_bf16 v[80:83], v[176:179], v[206:209], v[80:83]
	v_mfma_f32_16x16x32_bf16 v[68:71], v[168:171], v[214:217], v[68:71]
	v_mfma_f32_16x16x32_bf16 v[64:67], v[176:179], v[214:217], v[64:67]
	s_setprio 0
	s_barrier
	s_add_i32 s10, s35, s13
	v_lshl_add_u64 v[162:163], v[162:163], 0, s[36:37]
	s_mov_b32 m0, s10
	ds_read_b128 v[180:183], v166 offset:49152
	ds_read_b128 v[184:187], v166 offset:50176
	ds_read_b128 v[188:191], v166 offset:51200
	ds_read_b128 v[192:195], v166 offset:52224
	ds_read_b128 v[200:203], v166 offset:53248
	ds_read_b128 v[206:209], v166 offset:54272
	ds_read_b128 v[210:213], v166 offset:55296
	ds_read_b128 v[214:217], v166 offset:56320
	global_load_lds_dwordx4 v[162:163], off
	s_add_i32 m0, s10, 0x2000
	s_add_u32 s8, s8, 0x40080
	v_lshl_add_u64 v[162:163], v[196:197], 0, s[36:37]
	s_addc_u32 s9, s9, 0
	s_add_i32 s10, s60, s13
	global_load_lds_dwordx4 v[162:163], off
	v_lshl_add_u64 v[162:163], s[8:9], 0, v[132:133]
	s_mov_b32 m0, s10
	s_nop 0
	global_load_lds_dwordx4 v[162:163], off
	v_lshl_add_u64 v[162:163], s[8:9], 0, v[128:129]
	s_add_i32 m0, s10, 0x2000
	s_nop 0
	global_load_lds_dwordx4 v[162:163], off
	v_lshl_add_u64 v[162:163], v[198:199], 0, s[36:37]
	s_mov_b32 m0, s42
	s_nop 0
	global_load_lds_dwordx4 v[162:163], off
	v_lshl_add_u64 v[162:163], v[204:205], 0, s[36:37]
	s_mov_b32 m0, s43
	s_nop 0
	global_load_lds_dwordx4 v[162:163], off
	s_waitcnt vmcnt(8)
	s_waitcnt lgkmcnt(0)
	s_barrier
	s_setprio 1
	s_waitcnt lgkmcnt(0)
	v_mfma_f32_16x16x32_bf16 v[60:63], v[142:145], v[180:183], v[60:63]
	v_mfma_f32_16x16x32_bf16 v[56:59], v[150:153], v[180:183], v[56:59]
	v_mfma_f32_16x16x32_bf16 v[44:47], v[142:145], v[188:191], v[44:47]
	v_mfma_f32_16x16x32_bf16 v[40:43], v[150:153], v[188:191], v[40:43]
	v_mfma_f32_16x16x32_bf16 v[28:31], v[142:145], v[200:203], v[28:31]
	v_mfma_f32_16x16x32_bf16 v[24:27], v[150:153], v[200:203], v[24:27]
	v_mfma_f32_16x16x32_bf16 v[12:15], v[142:145], v[210:213], v[12:15]
	v_mfma_f32_16x16x32_bf16 v[8:11], v[150:153], v[210:213], v[8:11]
	v_mfma_f32_16x16x32_bf16 v[60:63], v[146:149], v[184:187], v[60:63]
	v_mfma_f32_16x16x32_bf16 v[56:59], v[154:157], v[184:187], v[56:59]
	v_mfma_f32_16x16x32_bf16 v[44:47], v[146:149], v[192:195], v[44:47]
	v_mfma_f32_16x16x32_bf16 v[40:43], v[154:157], v[192:195], v[40:43]
	v_mfma_f32_16x16x32_bf16 v[28:31], v[146:149], v[206:209], v[28:31]
	v_mfma_f32_16x16x32_bf16 v[24:27], v[154:157], v[206:209], v[24:27]
	v_mfma_f32_16x16x32_bf16 v[12:15], v[146:149], v[214:217], v[12:15]
	v_mfma_f32_16x16x32_bf16 v[8:11], v[154:157], v[214:217], v[8:11]
	v_mfma_f32_16x16x32_bf16 v[52:55], v[158:161], v[180:183], v[52:55]
	v_mfma_f32_16x16x32_bf16 v[48:51], v[172:175], v[180:183], v[48:51]
	v_mfma_f32_16x16x32_bf16 v[36:39], v[158:161], v[188:191], v[36:39]
	v_mfma_f32_16x16x32_bf16 v[32:35], v[172:175], v[188:191], v[32:35]
	v_mfma_f32_16x16x32_bf16 v[20:23], v[158:161], v[200:203], v[20:23]
	v_mfma_f32_16x16x32_bf16 v[16:19], v[172:175], v[200:203], v[16:19]
	v_mfma_f32_16x16x32_bf16 v[4:7], v[158:161], v[210:213], v[4:7]
	v_mfma_f32_16x16x32_bf16 v[0:3], v[172:175], v[210:213], v[0:3]
	v_mfma_f32_16x16x32_bf16 v[52:55], v[168:171], v[184:187], v[52:55]
	v_mfma_f32_16x16x32_bf16 v[48:51], v[176:179], v[184:187], v[48:51]
	v_mfma_f32_16x16x32_bf16 v[36:39], v[168:171], v[192:195], v[36:39]
	v_mfma_f32_16x16x32_bf16 v[32:35], v[176:179], v[192:195], v[32:35]
	v_mfma_f32_16x16x32_bf16 v[20:23], v[168:171], v[206:209], v[20:23]
	v_mfma_f32_16x16x32_bf16 v[16:19], v[176:179], v[206:209], v[16:19]
	v_mfma_f32_16x16x32_bf16 v[4:7], v[168:171], v[214:217], v[4:7]
	v_mfma_f32_16x16x32_bf16 v[0:3], v[176:179], v[214:217], v[0:3]
	s_setprio 0
	s_barrier
	s_add_i32 s59, s59, 2
	s_add_u32 s6, s6, 0x100
	s_addc_u32 s7, s7, 0
	s_add_u32 s53, s53, 0x100
	s_addc_u32 s58, s58, 0
	s_cmp_gt_u32 s59, 13
	s_cbranch_scc0 .LBB0_92
	s_and_b64 vcc, exec, s[48:49]
	s_cbranch_vccz .LBB0_95
	s_barrier

.LBB0_147:
	s_add_u32 s8, s6, 0xfffc0080
	s_addc_u32 s9, s7, -1
	s_add_i32 s35, 0, 0x10000
	s_cmp_eq_u32 s74, 12
	s_cselect_b32 s11, s24, s9
	s_cselect_b32 s10, s38, s8
	s_cselect_b32 s9, s53, s61
	s_cselect_b32 s8, s55, s60
	s_add_i32 s75, 0, 0x14000
	v_add_u32_e32 v142, s35, v178
	v_add_u32_e32 v168, s75, v178
	ds_read_b128 v[128:131], v142
	ds_read_b128 v[132:135], v142 offset:1024
	ds_read_b128 v[136:139], v142 offset:2048
	ds_read_b128 v[142:145], v142 offset:3072
	ds_read_b128 v[146:149], v168
	ds_read_b128 v[150:153], v168 offset:1024
	ds_read_b128 v[154:157], v168 offset:2048
	ds_read_b128 v[168:171], v168 offset:3072
	v_lshl_add_u64 v[176:177], s[6:7], 0, v[164:165]
	s_add_i32 m0, s15, 0xc000
	ds_read_b128 v[172:175], v179
	ds_read_b128 v[180:183], v179 offset:1024
	ds_read_b128 v[184:187], v179 offset:2048
	ds_read_b128 v[188:191], v179 offset:3072
	ds_read_b128 v[192:195], v179 offset:4096
	ds_read_b128 v[200:203], v179 offset:5120
	ds_read_b128 v[206:209], v179 offset:6144
	ds_read_b128 v[210:213], v179 offset:7168
	global_load_lds_dwordx4 v[176:177], off
	v_lshl_add_u64 v[176:177], s[6:7], 0, v[166:167]
	s_add_i32 m0, s15, 0xe000
	s_nop 0
	global_load_lds_dwordx4 v[176:177], off
	s_waitcnt vmcnt(8)
	s_waitcnt lgkmcnt(0)
	s_barrier
	s_setprio 1
	s_waitcnt lgkmcnt(0)
	v_mfma_f32_16x16x32_bf16 v[124:127], v[128:131], v[172:175], v[124:127]
	v_mfma_f32_16x16x32_bf16 v[120:123], v[136:139], v[172:175], v[120:123]
	v_mfma_f32_16x16x32_bf16 v[108:111], v[128:131], v[184:187], v[108:111]
	v_mfma_f32_16x16x32_bf16 v[104:107], v[136:139], v[184:187], v[104:107]
	v_mfma_f32_16x16x32_bf16 v[92:95], v[128:131], v[192:195], v[92:95]
	v_mfma_f32_16x16x32_bf16 v[88:91], v[136:139], v[192:195], v[88:91]
	v_mfma_f32_16x16x32_bf16 v[76:79], v[128:131], v[206:209], v[76:79]
	v_mfma_f32_16x16x32_bf16 v[72:75], v[136:139], v[206:209], v[72:75]
	v_mfma_f32_16x16x32_bf16 v[124:127], v[132:135], v[180:183], v[124:127]
	v_mfma_f32_16x16x32_bf16 v[120:123], v[142:145], v[180:183], v[120:123]
	v_mfma_f32_16x16x32_bf16 v[108:111], v[132:135], v[188:191], v[108:111]
	v_mfma_f32_16x16x32_bf16 v[104:107], v[142:145], v[188:191], v[104:107]
	v_mfma_f32_16x16x32_bf16 v[92:95], v[132:135], v[200:203], v[92:95]
	v_mfma_f32_16x16x32_bf16 v[88:91], v[142:145], v[200:203], v[88:91]
	v_mfma_f32_16x16x32_bf16 v[76:79], v[132:135], v[210:213], v[76:79]
	v_mfma_f32_16x16x32_bf16 v[72:75], v[142:145], v[210:213], v[72:75]
	v_mfma_f32_16x16x32_bf16 v[116:119], v[146:149], v[172:175], v[116:119]
	v_mfma_f32_16x16x32_bf16 v[112:115], v[154:157], v[172:175], v[112:115]
	v_mfma_f32_16x16x32_bf16 v[100:103], v[146:149], v[184:187], v[100:103]
	v_mfma_f32_16x16x32_bf16 v[96:99], v[154:157], v[184:187], v[96:99]
	v_mfma_f32_16x16x32_bf16 v[84:87], v[146:149], v[192:195], v[84:87]
	v_mfma_f32_16x16x32_bf16 v[80:83], v[154:157], v[192:195], v[80:83]
	v_mfma_f32_16x16x32_bf16 v[68:71], v[146:149], v[206:209], v[68:71]
	v_mfma_f32_16x16x32_bf16 v[64:67], v[154:157], v[206:209], v[64:67]
	v_mfma_f32_16x16x32_bf16 v[116:119], v[150:153], v[180:183], v[116:119]
	v_mfma_f32_16x16x32_bf16 v[112:115], v[168:171], v[180:183], v[112:115]
	v_mfma_f32_16x16x32_bf16 v[100:103], v[150:153], v[188:191], v[100:103]
	v_mfma_f32_16x16x32_bf16 v[96:99], v[168:171], v[188:191], v[96:99]
	v_mfma_f32_16x16x32_bf16 v[84:87], v[150:153], v[200:203], v[84:87]
	v_mfma_f32_16x16x32_bf16 v[80:83], v[168:171], v[200:203], v[80:83]
	v_mfma_f32_16x16x32_bf16 v[68:71], v[150:153], v[210:213], v[68:71]
	v_mfma_f32_16x16x32_bf16 v[64:67], v[168:171], v[210:213], v[64:67]
	s_setprio 0
	s_barrier
	s_add_i32 s35, s35, s13
	v_lshl_add_u64 v[176:177], s[8:9], 0, v[140:141]
	s_mov_b32 m0, s35
	ds_read_b128 v[172:175], v179 offset:16384
	ds_read_b128 v[180:183], v179 offset:17408
	ds_read_b128 v[184:187], v179 offset:18432
	ds_read_b128 v[188:191], v179 offset:19456
	ds_read_b128 v[192:195], v179 offset:20480
	ds_read_b128 v[200:203], v179 offset:21504
	ds_read_b128 v[206:209], v179 offset:22528
	ds_read_b128 v[210:213], v179 offset:23552
	global_load_lds_dwordx4 v[176:177], off
	s_add_i32 m0, s35, 0x2000
	s_add_u32 s84, s8, 0x40000
	v_lshl_add_u64 v[196:197], s[8:9], 0, v[158:159]
	s_addc_u32 s85, s9, 0
	s_add_i32 s35, s75, s13
	global_load_lds_dwordx4 v[196:197], off
	v_lshl_add_u64 v[198:199], s[84:85], 0, v[140:141]
	s_mov_b32 m0, s35
	v_lshl_add_u64 v[204:205], s[10:11], 0, v[160:161]
	global_load_lds_dwordx4 v[198:199], off
	v_lshl_add_u64 v[198:199], s[84:85], 0, v[158:159]
	s_add_i32 m0, s35, 0x2000
	s_nop 0
	global_load_lds_dwordx4 v[198:199], off
	v_lshl_add_u64 v[198:199], s[10:11], 0, v[162:163]
	s_mov_b32 m0, s15
	s_nop 0
	global_load_lds_dwordx4 v[198:199], off
	s_mov_b32 m0, s26
	s_nop 0
	global_load_lds_dwordx4 v[204:205], off
	s_waitcnt vmcnt(8)
	s_waitcnt lgkmcnt(0)
	s_barrier
	s_setprio 1
	s_waitcnt lgkmcnt(0)
	v_mfma_f32_16x16x32_bf16 v[60:63], v[128:131], v[172:175], v[60:63]
	v_mfma_f32_16x16x32_bf16 v[56:59], v[136:139], v[172:175], v[56:59]
	v_mfma_f32_16x16x32_bf16 v[44:47], v[128:131], v[184:187], v[44:47]
	v_mfma_f32_16x16x32_bf16 v[40:43], v[136:139], v[184:187], v[40:43]
	v_mfma_f32_16x16x32_bf16 v[28:31], v[128:131], v[192:195], v[28:31]
	v_mfma_f32_16x16x32_bf16 v[24:27], v[136:139], v[192:195], v[24:27]
	v_mfma_f32_16x16x32_bf16 v[12:15], v[128:131], v[206:209], v[12:15]
	v_mfma_f32_16x16x32_bf16 v[8:11], v[136:139], v[206:209], v[8:11]
	v_mfma_f32_16x16x32_bf16 v[60:63], v[132:135], v[180:183], v[60:63]
	v_mfma_f32_16x16x32_bf16 v[56:59], v[142:145], v[180:183], v[56:59]
	v_mfma_f32_16x16x32_bf16 v[44:47], v[132:135], v[188:191], v[44:47]
	v_mfma_f32_16x16x32_bf16 v[40:43], v[142:145], v[188:191], v[40:43]
	v_mfma_f32_16x16x32_bf16 v[28:31], v[132:135], v[200:203], v[28:31]
	v_mfma_f32_16x16x32_bf16 v[24:27], v[142:145], v[200:203], v[24:27]
	v_mfma_f32_16x16x32_bf16 v[12:15], v[132:135], v[210:213], v[12:15]
	v_mfma_f32_16x16x32_bf16 v[8:11], v[142:145], v[210:213], v[8:11]
	v_mfma_f32_16x16x32_bf16 v[52:55], v[146:149], v[172:175], v[52:55]
	v_mfma_f32_16x16x32_bf16 v[48:51], v[154:157], v[172:175], v[48:51]
	v_mfma_f32_16x16x32_bf16 v[36:39], v[146:149], v[184:187], v[36:39]
	v_mfma_f32_16x16x32_bf16 v[32:35], v[154:157], v[184:187], v[32:35]
	v_mfma_f32_16x16x32_bf16 v[20:23], v[146:149], v[192:195], v[20:23]
	v_mfma_f32_16x16x32_bf16 v[16:19], v[154:157], v[192:195], v[16:19]
	v_mfma_f32_16x16x32_bf16 v[4:7], v[146:149], v[206:209], v[4:7]
	v_mfma_f32_16x16x32_bf16 v[0:3], v[154:157], v[206:209], v[0:3]
	v_mfma_f32_16x16x32_bf16 v[52:55], v[150:153], v[180:183], v[52:55]
	v_mfma_f32_16x16x32_bf16 v[48:51], v[168:171], v[180:183], v[48:51]
	v_mfma_f32_16x16x32_bf16 v[36:39], v[150:153], v[188:191], v[36:39]
	v_mfma_f32_16x16x32_bf16 v[32:35], v[168:171], v[188:191], v[32:35]
	v_mfma_f32_16x16x32_bf16 v[20:23], v[150:153], v[200:203], v[20:23]
	v_mfma_f32_16x16x32_bf16 v[16:19], v[168:171], v[200:203], v[16:19]
	v_mfma_f32_16x16x32_bf16 v[4:7], v[150:153], v[210:213], v[4:7]
	v_mfma_f32_16x16x32_bf16 v[0:3], v[168:171], v[210:213], v[0:3]
	s_setprio 0
	s_barrier
	s_add_i32 s35, 0, 0x18000
	s_add_i32 s75, 0, 0x1c000
	v_add_u32_e32 v142, s35, v178
	v_add_u32_e32 v168, s75, v178
	ds_read_b128 v[128:131], v142
	ds_read_b128 v[132:135], v142 offset:1024
	ds_read_b128 v[136:139], v142 offset:2048
	ds_read_b128 v[142:145], v142 offset:3072
	ds_read_b128 v[146:149], v168
	ds_read_b128 v[150:153], v168 offset:1024
	ds_read_b128 v[154:157], v168 offset:2048
	ds_read_b128 v[168:171], v168 offset:3072
	s_add_u32 s10, s10, 0x40000
	s_addc_u32 s11, s11, 0
	s_mov_b32 m0, s27
	v_lshl_add_u64 v[214:215], s[10:11], 0, v[162:163]
	ds_read_b128 v[172:175], v179 offset:32768
	ds_read_b128 v[180:183], v179 offset:33792
	ds_read_b128 v[184:187], v179 offset:34816
	ds_read_b128 v[188:191], v179 offset:35840
	ds_read_b128 v[192:195], v179 offset:36864
	ds_read_b128 v[200:203], v179 offset:37888
	ds_read_b128 v[206:209], v179 offset:38912
	ds_read_b128 v[210:213], v179 offset:39936
	global_load_lds_dwordx4 v[214:215], off
	v_lshl_add_u64 v[214:215], s[10:11], 0, v[160:161]
	s_mov_b32 m0, s28
	s_nop 0
	global_load_lds_dwordx4 v[214:215], off
	s_waitcnt vmcnt(8)
	s_waitcnt lgkmcnt(0)
	s_barrier
	s_setprio 1
	s_waitcnt lgkmcnt(0)
	v_mfma_f32_16x16x32_bf16 v[124:127], v[128:131], v[172:175], v[124:127]
	v_mfma_f32_16x16x32_bf16 v[120:123], v[136:139], v[172:175], v[120:123]
	v_mfma_f32_16x16x32_bf16 v[108:111], v[128:131], v[184:187], v[108:111]
	v_mfma_f32_16x16x32_bf16 v[104:107], v[136:139], v[184:187], v[104:107]
	v_mfma_f32_16x16x32_bf16 v[92:95], v[128:131], v[192:195], v[92:95]
	v_mfma_f32_16x16x32_bf16 v[88:91], v[136:139], v[192:195], v[88:91]
	v_mfma_f32_16x16x32_bf16 v[76:79], v[128:131], v[206:209], v[76:79]
	v_mfma_f32_16x16x32_bf16 v[72:75], v[136:139], v[206:209], v[72:75]
	v_mfma_f32_16x16x32_bf16 v[124:127], v[132:135], v[180:183], v[124:127]
	v_mfma_f32_16x16x32_bf16 v[120:123], v[142:145], v[180:183], v[120:123]
	v_mfma_f32_16x16x32_bf16 v[108:111], v[132:135], v[188:191], v[108:111]
	v_mfma_f32_16x16x32_bf16 v[104:107], v[142:145], v[188:191], v[104:107]
	v_mfma_f32_16x16x32_bf16 v[92:95], v[132:135], v[200:203], v[92:95]
	v_mfma_f32_16x16x32_bf16 v[88:91], v[142:145], v[200:203], v[88:91]
	v_mfma_f32_16x16x32_bf16 v[76:79], v[132:135], v[210:213], v[76:79]
	v_mfma_f32_16x16x32_bf16 v[72:75], v[142:145], v[210:213], v[72:75]
	v_mfma_f32_16x16x32_bf16 v[116:119], v[146:149], v[172:175], v[116:119]
	v_mfma_f32_16x16x32_bf16 v[112:115], v[154:157], v[172:175], v[112:115]
	v_mfma_f32_16x16x32_bf16 v[100:103], v[146:149], v[184:187], v[100:103]
	v_mfma_f32_16x16x32_bf16 v[96:99], v[154:157], v[184:187], v[96:99]
	v_mfma_f32_16x16x32_bf16 v[84:87], v[146:149], v[192:195], v[84:87]
	v_mfma_f32_16x16x32_bf16 v[80:83], v[154:157], v[192:195], v[80:83]
	v_mfma_f32_16x16x32_bf16 v[68:71], v[146:149], v[206:209], v[68:71]
	v_mfma_f32_16x16x32_bf16 v[64:67], v[154:157], v[206:209], v[64:67]
	v_mfma_f32_16x16x32_bf16 v[116:119], v[150:153], v[180:183], v[116:119]
	v_mfma_f32_16x16x32_bf16 v[112:115], v[168:171], v[180:183], v[112:115]
	v_mfma_f32_16x16x32_bf16 v[100:103], v[150:153], v[188:191], v[100:103]
	v_mfma_f32_16x16x32_bf16 v[96:99], v[168:171], v[188:191], v[96:99]
	v_mfma_f32_16x16x32_bf16 v[84:87], v[150:153], v[200:203], v[84:87]
	v_mfma_f32_16x16x32_bf16 v[80:83], v[168:171], v[200:203], v[80:83]
	v_mfma_f32_16x16x32_bf16 v[68:71], v[150:153], v[210:213], v[68:71]
	v_mfma_f32_16x16x32_bf16 v[64:67], v[168:171], v[210:213], v[64:67]
	s_setprio 0
	s_barrier
	s_add_i32 s10, s35, s13
	v_lshl_add_u64 v[176:177], v[176:177], 0, s[36:37]
	s_mov_b32 m0, s10
	ds_read_b128 v[172:175], v179 offset:49152
	ds_read_b128 v[180:183], v179 offset:50176
	ds_read_b128 v[184:187], v179 offset:51200
	ds_read_b128 v[188:191], v179 offset:52224
	ds_read_b128 v[192:195], v179 offset:53248
	ds_read_b128 v[200:203], v179 offset:54272
	ds_read_b128 v[206:209], v179 offset:55296
	ds_read_b128 v[210:213], v179 offset:56320
	global_load_lds_dwordx4 v[176:177], off
	s_add_i32 m0, s10, 0x2000
	s_add_u32 s8, s8, 0x40080
	v_lshl_add_u64 v[176:177], v[196:197], 0, s[36:37]
	s_addc_u32 s9, s9, 0
	s_add_i32 s10, s75, s13
	global_load_lds_dwordx4 v[176:177], off
	v_lshl_add_u64 v[176:177], s[8:9], 0, v[140:141]
	s_mov_b32 m0, s10
	s_nop 0
	global_load_lds_dwordx4 v[176:177], off
	v_lshl_add_u64 v[176:177], s[8:9], 0, v[158:159]
	s_add_i32 m0, s10, 0x2000
	s_nop 0
	global_load_lds_dwordx4 v[176:177], off
	v_lshl_add_u64 v[176:177], v[198:199], 0, s[36:37]
	s_mov_b32 m0, s29
	s_nop 0
	global_load_lds_dwordx4 v[176:177], off
	v_lshl_add_u64 v[176:177], v[204:205], 0, s[36:37]
	s_mov_b32 m0, s42
	s_nop 0
	global_load_lds_dwordx4 v[176:177], off
	s_waitcnt vmcnt(8)
	s_waitcnt lgkmcnt(0)
	s_barrier
	s_setprio 1
	s_waitcnt lgkmcnt(0)
	v_mfma_f32_16x16x32_bf16 v[60:63], v[128:131], v[172:175], v[60:63]
	v_mfma_f32_16x16x32_bf16 v[56:59], v[136:139], v[172:175], v[56:59]
	v_mfma_f32_16x16x32_bf16 v[44:47], v[128:131], v[184:187], v[44:47]
	v_mfma_f32_16x16x32_bf16 v[40:43], v[136:139], v[184:187], v[40:43]
	v_mfma_f32_16x16x32_bf16 v[28:31], v[128:131], v[192:195], v[28:31]
	v_mfma_f32_16x16x32_bf16 v[24:27], v[136:139], v[192:195], v[24:27]
	v_mfma_f32_16x16x32_bf16 v[12:15], v[128:131], v[206:209], v[12:15]
	v_mfma_f32_16x16x32_bf16 v[8:11], v[136:139], v[206:209], v[8:11]
	v_mfma_f32_16x16x32_bf16 v[60:63], v[132:135], v[180:183], v[60:63]
	v_mfma_f32_16x16x32_bf16 v[56:59], v[142:145], v[180:183], v[56:59]
	v_mfma_f32_16x16x32_bf16 v[44:47], v[132:135], v[188:191], v[44:47]
	v_mfma_f32_16x16x32_bf16 v[40:43], v[142:145], v[188:191], v[40:43]
	v_mfma_f32_16x16x32_bf16 v[28:31], v[132:135], v[200:203], v[28:31]
	v_mfma_f32_16x16x32_bf16 v[24:27], v[142:145], v[200:203], v[24:27]
	v_mfma_f32_16x16x32_bf16 v[12:15], v[132:135], v[210:213], v[12:15]
	v_mfma_f32_16x16x32_bf16 v[8:11], v[142:145], v[210:213], v[8:11]
	v_mfma_f32_16x16x32_bf16 v[52:55], v[146:149], v[172:175], v[52:55]
	v_mfma_f32_16x16x32_bf16 v[48:51], v[154:157], v[172:175], v[48:51]
	v_mfma_f32_16x16x32_bf16 v[36:39], v[146:149], v[184:187], v[36:39]
	v_mfma_f32_16x16x32_bf16 v[32:35], v[154:157], v[184:187], v[32:35]
	v_mfma_f32_16x16x32_bf16 v[20:23], v[146:149], v[192:195], v[20:23]
	v_mfma_f32_16x16x32_bf16 v[16:19], v[154:157], v[192:195], v[16:19]
	v_mfma_f32_16x16x32_bf16 v[4:7], v[146:149], v[206:209], v[4:7]
	v_mfma_f32_16x16x32_bf16 v[0:3], v[154:157], v[206:209], v[0:3]
	v_mfma_f32_16x16x32_bf16 v[52:55], v[150:153], v[180:183], v[52:55]
	v_mfma_f32_16x16x32_bf16 v[48:51], v[168:171], v[180:183], v[48:51]
	v_mfma_f32_16x16x32_bf16 v[36:39], v[150:153], v[188:191], v[36:39]
	v_mfma_f32_16x16x32_bf16 v[32:35], v[168:171], v[188:191], v[32:35]
	v_mfma_f32_16x16x32_bf16 v[20:23], v[150:153], v[200:203], v[20:23]
	v_mfma_f32_16x16x32_bf16 v[16:19], v[168:171], v[200:203], v[16:19]
	v_mfma_f32_16x16x32_bf16 v[4:7], v[150:153], v[210:213], v[4:7]
	v_mfma_f32_16x16x32_bf16 v[0:3], v[168:171], v[210:213], v[0:3]
	s_setprio 0
	s_barrier
	s_add_i32 s74, s74, 2
	s_add_u32 s6, s6, 0x100
	s_addc_u32 s7, s7, 0
	s_add_u32 s60, s60, 0x100
	s_addc_u32 s61, s61, 0
	s_cmp_gt_u32 s74, 13
	s_cbranch_scc0 .LBB0_147
	s_and_b64 vcc, exec, s[50:51]
	s_cbranch_vccz .LBB0_150
	s_barrier

.LBB0_234:
	s_add_u32 s8, s6, 0xfffc0080
	s_addc_u32 s9, s7, -1
	s_add_i32 s35, 0, 0x10000
	s_cmp_eq_u32 s53, 12
	s_cselect_b32 s11, s4, s9
	s_cselect_b32 s10, s5, s8
	v_add_u32_e32 v140, s35, v206
	s_cselect_b32 s9, s24, s51
	s_cselect_b32 s8, s42, s43
	s_add_i32 s76, 0, 0x14000
	ds_read_b128 v[142:145], v140
	ds_read_b128 v[146:149], v140 offset:1024
	ds_read_b128 v[150:153], v140 offset:2048
	ds_read_b128 v[154:157], v140 offset:3072
	v_add_u32_e32 v140, s76, v206
	ds_read_b128 v[158:161], v140
	ds_read_b128 v[162:165], v140 offset:1024
	ds_read_b128 v[166:169], v140 offset:2048
	ds_read_b128 v[170:173], v140 offset:3072
	v_lshl_add_u64 v[198:199], s[6:7], 0, v[136:137]
	s_add_i32 m0, s15, 0xc000
	ds_read_b128 v[174:177], v207
	ds_read_b128 v[178:181], v207 offset:1024
	ds_read_b128 v[182:185], v207 offset:2048
	ds_read_b128 v[186:189], v207 offset:3072
	ds_read_b128 v[190:193], v207 offset:4096
	ds_read_b128 v[194:197], v207 offset:5120
	ds_read_b128 v[200:203], v207 offset:6144
	ds_read_b128 v[208:211], v207 offset:7168
	global_load_lds_dwordx4 v[198:199], off
	v_lshl_add_u64 v[198:199], s[6:7], 0, v[138:139]
	s_add_i32 m0, s15, 0xe000
	s_nop 0
	global_load_lds_dwordx4 v[198:199], off
	s_waitcnt vmcnt(8)
	s_waitcnt lgkmcnt(0)
	s_barrier
	s_setprio 1
	s_waitcnt lgkmcnt(0)
	v_mfma_f32_16x16x32_bf16 v[124:127], v[142:145], v[174:177], v[124:127]
	v_mfma_f32_16x16x32_bf16 v[120:123], v[150:153], v[174:177], v[120:123]
	v_mfma_f32_16x16x32_bf16 v[108:111], v[142:145], v[182:185], v[108:111]
	v_mfma_f32_16x16x32_bf16 v[104:107], v[150:153], v[182:185], v[104:107]
	v_mfma_f32_16x16x32_bf16 v[92:95], v[142:145], v[190:193], v[92:95]
	v_mfma_f32_16x16x32_bf16 v[88:91], v[150:153], v[190:193], v[88:91]
	v_mfma_f32_16x16x32_bf16 v[76:79], v[142:145], v[200:203], v[76:79]
	v_mfma_f32_16x16x32_bf16 v[72:75], v[150:153], v[200:203], v[72:75]
	v_mfma_f32_16x16x32_bf16 v[124:127], v[146:149], v[178:181], v[124:127]
	v_mfma_f32_16x16x32_bf16 v[120:123], v[154:157], v[178:181], v[120:123]
	v_mfma_f32_16x16x32_bf16 v[108:111], v[146:149], v[186:189], v[108:111]
	v_mfma_f32_16x16x32_bf16 v[104:107], v[154:157], v[186:189], v[104:107]
	v_mfma_f32_16x16x32_bf16 v[92:95], v[146:149], v[194:197], v[92:95]
	v_mfma_f32_16x16x32_bf16 v[88:91], v[154:157], v[194:197], v[88:91]
	v_mfma_f32_16x16x32_bf16 v[76:79], v[146:149], v[208:211], v[76:79]
	v_mfma_f32_16x16x32_bf16 v[72:75], v[154:157], v[208:211], v[72:75]
	v_mfma_f32_16x16x32_bf16 v[116:119], v[158:161], v[174:177], v[116:119]
	v_mfma_f32_16x16x32_bf16 v[112:115], v[166:169], v[174:177], v[112:115]
	v_mfma_f32_16x16x32_bf16 v[100:103], v[158:161], v[182:185], v[100:103]
	v_mfma_f32_16x16x32_bf16 v[96:99], v[166:169], v[182:185], v[96:99]
	v_mfma_f32_16x16x32_bf16 v[84:87], v[158:161], v[190:193], v[84:87]
	v_mfma_f32_16x16x32_bf16 v[80:83], v[166:169], v[190:193], v[80:83]
	v_mfma_f32_16x16x32_bf16 v[68:71], v[158:161], v[200:203], v[68:71]
	v_mfma_f32_16x16x32_bf16 v[64:67], v[166:169], v[200:203], v[64:67]
	v_mfma_f32_16x16x32_bf16 v[116:119], v[162:165], v[178:181], v[116:119]
	v_mfma_f32_16x16x32_bf16 v[112:115], v[170:173], v[178:181], v[112:115]
	v_mfma_f32_16x16x32_bf16 v[100:103], v[162:165], v[186:189], v[100:103]
	v_mfma_f32_16x16x32_bf16 v[96:99], v[170:173], v[186:189], v[96:99]
	v_mfma_f32_16x16x32_bf16 v[84:87], v[162:165], v[194:197], v[84:87]
	v_mfma_f32_16x16x32_bf16 v[80:83], v[170:173], v[194:197], v[80:83]
	v_mfma_f32_16x16x32_bf16 v[68:71], v[162:165], v[208:211], v[68:71]
	v_mfma_f32_16x16x32_bf16 v[64:67], v[170:173], v[208:211], v[64:67]
	s_setprio 0
	s_barrier
	s_add_i32 s35, s35, s13
	v_lshl_add_u64 v[198:199], s[8:9], 0, v[132:133]
	s_mov_b32 m0, s35
	ds_read_b128 v[174:177], v207 offset:16384
	ds_read_b128 v[178:181], v207 offset:17408
	ds_read_b128 v[182:185], v207 offset:18432
	ds_read_b128 v[186:189], v207 offset:19456
	ds_read_b128 v[190:193], v207 offset:20480
	ds_read_b128 v[194:197], v207 offset:21504
	ds_read_b128 v[200:203], v207 offset:22528
	ds_read_b128 v[208:211], v207 offset:23552
	global_load_lds_dwordx4 v[198:199], off
	s_add_i32 m0, s35, 0x2000
	s_add_u32 s60, s8, 0x40000
	v_lshl_add_u64 v[204:205], s[8:9], 0, v[128:129]
	s_addc_u32 s61, s9, 0
	s_add_i32 s35, s76, s13
	global_load_lds_dwordx4 v[204:205], off
	v_lshl_add_u64 v[212:213], s[60:61], 0, v[132:133]
	s_mov_b32 m0, s35
	v_lshl_add_u64 v[214:215], s[10:11], 0, v[130:131]
	global_load_lds_dwordx4 v[212:213], off
	v_lshl_add_u64 v[212:213], s[60:61], 0, v[128:129]
	s_add_i32 m0, s35, 0x2000
	s_nop 0
	global_load_lds_dwordx4 v[212:213], off
	v_lshl_add_u64 v[212:213], s[10:11], 0, v[134:135]
	s_mov_b32 m0, s15
	s_nop 0
	global_load_lds_dwordx4 v[212:213], off
	s_mov_b32 m0, s26
	s_nop 0
	global_load_lds_dwordx4 v[214:215], off
	s_waitcnt vmcnt(8)
	s_waitcnt lgkmcnt(0)
	s_barrier
	s_setprio 1
	s_waitcnt lgkmcnt(0)
	v_mfma_f32_16x16x32_bf16 v[60:63], v[142:145], v[174:177], v[60:63]
	v_mfma_f32_16x16x32_bf16 v[56:59], v[150:153], v[174:177], v[56:59]
	v_mfma_f32_16x16x32_bf16 v[44:47], v[142:145], v[182:185], v[44:47]
	v_mfma_f32_16x16x32_bf16 v[40:43], v[150:153], v[182:185], v[40:43]
	v_mfma_f32_16x16x32_bf16 v[28:31], v[142:145], v[190:193], v[28:31]
	v_mfma_f32_16x16x32_bf16 v[24:27], v[150:153], v[190:193], v[24:27]
	v_mfma_f32_16x16x32_bf16 v[12:15], v[142:145], v[200:203], v[12:15]
	v_mfma_f32_16x16x32_bf16 v[8:11], v[150:153], v[200:203], v[8:11]
	v_mfma_f32_16x16x32_bf16 v[60:63], v[146:149], v[178:181], v[60:63]
	v_mfma_f32_16x16x32_bf16 v[56:59], v[154:157], v[178:181], v[56:59]
	v_mfma_f32_16x16x32_bf16 v[44:47], v[146:149], v[186:189], v[44:47]
	v_mfma_f32_16x16x32_bf16 v[40:43], v[154:157], v[186:189], v[40:43]
	v_mfma_f32_16x16x32_bf16 v[28:31], v[146:149], v[194:197], v[28:31]
	v_mfma_f32_16x16x32_bf16 v[24:27], v[154:157], v[194:197], v[24:27]
	v_mfma_f32_16x16x32_bf16 v[12:15], v[146:149], v[208:211], v[12:15]
	v_mfma_f32_16x16x32_bf16 v[8:11], v[154:157], v[208:211], v[8:11]
	v_mfma_f32_16x16x32_bf16 v[52:55], v[158:161], v[174:177], v[52:55]
	v_mfma_f32_16x16x32_bf16 v[48:51], v[166:169], v[174:177], v[48:51]
	v_mfma_f32_16x16x32_bf16 v[36:39], v[158:161], v[182:185], v[36:39]
	v_mfma_f32_16x16x32_bf16 v[32:35], v[166:169], v[182:185], v[32:35]
	v_mfma_f32_16x16x32_bf16 v[20:23], v[158:161], v[190:193], v[20:23]
	v_mfma_f32_16x16x32_bf16 v[16:19], v[166:169], v[190:193], v[16:19]
	v_mfma_f32_16x16x32_bf16 v[4:7], v[158:161], v[200:203], v[4:7]
	v_mfma_f32_16x16x32_bf16 v[0:3], v[166:169], v[200:203], v[0:3]
	v_mfma_f32_16x16x32_bf16 v[52:55], v[162:165], v[178:181], v[52:55]
	v_mfma_f32_16x16x32_bf16 v[48:51], v[170:173], v[178:181], v[48:51]
	v_mfma_f32_16x16x32_bf16 v[36:39], v[162:165], v[186:189], v[36:39]
	v_mfma_f32_16x16x32_bf16 v[32:35], v[170:173], v[186:189], v[32:35]
	v_mfma_f32_16x16x32_bf16 v[20:23], v[162:165], v[194:197], v[20:23]
	v_mfma_f32_16x16x32_bf16 v[16:19], v[170:173], v[194:197], v[16:19]
	v_mfma_f32_16x16x32_bf16 v[4:7], v[162:165], v[208:211], v[4:7]
	v_mfma_f32_16x16x32_bf16 v[0:3], v[170:173], v[208:211], v[0:3]
	s_setprio 0
	s_barrier
	s_add_i32 s35, 0, 0x18000
	v_add_u32_e32 v140, s35, v206
	s_add_i32 s60, 0, 0x1c000
	ds_read_b128 v[142:145], v140
	ds_read_b128 v[146:149], v140 offset:1024
	ds_read_b128 v[150:153], v140 offset:2048
	ds_read_b128 v[154:157], v140 offset:3072
	v_add_u32_e32 v140, s60, v206
	ds_read_b128 v[158:161], v140
	ds_read_b128 v[162:165], v140 offset:1024
	ds_read_b128 v[166:169], v140 offset:2048
	ds_read_b128 v[170:173], v140 offset:3072
	s_add_u32 s10, s10, 0x40000
	s_addc_u32 s11, s11, 0
	s_mov_b32 m0, s27
	v_lshl_add_u64 v[216:217], s[10:11], 0, v[134:135]
	ds_read_b128 v[174:177], v207 offset:32768
	ds_read_b128 v[178:181], v207 offset:33792
	ds_read_b128 v[182:185], v207 offset:34816
	ds_read_b128 v[186:189], v207 offset:35840
	ds_read_b128 v[190:193], v207 offset:36864
	ds_read_b128 v[194:197], v207 offset:37888
	ds_read_b128 v[200:203], v207 offset:38912
	ds_read_b128 v[208:211], v207 offset:39936
	global_load_lds_dwordx4 v[216:217], off
	v_lshl_add_u64 v[216:217], s[10:11], 0, v[130:131]
	s_mov_b32 m0, s28
	s_nop 0
	global_load_lds_dwordx4 v[216:217], off
	s_waitcnt vmcnt(8)
	s_waitcnt lgkmcnt(0)
	s_barrier
	s_setprio 1
	s_waitcnt lgkmcnt(0)
	v_mfma_f32_16x16x32_bf16 v[124:127], v[142:145], v[174:177], v[124:127]
	v_mfma_f32_16x16x32_bf16 v[120:123], v[150:153], v[174:177], v[120:123]
	v_mfma_f32_16x16x32_bf16 v[108:111], v[142:145], v[182:185], v[108:111]
	v_mfma_f32_16x16x32_bf16 v[104:107], v[150:153], v[182:185], v[104:107]
	v_mfma_f32_16x16x32_bf16 v[92:95], v[142:145], v[190:193], v[92:95]
	v_mfma_f32_16x16x32_bf16 v[88:91], v[150:153], v[190:193], v[88:91]
	v_mfma_f32_16x16x32_bf16 v[76:79], v[142:145], v[200:203], v[76:79]
	v_mfma_f32_16x16x32_bf16 v[72:75], v[150:153], v[200:203], v[72:75]
	v_mfma_f32_16x16x32_bf16 v[124:127], v[146:149], v[178:181], v[124:127]
	v_mfma_f32_16x16x32_bf16 v[120:123], v[154:157], v[178:181], v[120:123]
	v_mfma_f32_16x16x32_bf16 v[108:111], v[146:149], v[186:189], v[108:111]
	v_mfma_f32_16x16x32_bf16 v[104:107], v[154:157], v[186:189], v[104:107]
	v_mfma_f32_16x16x32_bf16 v[92:95], v[146:149], v[194:197], v[92:95]
	v_mfma_f32_16x16x32_bf16 v[88:91], v[154:157], v[194:197], v[88:91]
	v_mfma_f32_16x16x32_bf16 v[76:79], v[146:149], v[208:211], v[76:79]
	v_mfma_f32_16x16x32_bf16 v[72:75], v[154:157], v[208:211], v[72:75]
	v_mfma_f32_16x16x32_bf16 v[116:119], v[158:161], v[174:177], v[116:119]
	v_mfma_f32_16x16x32_bf16 v[112:115], v[166:169], v[174:177], v[112:115]
	v_mfma_f32_16x16x32_bf16 v[100:103], v[158:161], v[182:185], v[100:103]
	v_mfma_f32_16x16x32_bf16 v[96:99], v[166:169], v[182:185], v[96:99]
	v_mfma_f32_16x16x32_bf16 v[84:87], v[158:161], v[190:193], v[84:87]
	v_mfma_f32_16x16x32_bf16 v[80:83], v[166:169], v[190:193], v[80:83]
	v_mfma_f32_16x16x32_bf16 v[68:71], v[158:161], v[200:203], v[68:71]
	v_mfma_f32_16x16x32_bf16 v[64:67], v[166:169], v[200:203], v[64:67]
	v_mfma_f32_16x16x32_bf16 v[116:119], v[162:165], v[178:181], v[116:119]
	v_mfma_f32_16x16x32_bf16 v[112:115], v[170:173], v[178:181], v[112:115]
	v_mfma_f32_16x16x32_bf16 v[100:103], v[162:165], v[186:189], v[100:103]
	v_mfma_f32_16x16x32_bf16 v[96:99], v[170:173], v[186:189], v[96:99]
	v_mfma_f32_16x16x32_bf16 v[84:87], v[162:165], v[194:197], v[84:87]
	v_mfma_f32_16x16x32_bf16 v[80:83], v[170:173], v[194:197], v[80:83]
	v_mfma_f32_16x16x32_bf16 v[68:71], v[162:165], v[208:211], v[68:71]
	v_mfma_f32_16x16x32_bf16 v[64:67], v[170:173], v[208:211], v[64:67]
	s_setprio 0
	s_barrier
	s_add_i32 s10, s35, s13
	v_lshl_add_u64 v[198:199], v[198:199], 0, s[36:37]
	s_mov_b32 m0, s10
	ds_read_b128 v[174:177], v207 offset:49152
	ds_read_b128 v[178:181], v207 offset:50176
	ds_read_b128 v[182:185], v207 offset:51200
	ds_read_b128 v[186:189], v207 offset:52224
	ds_read_b128 v[190:193], v207 offset:53248
	ds_read_b128 v[194:197], v207 offset:54272
	ds_read_b128 v[200:203], v207 offset:55296
	ds_read_b128 v[208:211], v207 offset:56320
	global_load_lds_dwordx4 v[198:199], off
	s_add_i32 m0, s10, 0x2000
	s_add_u32 s8, s8, 0x40080
	v_lshl_add_u64 v[198:199], v[204:205], 0, s[36:37]
	s_addc_u32 s9, s9, 0
	s_add_i32 s10, s60, s13
	global_load_lds_dwordx4 v[198:199], off
	v_lshl_add_u64 v[198:199], s[8:9], 0, v[132:133]
	s_mov_b32 m0, s10
	s_nop 0
	global_load_lds_dwordx4 v[198:199], off
	v_lshl_add_u64 v[198:199], s[8:9], 0, v[128:129]
	s_add_i32 m0, s10, 0x2000
	s_nop 0
	global_load_lds_dwordx4 v[198:199], off
	v_lshl_add_u64 v[198:199], v[212:213], 0, s[36:37]
	s_mov_b32 m0, s29
	s_nop 0
	global_load_lds_dwordx4 v[198:199], off
	v_lshl_add_u64 v[198:199], v[214:215], 0, s[36:37]
	s_mov_b32 m0, s38
	s_nop 0
	global_load_lds_dwordx4 v[198:199], off
	s_waitcnt vmcnt(8)
	s_waitcnt lgkmcnt(0)
	s_barrier
	s_setprio 1
	s_waitcnt lgkmcnt(0)
	v_mfma_f32_16x16x32_bf16 v[60:63], v[142:145], v[174:177], v[60:63]
	v_mfma_f32_16x16x32_bf16 v[56:59], v[150:153], v[174:177], v[56:59]
	v_mfma_f32_16x16x32_bf16 v[44:47], v[142:145], v[182:185], v[44:47]
	v_mfma_f32_16x16x32_bf16 v[40:43], v[150:153], v[182:185], v[40:43]
	v_mfma_f32_16x16x32_bf16 v[28:31], v[142:145], v[190:193], v[28:31]
	v_mfma_f32_16x16x32_bf16 v[24:27], v[150:153], v[190:193], v[24:27]
	v_mfma_f32_16x16x32_bf16 v[12:15], v[142:145], v[200:203], v[12:15]
	v_mfma_f32_16x16x32_bf16 v[8:11], v[150:153], v[200:203], v[8:11]
	v_mfma_f32_16x16x32_bf16 v[60:63], v[146:149], v[178:181], v[60:63]
	v_mfma_f32_16x16x32_bf16 v[56:59], v[154:157], v[178:181], v[56:59]
	v_mfma_f32_16x16x32_bf16 v[44:47], v[146:149], v[186:189], v[44:47]
	v_mfma_f32_16x16x32_bf16 v[40:43], v[154:157], v[186:189], v[40:43]
	v_mfma_f32_16x16x32_bf16 v[28:31], v[146:149], v[194:197], v[28:31]
	v_mfma_f32_16x16x32_bf16 v[24:27], v[154:157], v[194:197], v[24:27]
	v_mfma_f32_16x16x32_bf16 v[12:15], v[146:149], v[208:211], v[12:15]
	v_mfma_f32_16x16x32_bf16 v[8:11], v[154:157], v[208:211], v[8:11]
	v_mfma_f32_16x16x32_bf16 v[52:55], v[158:161], v[174:177], v[52:55]
	v_mfma_f32_16x16x32_bf16 v[48:51], v[166:169], v[174:177], v[48:51]
	v_mfma_f32_16x16x32_bf16 v[36:39], v[158:161], v[182:185], v[36:39]
	v_mfma_f32_16x16x32_bf16 v[32:35], v[166:169], v[182:185], v[32:35]
	v_mfma_f32_16x16x32_bf16 v[20:23], v[158:161], v[190:193], v[20:23]
	v_mfma_f32_16x16x32_bf16 v[16:19], v[166:169], v[190:193], v[16:19]
	v_mfma_f32_16x16x32_bf16 v[4:7], v[158:161], v[200:203], v[4:7]
	v_mfma_f32_16x16x32_bf16 v[0:3], v[166:169], v[200:203], v[0:3]
	v_mfma_f32_16x16x32_bf16 v[52:55], v[162:165], v[178:181], v[52:55]
	v_mfma_f32_16x16x32_bf16 v[48:51], v[170:173], v[178:181], v[48:51]
	v_mfma_f32_16x16x32_bf16 v[36:39], v[162:165], v[186:189], v[36:39]
	v_mfma_f32_16x16x32_bf16 v[32:35], v[170:173], v[186:189], v[32:35]
	v_mfma_f32_16x16x32_bf16 v[20:23], v[162:165], v[194:197], v[20:23]
	v_mfma_f32_16x16x32_bf16 v[16:19], v[170:173], v[194:197], v[16:19]
	v_mfma_f32_16x16x32_bf16 v[4:7], v[162:165], v[208:211], v[4:7]
	v_mfma_f32_16x16x32_bf16 v[0:3], v[170:173], v[208:211], v[0:3]
	s_setprio 0
	s_barrier
	s_add_i32 s53, s53, 2
	s_add_u32 s6, s6, 0x100
	s_addc_u32 s7, s7, 0
	s_add_u32 s43, s43, 0x100
	s_addc_u32 s51, s51, 0
	s_cmp_gt_u32 s53, 13
	s_cbranch_scc0 .LBB0_234
	s_and_b64 vcc, exec, s[48:49]
	s_cbranch_vccz .LBB0_237
	s_barrier

.LBB0_333:
	s_add_i32 s56, s8, 2
	s_add_u32 s9, s6, 0x8000
	s_addc_u32 s10, s7, 0
	s_cmp_eq_u32 s94, s8
	s_cselect_b32 s11, s43, s10
	s_cselect_b32 s10, s42, s9
	s_cselect_b32 s60, s54, s24
	s_cselect_b32 s61, s55, s38
	s_add_u32 s8, s10, 0x8000
	s_addc_u32 s9, s11, 0
	s_add_i32 s35, 0, 0x10000
	s_add_i32 s57, 0, 0x14000
	v_add_u32_e32 v142, s35, v178
	v_add_u32_e32 v168, s57, v178
	ds_read_b128 v[128:131], v142
	ds_read_b128 v[132:135], v142 offset:1024
	ds_read_b128 v[136:139], v142 offset:2048
	ds_read_b128 v[142:145], v142 offset:3072
	ds_read_b128 v[146:149], v168
	ds_read_b128 v[150:153], v168 offset:1024
	ds_read_b128 v[154:157], v168 offset:2048
	ds_read_b128 v[168:171], v168 offset:3072
	v_lshl_add_u64 v[176:177], s[6:7], 0, v[164:165]
	s_add_i32 m0, s75, 0xc000
	ds_read_b128 v[172:175], v179
	ds_read_b128 v[180:183], v179 offset:1024
	ds_read_b128 v[184:187], v179 offset:2048
	ds_read_b128 v[188:191], v179 offset:3072
	ds_read_b128 v[192:195], v179 offset:4096
	ds_read_b128 v[200:203], v179 offset:5120
	ds_read_b128 v[206:209], v179 offset:6144
	ds_read_b128 v[210:213], v179 offset:7168
	global_load_lds_dwordx4 v[176:177], off
	v_lshl_add_u64 v[176:177], s[6:7], 0, v[166:167]
	s_add_i32 m0, s75, 0xe000
	s_nop 0
	global_load_lds_dwordx4 v[176:177], off
	s_waitcnt vmcnt(8)
	s_waitcnt lgkmcnt(0)
	s_barrier
	s_setprio 1
	s_waitcnt lgkmcnt(0)
	v_mfma_f32_16x16x32_bf16 v[124:127], v[128:131], v[172:175], v[124:127]
	v_mfma_f32_16x16x32_bf16 v[120:123], v[136:139], v[172:175], v[120:123]
	v_mfma_f32_16x16x32_bf16 v[108:111], v[128:131], v[184:187], v[108:111]
	v_mfma_f32_16x16x32_bf16 v[104:107], v[136:139], v[184:187], v[104:107]
	v_mfma_f32_16x16x32_bf16 v[92:95], v[128:131], v[192:195], v[92:95]
	v_mfma_f32_16x16x32_bf16 v[88:91], v[136:139], v[192:195], v[88:91]
	v_mfma_f32_16x16x32_bf16 v[76:79], v[128:131], v[206:209], v[76:79]
	v_mfma_f32_16x16x32_bf16 v[72:75], v[136:139], v[206:209], v[72:75]
	v_mfma_f32_16x16x32_bf16 v[124:127], v[132:135], v[180:183], v[124:127]
	v_mfma_f32_16x16x32_bf16 v[120:123], v[142:145], v[180:183], v[120:123]
	v_mfma_f32_16x16x32_bf16 v[108:111], v[132:135], v[188:191], v[108:111]
	v_mfma_f32_16x16x32_bf16 v[104:107], v[142:145], v[188:191], v[104:107]
	v_mfma_f32_16x16x32_bf16 v[92:95], v[132:135], v[200:203], v[92:95]
	v_mfma_f32_16x16x32_bf16 v[88:91], v[142:145], v[200:203], v[88:91]
	v_mfma_f32_16x16x32_bf16 v[76:79], v[132:135], v[210:213], v[76:79]
	v_mfma_f32_16x16x32_bf16 v[72:75], v[142:145], v[210:213], v[72:75]
	v_mfma_f32_16x16x32_bf16 v[116:119], v[146:149], v[172:175], v[116:119]
	v_mfma_f32_16x16x32_bf16 v[112:115], v[154:157], v[172:175], v[112:115]
	v_mfma_f32_16x16x32_bf16 v[100:103], v[146:149], v[184:187], v[100:103]
	v_mfma_f32_16x16x32_bf16 v[96:99], v[154:157], v[184:187], v[96:99]
	v_mfma_f32_16x16x32_bf16 v[84:87], v[146:149], v[192:195], v[84:87]
	v_mfma_f32_16x16x32_bf16 v[80:83], v[154:157], v[192:195], v[80:83]
	v_mfma_f32_16x16x32_bf16 v[68:71], v[146:149], v[206:209], v[68:71]
	v_mfma_f32_16x16x32_bf16 v[64:67], v[154:157], v[206:209], v[64:67]
	v_mfma_f32_16x16x32_bf16 v[116:119], v[150:153], v[180:183], v[116:119]
	v_mfma_f32_16x16x32_bf16 v[112:115], v[168:171], v[180:183], v[112:115]
	v_mfma_f32_16x16x32_bf16 v[100:103], v[150:153], v[188:191], v[100:103]
	v_mfma_f32_16x16x32_bf16 v[96:99], v[168:171], v[188:191], v[96:99]
	v_mfma_f32_16x16x32_bf16 v[84:87], v[150:153], v[200:203], v[84:87]
	v_mfma_f32_16x16x32_bf16 v[80:83], v[168:171], v[200:203], v[80:83]
	v_mfma_f32_16x16x32_bf16 v[68:71], v[150:153], v[210:213], v[68:71]
	v_mfma_f32_16x16x32_bf16 v[64:67], v[168:171], v[210:213], v[64:67]
	s_setprio 0
	s_barrier
	s_add_i32 s35, s35, s74
	v_lshl_add_u64 v[176:177], s[60:61], 0, v[140:141]
	s_mov_b32 m0, s35
	ds_read_b128 v[172:175], v179 offset:16384
	ds_read_b128 v[180:183], v179 offset:17408
	ds_read_b128 v[184:187], v179 offset:18432
	ds_read_b128 v[188:191], v179 offset:19456
	ds_read_b128 v[192:195], v179 offset:20480
	ds_read_b128 v[200:203], v179 offset:21504
	ds_read_b128 v[206:209], v179 offset:22528
	ds_read_b128 v[210:213], v179 offset:23552
	global_load_lds_dwordx4 v[176:177], off
	s_add_i32 m0, s35, 0x2000
	v_lshl_add_u64 v[196:197], s[60:61], 0, v[158:159]
	s_add_u32 s60, s60, s13
	s_addc_u32 s61, s61, 0
	s_add_i32 s35, s57, s74
	global_load_lds_dwordx4 v[196:197], off
	v_lshl_add_u64 v[198:199], s[60:61], 0, v[140:141]
	s_mov_b32 m0, s35
	v_lshl_add_u64 v[204:205], s[60:61], 0, v[158:159]
	global_load_lds_dwordx4 v[198:199], off
	s_add_i32 m0, s35, 0x2000
	v_lshl_add_u64 v[214:215], s[10:11], 0, v[162:163]
	global_load_lds_dwordx4 v[204:205], off
	s_mov_b32 m0, s75
	s_nop 0
	global_load_lds_dwordx4 v[214:215], off
	v_lshl_add_u64 v[214:215], s[10:11], 0, v[160:161]
	s_mov_b32 m0, s26
	s_nop 0
	global_load_lds_dwordx4 v[214:215], off
	s_waitcnt vmcnt(8)
	s_waitcnt lgkmcnt(0)
	s_barrier
	s_setprio 1
	s_waitcnt lgkmcnt(0)
	v_mfma_f32_16x16x32_bf16 v[60:63], v[128:131], v[172:175], v[60:63]
	v_mfma_f32_16x16x32_bf16 v[56:59], v[136:139], v[172:175], v[56:59]
	v_mfma_f32_16x16x32_bf16 v[44:47], v[128:131], v[184:187], v[44:47]
	v_mfma_f32_16x16x32_bf16 v[40:43], v[136:139], v[184:187], v[40:43]
	v_mfma_f32_16x16x32_bf16 v[28:31], v[128:131], v[192:195], v[28:31]
	v_mfma_f32_16x16x32_bf16 v[24:27], v[136:139], v[192:195], v[24:27]
	v_mfma_f32_16x16x32_bf16 v[12:15], v[128:131], v[206:209], v[12:15]
	v_mfma_f32_16x16x32_bf16 v[8:11], v[136:139], v[206:209], v[8:11]
	v_mfma_f32_16x16x32_bf16 v[60:63], v[132:135], v[180:183], v[60:63]
	v_mfma_f32_16x16x32_bf16 v[56:59], v[142:145], v[180:183], v[56:59]
	v_mfma_f32_16x16x32_bf16 v[44:47], v[132:135], v[188:191], v[44:47]
	v_mfma_f32_16x16x32_bf16 v[40:43], v[142:145], v[188:191], v[40:43]
	v_mfma_f32_16x16x32_bf16 v[28:31], v[132:135], v[200:203], v[28:31]
	v_mfma_f32_16x16x32_bf16 v[24:27], v[142:145], v[200:203], v[24:27]
	v_mfma_f32_16x16x32_bf16 v[12:15], v[132:135], v[210:213], v[12:15]
	v_mfma_f32_16x16x32_bf16 v[8:11], v[142:145], v[210:213], v[8:11]
	v_mfma_f32_16x16x32_bf16 v[52:55], v[146:149], v[172:175], v[52:55]
	v_mfma_f32_16x16x32_bf16 v[48:51], v[154:157], v[172:175], v[48:51]
	v_mfma_f32_16x16x32_bf16 v[36:39], v[146:149], v[184:187], v[36:39]
	v_mfma_f32_16x16x32_bf16 v[32:35], v[154:157], v[184:187], v[32:35]
	v_mfma_f32_16x16x32_bf16 v[20:23], v[146:149], v[192:195], v[20:23]
	v_mfma_f32_16x16x32_bf16 v[16:19], v[154:157], v[192:195], v[16:19]
	v_mfma_f32_16x16x32_bf16 v[4:7], v[146:149], v[206:209], v[4:7]
	v_mfma_f32_16x16x32_bf16 v[0:3], v[154:157], v[206:209], v[0:3]
	v_mfma_f32_16x16x32_bf16 v[52:55], v[150:153], v[180:183], v[52:55]
	v_mfma_f32_16x16x32_bf16 v[48:51], v[168:171], v[180:183], v[48:51]
	v_mfma_f32_16x16x32_bf16 v[36:39], v[150:153], v[188:191], v[36:39]
	v_mfma_f32_16x16x32_bf16 v[32:35], v[168:171], v[188:191], v[32:35]
	v_mfma_f32_16x16x32_bf16 v[20:23], v[150:153], v[200:203], v[20:23]
	v_mfma_f32_16x16x32_bf16 v[16:19], v[168:171], v[200:203], v[16:19]
	v_mfma_f32_16x16x32_bf16 v[4:7], v[150:153], v[210:213], v[4:7]
	v_mfma_f32_16x16x32_bf16 v[0:3], v[168:171], v[210:213], v[0:3]
	s_setprio 0
	s_barrier
	s_add_i32 s35, 0, 0x18000
	s_add_i32 s57, 0, 0x1c000
	v_add_u32_e32 v142, s35, v178
	v_add_u32_e32 v168, s57, v178
	ds_read_b128 v[128:131], v142
	ds_read_b128 v[132:135], v142 offset:1024
	ds_read_b128 v[136:139], v142 offset:2048
	ds_read_b128 v[142:145], v142 offset:3072
	ds_read_b128 v[146:149], v168
	ds_read_b128 v[150:153], v168 offset:1024
	ds_read_b128 v[154:157], v168 offset:2048
	ds_read_b128 v[168:171], v168 offset:3072
	s_add_u32 s10, s10, s48
	s_addc_u32 s11, s11, 0
	s_mov_b32 m0, s27
	v_lshl_add_u64 v[214:215], s[10:11], 0, v[162:163]
	ds_read_b128 v[172:175], v179 offset:32768
	ds_read_b128 v[180:183], v179 offset:33792
	ds_read_b128 v[184:187], v179 offset:34816
	ds_read_b128 v[188:191], v179 offset:35840
	ds_read_b128 v[192:195], v179 offset:36864
	ds_read_b128 v[200:203], v179 offset:37888
	ds_read_b128 v[206:209], v179 offset:38912
	ds_read_b128 v[210:213], v179 offset:39936
	global_load_lds_dwordx4 v[214:215], off
	v_lshl_add_u64 v[214:215], s[10:11], 0, v[160:161]
	s_mov_b32 m0, s15
	s_nop 0
	global_load_lds_dwordx4 v[214:215], off
	s_waitcnt vmcnt(8)
	s_waitcnt lgkmcnt(0)
	s_barrier
	s_setprio 1
	s_waitcnt lgkmcnt(0)
	v_mfma_f32_16x16x32_bf16 v[124:127], v[128:131], v[172:175], v[124:127]
	v_mfma_f32_16x16x32_bf16 v[120:123], v[136:139], v[172:175], v[120:123]
	v_mfma_f32_16x16x32_bf16 v[108:111], v[128:131], v[184:187], v[108:111]
	v_mfma_f32_16x16x32_bf16 v[104:107], v[136:139], v[184:187], v[104:107]
	v_mfma_f32_16x16x32_bf16 v[92:95], v[128:131], v[192:195], v[92:95]
	v_mfma_f32_16x16x32_bf16 v[88:91], v[136:139], v[192:195], v[88:91]
	v_mfma_f32_16x16x32_bf16 v[76:79], v[128:131], v[206:209], v[76:79]
	v_mfma_f32_16x16x32_bf16 v[72:75], v[136:139], v[206:209], v[72:75]
	v_mfma_f32_16x16x32_bf16 v[124:127], v[132:135], v[180:183], v[124:127]
	v_mfma_f32_16x16x32_bf16 v[120:123], v[142:145], v[180:183], v[120:123]
	v_mfma_f32_16x16x32_bf16 v[108:111], v[132:135], v[188:191], v[108:111]
	v_mfma_f32_16x16x32_bf16 v[104:107], v[142:145], v[188:191], v[104:107]
	v_mfma_f32_16x16x32_bf16 v[92:95], v[132:135], v[200:203], v[92:95]
	v_mfma_f32_16x16x32_bf16 v[88:91], v[142:145], v[200:203], v[88:91]
	v_mfma_f32_16x16x32_bf16 v[76:79], v[132:135], v[210:213], v[76:79]
	v_mfma_f32_16x16x32_bf16 v[72:75], v[142:145], v[210:213], v[72:75]
	v_mfma_f32_16x16x32_bf16 v[116:119], v[146:149], v[172:175], v[116:119]
	v_mfma_f32_16x16x32_bf16 v[112:115], v[154:157], v[172:175], v[112:115]
	v_mfma_f32_16x16x32_bf16 v[100:103], v[146:149], v[184:187], v[100:103]
	v_mfma_f32_16x16x32_bf16 v[96:99], v[154:157], v[184:187], v[96:99]
	v_mfma_f32_16x16x32_bf16 v[84:87], v[146:149], v[192:195], v[84:87]
	v_mfma_f32_16x16x32_bf16 v[80:83], v[154:157], v[192:195], v[80:83]
	v_mfma_f32_16x16x32_bf16 v[68:71], v[146:149], v[206:209], v[68:71]
	v_mfma_f32_16x16x32_bf16 v[64:67], v[154:157], v[206:209], v[64:67]
	v_mfma_f32_16x16x32_bf16 v[116:119], v[150:153], v[180:183], v[116:119]
	v_mfma_f32_16x16x32_bf16 v[112:115], v[168:171], v[180:183], v[112:115]
	v_mfma_f32_16x16x32_bf16 v[100:103], v[150:153], v[188:191], v[100:103]
	v_mfma_f32_16x16x32_bf16 v[96:99], v[168:171], v[188:191], v[96:99]
	v_mfma_f32_16x16x32_bf16 v[84:87], v[150:153], v[200:203], v[84:87]
	v_mfma_f32_16x16x32_bf16 v[80:83], v[168:171], v[200:203], v[80:83]
	v_mfma_f32_16x16x32_bf16 v[68:71], v[150:153], v[210:213], v[68:71]
	v_mfma_f32_16x16x32_bf16 v[64:67], v[168:171], v[210:213], v[64:67]
	s_setprio 0
	s_barrier
	s_add_i32 s10, s35, s74
	v_lshl_add_u64 v[176:177], v[176:177], 0, s[36:37]
	s_mov_b32 m0, s10
	ds_read_b128 v[172:175], v179 offset:49152
	ds_read_b128 v[180:183], v179 offset:50176
	ds_read_b128 v[184:187], v179 offset:51200
	ds_read_b128 v[188:191], v179 offset:52224
	ds_read_b128 v[192:195], v179 offset:53248
	ds_read_b128 v[200:203], v179 offset:54272
	ds_read_b128 v[206:209], v179 offset:55296
	ds_read_b128 v[210:213], v179 offset:56320
	global_load_lds_dwordx4 v[176:177], off
	v_lshl_add_u64 v[176:177], v[196:197], 0, s[36:37]
	s_add_i32 m0, s10, 0x2000
	s_add_i32 s10, s57, s74
	global_load_lds_dwordx4 v[176:177], off
	v_lshl_add_u64 v[176:177], v[198:199], 0, s[36:37]
	s_mov_b32 m0, s10
	s_nop 0
	global_load_lds_dwordx4 v[176:177], off
	v_lshl_add_u64 v[176:177], v[204:205], 0, s[36:37]
	s_add_i32 m0, s10, 0x2000
	s_nop 0
	global_load_lds_dwordx4 v[176:177], off
	v_lshl_add_u64 v[176:177], s[8:9], 0, v[162:163]
	s_mov_b32 m0, s28
	s_nop 0
	global_load_lds_dwordx4 v[176:177], off
	v_lshl_add_u64 v[176:177], s[8:9], 0, v[160:161]
	s_mov_b32 m0, s29
	s_nop 0
	global_load_lds_dwordx4 v[176:177], off
	s_waitcnt vmcnt(8)
	s_waitcnt lgkmcnt(0)
	s_barrier
	s_setprio 1
	s_waitcnt lgkmcnt(0)
	v_mfma_f32_16x16x32_bf16 v[60:63], v[128:131], v[172:175], v[60:63]
	v_mfma_f32_16x16x32_bf16 v[56:59], v[136:139], v[172:175], v[56:59]
	v_mfma_f32_16x16x32_bf16 v[44:47], v[128:131], v[184:187], v[44:47]
	v_mfma_f32_16x16x32_bf16 v[40:43], v[136:139], v[184:187], v[40:43]
	v_mfma_f32_16x16x32_bf16 v[28:31], v[128:131], v[192:195], v[28:31]
	v_mfma_f32_16x16x32_bf16 v[24:27], v[136:139], v[192:195], v[24:27]
	v_mfma_f32_16x16x32_bf16 v[12:15], v[128:131], v[206:209], v[12:15]
	v_mfma_f32_16x16x32_bf16 v[8:11], v[136:139], v[206:209], v[8:11]
	v_mfma_f32_16x16x32_bf16 v[60:63], v[132:135], v[180:183], v[60:63]
	v_mfma_f32_16x16x32_bf16 v[56:59], v[142:145], v[180:183], v[56:59]
	v_mfma_f32_16x16x32_bf16 v[44:47], v[132:135], v[188:191], v[44:47]
	v_mfma_f32_16x16x32_bf16 v[40:43], v[142:145], v[188:191], v[40:43]
	v_mfma_f32_16x16x32_bf16 v[28:31], v[132:135], v[200:203], v[28:31]
	v_mfma_f32_16x16x32_bf16 v[24:27], v[142:145], v[200:203], v[24:27]
	v_mfma_f32_16x16x32_bf16 v[12:15], v[132:135], v[210:213], v[12:15]
	v_mfma_f32_16x16x32_bf16 v[8:11], v[142:145], v[210:213], v[8:11]
	v_mfma_f32_16x16x32_bf16 v[52:55], v[146:149], v[172:175], v[52:55]
	v_mfma_f32_16x16x32_bf16 v[48:51], v[154:157], v[172:175], v[48:51]
	v_mfma_f32_16x16x32_bf16 v[36:39], v[146:149], v[184:187], v[36:39]
	v_mfma_f32_16x16x32_bf16 v[32:35], v[154:157], v[184:187], v[32:35]
	v_mfma_f32_16x16x32_bf16 v[20:23], v[146:149], v[192:195], v[20:23]
	v_mfma_f32_16x16x32_bf16 v[16:19], v[154:157], v[192:195], v[16:19]
	v_mfma_f32_16x16x32_bf16 v[4:7], v[146:149], v[206:209], v[4:7]
	v_mfma_f32_16x16x32_bf16 v[0:3], v[154:157], v[206:209], v[0:3]
	v_mfma_f32_16x16x32_bf16 v[52:55], v[150:153], v[180:183], v[52:55]
	v_mfma_f32_16x16x32_bf16 v[48:51], v[168:171], v[180:183], v[48:51]
	v_mfma_f32_16x16x32_bf16 v[36:39], v[150:153], v[188:191], v[36:39]
	v_mfma_f32_16x16x32_bf16 v[32:35], v[168:171], v[188:191], v[32:35]
	v_mfma_f32_16x16x32_bf16 v[20:23], v[150:153], v[200:203], v[20:23]
	v_mfma_f32_16x16x32_bf16 v[16:19], v[168:171], v[200:203], v[16:19]
	v_mfma_f32_16x16x32_bf16 v[4:7], v[150:153], v[210:213], v[4:7]
	v_mfma_f32_16x16x32_bf16 v[0:3], v[168:171], v[210:213], v[0:3]
	s_setprio 0
	s_barrier
	s_add_u32 s24, s24, 0x100
	s_addc_u32 s38, s38, 0
	s_add_u32 s6, s6, 0x10000
	s_addc_u32 s7, s7, 0
	s_cmp_ge_u32 s56, s12
	s_mov_b32 s8, s56
	s_cbranch_scc0 .LBB0_333
	s_and_b64 vcc, exec, s[52:53]
	s_cbranch_vccz .LBB0_336
	s_barrier

.LBB0_375:
	s_add_i32 s24, s8, 2
	s_add_u32 s35, s6, 0x80
	s_addc_u32 s9, s7, 0
	s_add_i32 s38, 0, 0x10000
	s_cmp_eq_u32 s94, s8
	s_cselect_b32 s9, s43, s9
	s_cselect_b32 s8, s42, s35
	s_cselect_b32 s57, s55, s11
	s_cselect_b32 s56, s54, s10
	s_add_i32 s35, 0, 0x14000
	v_add_u32_e32 v142, s38, v178
	v_add_u32_e32 v168, s35, v178
	ds_read_b128 v[128:131], v142
	ds_read_b128 v[132:135], v142 offset:1024
	ds_read_b128 v[136:139], v142 offset:2048
	ds_read_b128 v[142:145], v142 offset:3072
	ds_read_b128 v[146:149], v168
	ds_read_b128 v[150:153], v168 offset:1024
	ds_read_b128 v[154:157], v168 offset:2048
	ds_read_b128 v[168:171], v168 offset:3072
	v_lshl_add_u64 v[176:177], s[6:7], 0, v[164:165]
	s_add_i32 m0, s15, 0xc000
	ds_read_b128 v[172:175], v179
	ds_read_b128 v[180:183], v179 offset:1024
	ds_read_b128 v[184:187], v179 offset:2048
	ds_read_b128 v[188:191], v179 offset:3072
	ds_read_b128 v[192:195], v179 offset:4096
	ds_read_b128 v[200:203], v179 offset:5120
	ds_read_b128 v[206:209], v179 offset:6144
	ds_read_b128 v[210:213], v179 offset:7168
	global_load_lds_dwordx4 v[176:177], off
	v_lshl_add_u64 v[176:177], s[6:7], 0, v[166:167]
	s_add_i32 m0, s15, 0xe000
	s_nop 0
	global_load_lds_dwordx4 v[176:177], off
	s_waitcnt vmcnt(8)
	s_waitcnt lgkmcnt(0)
	s_barrier
	s_setprio 1
	s_waitcnt lgkmcnt(0)
	v_mfma_f32_16x16x32_bf16 v[124:127], v[128:131], v[172:175], v[124:127]
	v_mfma_f32_16x16x32_bf16 v[120:123], v[136:139], v[172:175], v[120:123]
	v_mfma_f32_16x16x32_bf16 v[108:111], v[128:131], v[184:187], v[108:111]
	v_mfma_f32_16x16x32_bf16 v[104:107], v[136:139], v[184:187], v[104:107]
	v_mfma_f32_16x16x32_bf16 v[92:95], v[128:131], v[192:195], v[92:95]
	v_mfma_f32_16x16x32_bf16 v[88:91], v[136:139], v[192:195], v[88:91]
	v_mfma_f32_16x16x32_bf16 v[76:79], v[128:131], v[206:209], v[76:79]
	v_mfma_f32_16x16x32_bf16 v[72:75], v[136:139], v[206:209], v[72:75]
	v_mfma_f32_16x16x32_bf16 v[124:127], v[132:135], v[180:183], v[124:127]
	v_mfma_f32_16x16x32_bf16 v[120:123], v[142:145], v[180:183], v[120:123]
	v_mfma_f32_16x16x32_bf16 v[108:111], v[132:135], v[188:191], v[108:111]
	v_mfma_f32_16x16x32_bf16 v[104:107], v[142:145], v[188:191], v[104:107]
	v_mfma_f32_16x16x32_bf16 v[92:95], v[132:135], v[200:203], v[92:95]
	v_mfma_f32_16x16x32_bf16 v[88:91], v[142:145], v[200:203], v[88:91]
	v_mfma_f32_16x16x32_bf16 v[76:79], v[132:135], v[210:213], v[76:79]
	v_mfma_f32_16x16x32_bf16 v[72:75], v[142:145], v[210:213], v[72:75]
	v_mfma_f32_16x16x32_bf16 v[116:119], v[146:149], v[172:175], v[116:119]
	v_mfma_f32_16x16x32_bf16 v[112:115], v[154:157], v[172:175], v[112:115]
	v_mfma_f32_16x16x32_bf16 v[100:103], v[146:149], v[184:187], v[100:103]
	v_mfma_f32_16x16x32_bf16 v[96:99], v[154:157], v[184:187], v[96:99]
	v_mfma_f32_16x16x32_bf16 v[84:87], v[146:149], v[192:195], v[84:87]
	v_mfma_f32_16x16x32_bf16 v[80:83], v[154:157], v[192:195], v[80:83]
	v_mfma_f32_16x16x32_bf16 v[68:71], v[146:149], v[206:209], v[68:71]
	v_mfma_f32_16x16x32_bf16 v[64:67], v[154:157], v[206:209], v[64:67]
	v_mfma_f32_16x16x32_bf16 v[116:119], v[150:153], v[180:183], v[116:119]
	v_mfma_f32_16x16x32_bf16 v[112:115], v[168:171], v[180:183], v[112:115]
	v_mfma_f32_16x16x32_bf16 v[100:103], v[150:153], v[188:191], v[100:103]
	v_mfma_f32_16x16x32_bf16 v[96:99], v[168:171], v[188:191], v[96:99]
	v_mfma_f32_16x16x32_bf16 v[84:87], v[150:153], v[200:203], v[84:87]
	v_mfma_f32_16x16x32_bf16 v[80:83], v[168:171], v[200:203], v[80:83]
	v_mfma_f32_16x16x32_bf16 v[68:71], v[150:153], v[210:213], v[68:71]
	v_mfma_f32_16x16x32_bf16 v[64:67], v[168:171], v[210:213], v[64:67]
	s_setprio 0
	s_barrier
	s_add_i32 s38, s38, s75
	v_lshl_add_u64 v[176:177], s[56:57], 0, v[140:141]
	s_mov_b32 m0, s38
	ds_read_b128 v[172:175], v179 offset:16384
	ds_read_b128 v[180:183], v179 offset:17408
	ds_read_b128 v[184:187], v179 offset:18432
	ds_read_b128 v[188:191], v179 offset:19456
	ds_read_b128 v[192:195], v179 offset:20480
	ds_read_b128 v[200:203], v179 offset:21504
	ds_read_b128 v[206:209], v179 offset:22528
	ds_read_b128 v[210:213], v179 offset:23552
	global_load_lds_dwordx4 v[176:177], off
	s_add_i32 m0, s38, 0x2000
	v_lshl_add_u64 v[196:197], s[56:57], 0, v[158:159]
	s_add_u32 s56, s56, s13
	s_addc_u32 s57, s57, 0
	s_add_i32 s35, s35, s75
	global_load_lds_dwordx4 v[196:197], off
	v_lshl_add_u64 v[198:199], s[56:57], 0, v[140:141]
	s_mov_b32 m0, s35
	v_lshl_add_u64 v[204:205], s[56:57], 0, v[158:159]
	global_load_lds_dwordx4 v[198:199], off
	s_add_i32 m0, s35, 0x2000
	v_lshl_add_u64 v[214:215], s[8:9], 0, v[162:163]
	global_load_lds_dwordx4 v[204:205], off
	s_mov_b32 m0, s15
	v_lshl_add_u64 v[216:217], s[8:9], 0, v[160:161]
	global_load_lds_dwordx4 v[214:215], off
	s_mov_b32 m0, s26
	s_nop 0
	global_load_lds_dwordx4 v[216:217], off
	s_waitcnt vmcnt(8)
	s_waitcnt lgkmcnt(0)
	s_barrier
	s_setprio 1
	s_waitcnt lgkmcnt(0)
	v_mfma_f32_16x16x32_bf16 v[60:63], v[128:131], v[172:175], v[60:63]
	v_mfma_f32_16x16x32_bf16 v[56:59], v[136:139], v[172:175], v[56:59]
	v_mfma_f32_16x16x32_bf16 v[44:47], v[128:131], v[184:187], v[44:47]
	v_mfma_f32_16x16x32_bf16 v[40:43], v[136:139], v[184:187], v[40:43]
	v_mfma_f32_16x16x32_bf16 v[28:31], v[128:131], v[192:195], v[28:31]
	v_mfma_f32_16x16x32_bf16 v[24:27], v[136:139], v[192:195], v[24:27]
	v_mfma_f32_16x16x32_bf16 v[12:15], v[128:131], v[206:209], v[12:15]
	v_mfma_f32_16x16x32_bf16 v[8:11], v[136:139], v[206:209], v[8:11]
	v_mfma_f32_16x16x32_bf16 v[60:63], v[132:135], v[180:183], v[60:63]
	v_mfma_f32_16x16x32_bf16 v[56:59], v[142:145], v[180:183], v[56:59]
	v_mfma_f32_16x16x32_bf16 v[44:47], v[132:135], v[188:191], v[44:47]
	v_mfma_f32_16x16x32_bf16 v[40:43], v[142:145], v[188:191], v[40:43]
	v_mfma_f32_16x16x32_bf16 v[28:31], v[132:135], v[200:203], v[28:31]
	v_mfma_f32_16x16x32_bf16 v[24:27], v[142:145], v[200:203], v[24:27]
	v_mfma_f32_16x16x32_bf16 v[12:15], v[132:135], v[210:213], v[12:15]
	v_mfma_f32_16x16x32_bf16 v[8:11], v[142:145], v[210:213], v[8:11]
	v_mfma_f32_16x16x32_bf16 v[52:55], v[146:149], v[172:175], v[52:55]
	v_mfma_f32_16x16x32_bf16 v[48:51], v[154:157], v[172:175], v[48:51]
	v_mfma_f32_16x16x32_bf16 v[36:39], v[146:149], v[184:187], v[36:39]
	v_mfma_f32_16x16x32_bf16 v[32:35], v[154:157], v[184:187], v[32:35]
	v_mfma_f32_16x16x32_bf16 v[20:23], v[146:149], v[192:195], v[20:23]
	v_mfma_f32_16x16x32_bf16 v[16:19], v[154:157], v[192:195], v[16:19]
	v_mfma_f32_16x16x32_bf16 v[4:7], v[146:149], v[206:209], v[4:7]
	v_mfma_f32_16x16x32_bf16 v[0:3], v[154:157], v[206:209], v[0:3]
	v_mfma_f32_16x16x32_bf16 v[52:55], v[150:153], v[180:183], v[52:55]
	v_mfma_f32_16x16x32_bf16 v[48:51], v[168:171], v[180:183], v[48:51]
	v_mfma_f32_16x16x32_bf16 v[36:39], v[150:153], v[188:191], v[36:39]
	v_mfma_f32_16x16x32_bf16 v[32:35], v[168:171], v[188:191], v[32:35]
	v_mfma_f32_16x16x32_bf16 v[20:23], v[150:153], v[200:203], v[20:23]
	v_mfma_f32_16x16x32_bf16 v[16:19], v[168:171], v[200:203], v[16:19]
	v_mfma_f32_16x16x32_bf16 v[4:7], v[150:153], v[210:213], v[4:7]
	v_mfma_f32_16x16x32_bf16 v[0:3], v[168:171], v[210:213], v[0:3]
	s_setprio 0
	s_barrier
	s_add_i32 s35, 0, 0x18000
	s_add_i32 s38, 0, 0x1c000
	v_add_u32_e32 v142, s35, v178
	v_add_u32_e32 v168, s38, v178
	ds_read_b128 v[128:131], v142
	ds_read_b128 v[132:135], v142 offset:1024
	ds_read_b128 v[136:139], v142 offset:2048
	ds_read_b128 v[142:145], v142 offset:3072
	ds_read_b128 v[146:149], v168
	ds_read_b128 v[150:153], v168 offset:1024
	ds_read_b128 v[154:157], v168 offset:2048
	ds_read_b128 v[168:171], v168 offset:3072
	s_add_u32 s8, s8, s48
	s_addc_u32 s9, s9, 0
	s_mov_b32 m0, s27
	v_lshl_add_u64 v[218:219], s[8:9], 0, v[162:163]
	ds_read_b128 v[172:175], v179 offset:32768
	ds_read_b128 v[180:183], v179 offset:33792
	ds_read_b128 v[184:187], v179 offset:34816
	ds_read_b128 v[188:191], v179 offset:35840
	ds_read_b128 v[192:195], v179 offset:36864
	ds_read_b128 v[200:203], v179 offset:37888
	ds_read_b128 v[206:209], v179 offset:38912
	ds_read_b128 v[210:213], v179 offset:39936
	global_load_lds_dwordx4 v[218:219], off
	v_lshl_add_u64 v[218:219], s[8:9], 0, v[160:161]
	s_mov_b32 m0, s28
	s_nop 0
	global_load_lds_dwordx4 v[218:219], off
	s_waitcnt vmcnt(8)
	s_waitcnt lgkmcnt(0)
	s_barrier
	s_setprio 1
	s_waitcnt lgkmcnt(0)
	v_mfma_f32_16x16x32_bf16 v[124:127], v[128:131], v[172:175], v[124:127]
	v_mfma_f32_16x16x32_bf16 v[120:123], v[136:139], v[172:175], v[120:123]
	v_mfma_f32_16x16x32_bf16 v[108:111], v[128:131], v[184:187], v[108:111]
	v_mfma_f32_16x16x32_bf16 v[104:107], v[136:139], v[184:187], v[104:107]
	v_mfma_f32_16x16x32_bf16 v[92:95], v[128:131], v[192:195], v[92:95]
	v_mfma_f32_16x16x32_bf16 v[88:91], v[136:139], v[192:195], v[88:91]
	v_mfma_f32_16x16x32_bf16 v[76:79], v[128:131], v[206:209], v[76:79]
	v_mfma_f32_16x16x32_bf16 v[72:75], v[136:139], v[206:209], v[72:75]
	v_mfma_f32_16x16x32_bf16 v[124:127], v[132:135], v[180:183], v[124:127]
	v_mfma_f32_16x16x32_bf16 v[120:123], v[142:145], v[180:183], v[120:123]
	v_mfma_f32_16x16x32_bf16 v[108:111], v[132:135], v[188:191], v[108:111]
	v_mfma_f32_16x16x32_bf16 v[104:107], v[142:145], v[188:191], v[104:107]
	v_mfma_f32_16x16x32_bf16 v[92:95], v[132:135], v[200:203], v[92:95]
	v_mfma_f32_16x16x32_bf16 v[88:91], v[142:145], v[200:203], v[88:91]
	v_mfma_f32_16x16x32_bf16 v[76:79], v[132:135], v[210:213], v[76:79]
	v_mfma_f32_16x16x32_bf16 v[72:75], v[142:145], v[210:213], v[72:75]
	v_mfma_f32_16x16x32_bf16 v[116:119], v[146:149], v[172:175], v[116:119]
	v_mfma_f32_16x16x32_bf16 v[112:115], v[154:157], v[172:175], v[112:115]
	v_mfma_f32_16x16x32_bf16 v[100:103], v[146:149], v[184:187], v[100:103]
	v_mfma_f32_16x16x32_bf16 v[96:99], v[154:157], v[184:187], v[96:99]
	v_mfma_f32_16x16x32_bf16 v[84:87], v[146:149], v[192:195], v[84:87]
	v_mfma_f32_16x16x32_bf16 v[80:83], v[154:157], v[192:195], v[80:83]
	v_mfma_f32_16x16x32_bf16 v[68:71], v[146:149], v[206:209], v[68:71]
	v_mfma_f32_16x16x32_bf16 v[64:67], v[154:157], v[206:209], v[64:67]
	v_mfma_f32_16x16x32_bf16 v[116:119], v[150:153], v[180:183], v[116:119]
	v_mfma_f32_16x16x32_bf16 v[112:115], v[168:171], v[180:183], v[112:115]
	v_mfma_f32_16x16x32_bf16 v[100:103], v[150:153], v[188:191], v[100:103]
	v_mfma_f32_16x16x32_bf16 v[96:99], v[168:171], v[188:191], v[96:99]
	v_mfma_f32_16x16x32_bf16 v[84:87], v[150:153], v[200:203], v[84:87]
	v_mfma_f32_16x16x32_bf16 v[80:83], v[168:171], v[200:203], v[80:83]
	v_mfma_f32_16x16x32_bf16 v[68:71], v[150:153], v[210:213], v[68:71]
	v_mfma_f32_16x16x32_bf16 v[64:67], v[168:171], v[210:213], v[64:67]
	s_setprio 0
	s_barrier
	s_add_i32 s8, s35, s75
	v_lshl_add_u64 v[176:177], v[176:177], 0, s[36:37]
	s_mov_b32 m0, s8
	ds_read_b128 v[172:175], v179 offset:49152
	ds_read_b128 v[180:183], v179 offset:50176
	ds_read_b128 v[184:187], v179 offset:51200
	ds_read_b128 v[188:191], v179 offset:52224
	ds_read_b128 v[192:195], v179 offset:53248
	ds_read_b128 v[200:203], v179 offset:54272
	ds_read_b128 v[206:209], v179 offset:55296
	ds_read_b128 v[210:213], v179 offset:56320
	global_load_lds_dwordx4 v[176:177], off
	v_lshl_add_u64 v[176:177], v[196:197], 0, s[36:37]
	s_add_i32 m0, s8, 0x2000
	s_add_i32 s8, s38, s75
	global_load_lds_dwordx4 v[176:177], off
	v_lshl_add_u64 v[176:177], v[198:199], 0, s[36:37]
	s_mov_b32 m0, s8
	s_nop 0
	global_load_lds_dwordx4 v[176:177], off
	v_lshl_add_u64 v[176:177], v[204:205], 0, s[36:37]
	s_add_i32 m0, s8, 0x2000
	s_nop 0
	global_load_lds_dwordx4 v[176:177], off
	v_lshl_add_u64 v[176:177], v[214:215], 0, s[36:37]
	s_mov_b32 m0, s29
	s_nop 0
	global_load_lds_dwordx4 v[176:177], off
	v_lshl_add_u64 v[176:177], v[216:217], 0, s[36:37]
	s_mov_b32 m0, s58
	s_nop 0
	global_load_lds_dwordx4 v[176:177], off
	s_waitcnt vmcnt(8)
	s_waitcnt lgkmcnt(0)
	s_barrier
	s_setprio 1
	s_waitcnt lgkmcnt(0)
	v_mfma_f32_16x16x32_bf16 v[60:63], v[128:131], v[172:175], v[60:63]
	v_mfma_f32_16x16x32_bf16 v[56:59], v[136:139], v[172:175], v[56:59]
	v_mfma_f32_16x16x32_bf16 v[44:47], v[128:131], v[184:187], v[44:47]
	v_mfma_f32_16x16x32_bf16 v[40:43], v[136:139], v[184:187], v[40:43]
	v_mfma_f32_16x16x32_bf16 v[28:31], v[128:131], v[192:195], v[28:31]
	v_mfma_f32_16x16x32_bf16 v[24:27], v[136:139], v[192:195], v[24:27]
	v_mfma_f32_16x16x32_bf16 v[12:15], v[128:131], v[206:209], v[12:15]
	v_mfma_f32_16x16x32_bf16 v[8:11], v[136:139], v[206:209], v[8:11]
	v_mfma_f32_16x16x32_bf16 v[60:63], v[132:135], v[180:183], v[60:63]
	v_mfma_f32_16x16x32_bf16 v[56:59], v[142:145], v[180:183], v[56:59]
	v_mfma_f32_16x16x32_bf16 v[44:47], v[132:135], v[188:191], v[44:47]
	v_mfma_f32_16x16x32_bf16 v[40:43], v[142:145], v[188:191], v[40:43]
	v_mfma_f32_16x16x32_bf16 v[28:31], v[132:135], v[200:203], v[28:31]
	v_mfma_f32_16x16x32_bf16 v[24:27], v[142:145], v[200:203], v[24:27]
	v_mfma_f32_16x16x32_bf16 v[12:15], v[132:135], v[210:213], v[12:15]
	v_mfma_f32_16x16x32_bf16 v[8:11], v[142:145], v[210:213], v[8:11]
	v_mfma_f32_16x16x32_bf16 v[52:55], v[146:149], v[172:175], v[52:55]
	v_mfma_f32_16x16x32_bf16 v[48:51], v[154:157], v[172:175], v[48:51]
	v_mfma_f32_16x16x32_bf16 v[36:39], v[146:149], v[184:187], v[36:39]
	v_mfma_f32_16x16x32_bf16 v[32:35], v[154:157], v[184:187], v[32:35]
	v_mfma_f32_16x16x32_bf16 v[20:23], v[146:149], v[192:195], v[20:23]
	v_mfma_f32_16x16x32_bf16 v[16:19], v[154:157], v[192:195], v[16:19]
	v_mfma_f32_16x16x32_bf16 v[4:7], v[146:149], v[206:209], v[4:7]
	v_mfma_f32_16x16x32_bf16 v[0:3], v[154:157], v[206:209], v[0:3]
	v_mfma_f32_16x16x32_bf16 v[52:55], v[150:153], v[180:183], v[52:55]
	v_mfma_f32_16x16x32_bf16 v[48:51], v[168:171], v[180:183], v[48:51]
	v_mfma_f32_16x16x32_bf16 v[36:39], v[150:153], v[188:191], v[36:39]
	v_mfma_f32_16x16x32_bf16 v[32:35], v[168:171], v[188:191], v[32:35]
	v_mfma_f32_16x16x32_bf16 v[20:23], v[150:153], v[200:203], v[20:23]
	v_mfma_f32_16x16x32_bf16 v[16:19], v[168:171], v[200:203], v[16:19]
	v_mfma_f32_16x16x32_bf16 v[4:7], v[150:153], v[210:213], v[4:7]
	v_mfma_f32_16x16x32_bf16 v[0:3], v[168:171], v[210:213], v[0:3]
	s_setprio 0
	s_barrier
	s_add_u32 s6, s6, 0x100
	s_addc_u32 s7, s7, 0
	s_add_u32 s10, s10, 0x100
	s_addc_u32 s11, s11, 0
	s_cmp_ge_u32 s24, s12
	s_mov_b32 s8, s24
	s_cbranch_scc0 .LBB0_375
	s_and_b64 vcc, exec, s[52:53]
	s_cbranch_vccz .LBB0_378
	s_barrier

.LBB0_417:
	s_lshl_b64 s[10:11], s[52:53], 17
	s_add_u32 s56, s12, s10
	s_addc_u32 s57, s13, s11
	s_and_b64 s[10:11], s[40:41], exec
	s_cselect_b32 s11, s57, s9
	s_cselect_b32 s10, s56, s8
	s_add_i32 s55, 0, 0x10000
	s_add_i32 s38, 0, 0x14000
	v_add_u32_e32 v212, s55, v174
	v_add_u32_e32 v213, s38, v174
	ds_read_b128 v[0:3], v212
	ds_read_b128 v[4:7], v212 offset:1024
	ds_read_b128 v[8:11], v212 offset:2048
	ds_read_b128 v[12:15], v212 offset:3072
	ds_read_b128 v[16:19], v213
	ds_read_b128 v[20:23], v213 offset:1024
	ds_read_b128 v[24:27], v213 offset:2048
	ds_read_b128 v[28:31], v213 offset:3072
	s_add_u32 s60, s6, 0x40080
	s_addc_u32 s61, s7, 0
	s_add_i32 s59, s26, 0xc000
	v_lshl_add_u64 v[64:65], s[60:61], 0, v[162:163]
	s_mov_b32 m0, s59
	s_add_i32 s24, s26, 0xe000
	ds_read_b128 v[32:35], v175
	ds_read_b128 v[36:39], v175 offset:1024
	ds_read_b128 v[40:43], v175 offset:2048
	ds_read_b128 v[44:47], v175 offset:3072
	ds_read_b128 v[48:51], v175 offset:4096
	ds_read_b128 v[52:55], v175 offset:5120
	ds_read_b128 v[56:59], v175 offset:6144
	ds_read_b128 v[60:63], v175 offset:7168
	global_load_lds_dwordx4 v[64:65], off
	v_lshl_add_u64 v[64:65], s[60:61], 0, v[160:161]
	s_mov_b32 m0, s24
	s_nop 0
	global_load_lds_dwordx4 v[64:65], off
	s_waitcnt vmcnt(8)
	s_waitcnt lgkmcnt(0)
	s_barrier
	s_setprio 1
	s_waitcnt lgkmcnt(0)
	v_mfma_f32_16x16x32_bf16 v[64:67], v[0:3], v[32:35], 0
	v_mfma_f32_16x16x32_bf16 v[68:71], v[8:11], v[32:35], 0
	v_mfma_f32_16x16x32_bf16 v[72:75], v[0:3], v[40:43], 0
	v_mfma_f32_16x16x32_bf16 v[76:79], v[8:11], v[40:43], 0
	v_mfma_f32_16x16x32_bf16 v[80:83], v[0:3], v[48:51], 0
	v_mfma_f32_16x16x32_bf16 v[84:87], v[8:11], v[48:51], 0
	v_mfma_f32_16x16x32_bf16 v[88:91], v[0:3], v[56:59], 0
	v_mfma_f32_16x16x32_bf16 v[92:95], v[8:11], v[56:59], 0
	v_mfma_f32_16x16x32_bf16 v[64:67], v[4:7], v[36:39], v[64:67]
	v_mfma_f32_16x16x32_bf16 v[68:71], v[12:15], v[36:39], v[68:71]
	v_mfma_f32_16x16x32_bf16 v[72:75], v[4:7], v[44:47], v[72:75]
	v_mfma_f32_16x16x32_bf16 v[76:79], v[12:15], v[44:47], v[76:79]
	v_mfma_f32_16x16x32_bf16 v[80:83], v[4:7], v[52:55], v[80:83]
	v_mfma_f32_16x16x32_bf16 v[84:87], v[12:15], v[52:55], v[84:87]
	v_mfma_f32_16x16x32_bf16 v[88:91], v[4:7], v[60:63], v[88:91]
	v_mfma_f32_16x16x32_bf16 v[92:95], v[12:15], v[60:63], v[92:95]
	v_mfma_f32_16x16x32_bf16 v[96:99], v[16:19], v[32:35], 0
	v_mfma_f32_16x16x32_bf16 v[32:35], v[24:27], v[32:35], 0
	v_mfma_f32_16x16x32_bf16 v[96:99], v[20:23], v[36:39], v[96:99]
	v_mfma_f32_16x16x32_bf16 v[32:35], v[28:31], v[36:39], v[32:35]
	v_mfma_f32_16x16x32_bf16 v[36:39], v[16:19], v[40:43], 0
	v_mfma_f32_16x16x32_bf16 v[40:43], v[24:27], v[40:43], 0
	v_mfma_f32_16x16x32_bf16 v[36:39], v[20:23], v[44:47], v[36:39]
	v_mfma_f32_16x16x32_bf16 v[40:43], v[28:31], v[44:47], v[40:43]
	v_mfma_f32_16x16x32_bf16 v[44:47], v[16:19], v[48:51], 0
	v_mfma_f32_16x16x32_bf16 v[48:51], v[24:27], v[48:51], 0
	v_mfma_f32_16x16x32_bf16 v[44:47], v[20:23], v[52:55], v[44:47]
	v_mfma_f32_16x16x32_bf16 v[48:51], v[28:31], v[52:55], v[48:51]
	v_mfma_f32_16x16x32_bf16 v[52:55], v[16:19], v[56:59], 0
	v_mfma_f32_16x16x32_bf16 v[56:59], v[24:27], v[56:59], 0
	v_mfma_f32_16x16x32_bf16 v[52:55], v[20:23], v[60:63], v[52:55]
	v_mfma_f32_16x16x32_bf16 v[56:59], v[28:31], v[60:63], v[56:59]
	s_setprio 0
	s_barrier
	s_add_i32 s55, s55, s15
	v_lshl_add_u64 v[172:173], s[8:9], 0, v[140:141]
	s_mov_b64 s[2:3], 0x100
	s_add_i32 s35, s55, 0x2000
	v_lshl_add_u64 v[128:129], v[172:173], 0, s[2:3]
	s_mov_b32 m0, s55
	v_lshl_add_u64 v[196:197], s[8:9], 0, v[158:159]
	s_add_u32 s60, s8, 0x10100
	ds_read_b128 v[60:63], v175 offset:16384
	ds_read_b128 v[100:103], v175 offset:17408
	ds_read_b128 v[104:107], v175 offset:18432
	ds_read_b128 v[108:111], v175 offset:19456
	ds_read_b128 v[112:115], v175 offset:20480
	ds_read_b128 v[116:119], v175 offset:21504
	ds_read_b128 v[120:123], v175 offset:22528
	ds_read_b128 v[124:127], v175 offset:23552
	global_load_lds_dwordx4 v[128:129], off
	v_lshl_add_u64 v[128:129], v[196:197], 0, s[2:3]
	s_mov_b32 m0, s35
	s_addc_u32 s61, s9, 0
	s_add_i32 s38, s38, s15
	global_load_lds_dwordx4 v[128:129], off
	v_lshl_add_u64 v[128:129], s[60:61], 0, v[140:141]
	s_mov_b32 m0, s38
	s_add_i32 s53, s38, 0x2000
	global_load_lds_dwordx4 v[128:129], off
	v_lshl_add_u64 v[128:129], s[60:61], 0, v[158:159]
	s_mov_b32 m0, s53
	v_lshl_add_u64 v[198:199], s[6:7], 0, v[162:163]
	global_load_lds_dwordx4 v[128:129], off
	v_lshl_add_u64 v[128:129], v[198:199], 0, s[2:3]
	s_mov_b32 m0, s26
	v_lshl_add_u64 v[204:205], s[6:7], 0, v[160:161]
	global_load_lds_dwordx4 v[128:129], off
	v_lshl_add_u64 v[128:129], v[204:205], 0, s[2:3]
	s_mov_b32 m0, s27
	s_nop 0
	global_load_lds_dwordx4 v[128:129], off
	s_waitcnt vmcnt(8)
	s_waitcnt lgkmcnt(0)
	s_barrier
	s_setprio 1
	s_waitcnt lgkmcnt(0)
	v_mfma_f32_16x16x32_bf16 v[128:131], v[0:3], v[60:63], 0
	v_mfma_f32_16x16x32_bf16 v[136:139], v[0:3], v[104:107], 0
	v_mfma_f32_16x16x32_bf16 v[146:149], v[0:3], v[112:115], 0
	v_mfma_f32_16x16x32_bf16 v[0:3], v[0:3], v[120:123], 0
	v_mfma_f32_16x16x32_bf16 v[128:131], v[4:7], v[100:103], v[128:131]
	v_mfma_f32_16x16x32_bf16 v[132:135], v[8:11], v[60:63], 0
	v_mfma_f32_16x16x32_bf16 v[136:139], v[4:7], v[108:111], v[136:139]
	v_mfma_f32_16x16x32_bf16 v[146:149], v[4:7], v[116:119], v[146:149]
	v_mfma_f32_16x16x32_bf16 v[0:3], v[4:7], v[124:127], v[0:3]
	v_mfma_f32_16x16x32_bf16 v[4:7], v[8:11], v[120:123], 0
	v_mfma_f32_16x16x32_bf16 v[132:135], v[12:15], v[100:103], v[132:135]
	v_mfma_f32_16x16x32_bf16 v[142:145], v[8:11], v[104:107], 0
	v_mfma_f32_16x16x32_bf16 v[150:153], v[8:11], v[112:115], 0
	v_mfma_f32_16x16x32_bf16 v[4:7], v[12:15], v[124:127], v[4:7]
	v_mfma_f32_16x16x32_bf16 v[142:145], v[12:15], v[108:111], v[142:145]
	v_mfma_f32_16x16x32_bf16 v[150:153], v[12:15], v[116:119], v[150:153]
	v_mfma_f32_16x16x32_bf16 v[8:11], v[16:19], v[60:63], 0
	v_mfma_f32_16x16x32_bf16 v[12:15], v[24:27], v[60:63], 0
	v_mfma_f32_16x16x32_bf16 v[8:11], v[20:23], v[100:103], v[8:11]
	v_mfma_f32_16x16x32_bf16 v[12:15], v[28:31], v[100:103], v[12:15]
	v_mfma_f32_16x16x32_bf16 v[60:63], v[16:19], v[104:107], 0
	v_mfma_f32_16x16x32_bf16 v[100:103], v[24:27], v[104:107], 0
	v_mfma_f32_16x16x32_bf16 v[104:107], v[16:19], v[112:115], 0
	v_mfma_f32_16x16x32_bf16 v[16:19], v[16:19], v[120:123], 0
	v_mfma_f32_16x16x32_bf16 v[60:63], v[20:23], v[108:111], v[60:63]
	v_mfma_f32_16x16x32_bf16 v[100:103], v[28:31], v[108:111], v[100:103]
	v_mfma_f32_16x16x32_bf16 v[104:107], v[20:23], v[116:119], v[104:107]
	v_mfma_f32_16x16x32_bf16 v[108:111], v[24:27], v[112:115], 0
	v_mfma_f32_16x16x32_bf16 v[16:19], v[20:23], v[124:127], v[16:19]
	v_mfma_f32_16x16x32_bf16 v[20:23], v[24:27], v[120:123], 0
	v_mfma_f32_16x16x32_bf16 v[108:111], v[28:31], v[116:119], v[108:111]
	v_mfma_f32_16x16x32_bf16 v[20:23], v[28:31], v[124:127], v[20:23]
	s_setprio 0
	s_barrier
	s_add_i32 s58, 0, 0x18000
	s_add_i32 s76, 0, 0x1c000
	v_add_u32_e32 v222, s58, v174
	v_add_u32_e32 v223, s76, v174
	ds_read_b128 v[24:27], v222
	ds_read_b128 v[28:31], v222 offset:1024
	ds_read_b128 v[112:115], v222 offset:2048
	ds_read_b128 v[116:119], v222 offset:3072
	ds_read_b128 v[120:123], v223
	ds_read_b128 v[124:127], v223 offset:1024
	ds_read_b128 v[154:157], v223 offset:2048
	ds_read_b128 v[164:167], v223 offset:3072
	s_add_u32 s60, s6, 0x40100
	s_addc_u32 s61, s7, 0
	s_mov_b32 m0, s28
	v_lshl_add_u64 v[210:211], s[60:61], 0, v[162:163]
	ds_read_b128 v[168:171], v175 offset:32768
	ds_read_b128 v[176:179], v175 offset:33792
	ds_read_b128 v[180:183], v175 offset:34816
	ds_read_b128 v[184:187], v175 offset:35840
	ds_read_b128 v[188:191], v175 offset:36864
	ds_read_b128 v[192:195], v175 offset:37888
	ds_read_b128 v[200:203], v175 offset:38912
	ds_read_b128 v[206:209], v175 offset:39936
	global_load_lds_dwordx4 v[210:211], off
	v_lshl_add_u64 v[210:211], s[60:61], 0, v[160:161]
	s_mov_b32 m0, s29
	s_nop 0
	global_load_lds_dwordx4 v[210:211], off
	s_waitcnt vmcnt(8)
	s_waitcnt lgkmcnt(0)
	s_barrier
	s_setprio 1
	s_waitcnt lgkmcnt(0)
	v_mfma_f32_16x16x32_bf16 v[64:67], v[24:27], v[168:171], v[64:67]
	v_mfma_f32_16x16x32_bf16 v[68:71], v[112:115], v[168:171], v[68:71]
	v_mfma_f32_16x16x32_bf16 v[72:75], v[24:27], v[180:183], v[72:75]
	v_mfma_f32_16x16x32_bf16 v[76:79], v[112:115], v[180:183], v[76:79]
	v_mfma_f32_16x16x32_bf16 v[80:83], v[24:27], v[188:191], v[80:83]
	v_mfma_f32_16x16x32_bf16 v[84:87], v[112:115], v[188:191], v[84:87]
	v_mfma_f32_16x16x32_bf16 v[88:91], v[24:27], v[200:203], v[88:91]
	v_mfma_f32_16x16x32_bf16 v[92:95], v[112:115], v[200:203], v[92:95]
	v_mfma_f32_16x16x32_bf16 v[64:67], v[28:31], v[176:179], v[64:67]
	v_mfma_f32_16x16x32_bf16 v[68:71], v[116:119], v[176:179], v[68:71]
	v_mfma_f32_16x16x32_bf16 v[72:75], v[28:31], v[184:187], v[72:75]
	v_mfma_f32_16x16x32_bf16 v[76:79], v[116:119], v[184:187], v[76:79]
	v_mfma_f32_16x16x32_bf16 v[80:83], v[28:31], v[192:195], v[80:83]
	v_mfma_f32_16x16x32_bf16 v[84:87], v[116:119], v[192:195], v[84:87]
	v_mfma_f32_16x16x32_bf16 v[88:91], v[28:31], v[206:209], v[88:91]
	v_mfma_f32_16x16x32_bf16 v[92:95], v[116:119], v[206:209], v[92:95]
	v_mfma_f32_16x16x32_bf16 v[96:99], v[120:123], v[168:171], v[96:99]
	v_mfma_f32_16x16x32_bf16 v[32:35], v[154:157], v[168:171], v[32:35]
	v_mfma_f32_16x16x32_bf16 v[36:39], v[120:123], v[180:183], v[36:39]
	v_mfma_f32_16x16x32_bf16 v[40:43], v[154:157], v[180:183], v[40:43]
	v_mfma_f32_16x16x32_bf16 v[44:47], v[120:123], v[188:191], v[44:47]
	v_mfma_f32_16x16x32_bf16 v[48:51], v[154:157], v[188:191], v[48:51]
	v_mfma_f32_16x16x32_bf16 v[52:55], v[120:123], v[200:203], v[52:55]
	v_mfma_f32_16x16x32_bf16 v[56:59], v[154:157], v[200:203], v[56:59]
	v_mfma_f32_16x16x32_bf16 v[96:99], v[124:127], v[176:179], v[96:99]
	v_mfma_f32_16x16x32_bf16 v[32:35], v[164:167], v[176:179], v[32:35]
	v_mfma_f32_16x16x32_bf16 v[36:39], v[124:127], v[184:187], v[36:39]
	v_mfma_f32_16x16x32_bf16 v[40:43], v[164:167], v[184:187], v[40:43]
	v_mfma_f32_16x16x32_bf16 v[44:47], v[124:127], v[192:195], v[44:47]
	v_mfma_f32_16x16x32_bf16 v[48:51], v[164:167], v[192:195], v[48:51]
	v_mfma_f32_16x16x32_bf16 v[52:55], v[124:127], v[206:209], v[52:55]
	v_mfma_f32_16x16x32_bf16 v[56:59], v[164:167], v[206:209], v[56:59]
	s_setprio 0
	s_barrier
	s_add_i32 s60, s58, s15
	s_mov_b64 s[2:3], 0x180
	s_add_i32 s58, s60, 0x2000
	v_lshl_add_u64 v[172:173], v[172:173], 0, s[2:3]
	s_mov_b32 m0, s60
	s_add_u32 s84, s8, 0x10180
	ds_read_b128 v[168:171], v175 offset:49152
	ds_read_b128 v[176:179], v175 offset:50176
	ds_read_b128 v[180:183], v175 offset:51200
	ds_read_b128 v[184:187], v175 offset:52224
	ds_read_b128 v[188:191], v175 offset:53248
	ds_read_b128 v[192:195], v175 offset:54272
	ds_read_b128 v[200:203], v175 offset:55296
	ds_read_b128 v[206:209], v175 offset:56320
	global_load_lds_dwordx4 v[172:173], off
	v_lshl_add_u64 v[172:173], v[196:197], 0, s[2:3]
	s_mov_b32 m0, s58
	s_addc_u32 s85, s9, 0
	s_add_i32 s8, s76, s15
	global_load_lds_dwordx4 v[172:173], off
	v_lshl_add_u64 v[172:173], s[84:85], 0, v[140:141]
	s_mov_b32 m0, s8
	s_add_i32 s9, s8, 0x2000
	global_load_lds_dwordx4 v[172:173], off
	v_lshl_add_u64 v[172:173], s[84:85], 0, v[158:159]
	s_mov_b32 m0, s9
	s_nop 0
	global_load_lds_dwordx4 v[172:173], off
	v_lshl_add_u64 v[172:173], v[198:199], 0, s[2:3]
	s_mov_b32 m0, s74
	s_nop 0
	global_load_lds_dwordx4 v[172:173], off
	v_lshl_add_u64 v[172:173], v[204:205], 0, s[2:3]
	s_mov_b32 m0, s75
	s_nop 0
	global_load_lds_dwordx4 v[172:173], off
	s_waitcnt vmcnt(8)
	s_waitcnt lgkmcnt(0)
	s_barrier
	s_setprio 1
	s_waitcnt lgkmcnt(0)
	v_mfma_f32_16x16x32_bf16 v[132:135], v[112:115], v[168:171], v[132:135]
	v_mfma_f32_16x16x32_bf16 v[136:139], v[24:27], v[180:183], v[136:139]
	v_mfma_f32_16x16x32_bf16 v[0:3], v[24:27], v[200:203], v[0:3]
	v_mfma_f32_16x16x32_bf16 v[4:7], v[112:115], v[200:203], v[4:7]
	v_mfma_f32_16x16x32_bf16 v[128:131], v[24:27], v[168:171], v[128:131]
	v_mfma_f32_16x16x32_bf16 v[132:135], v[116:119], v[176:179], v[132:135]
	v_mfma_f32_16x16x32_bf16 v[136:139], v[28:31], v[184:187], v[136:139]
	v_mfma_f32_16x16x32_bf16 v[142:145], v[112:115], v[180:183], v[142:145]
	v_mfma_f32_16x16x32_bf16 v[146:149], v[24:27], v[188:191], v[146:149]
	v_mfma_f32_16x16x32_bf16 v[150:153], v[112:115], v[188:191], v[150:153]
	v_mfma_f32_16x16x32_bf16 v[0:3], v[28:31], v[206:209], v[0:3]
	v_mfma_f32_16x16x32_bf16 v[4:7], v[116:119], v[206:209], v[4:7]
	v_mfma_f32_16x16x32_bf16 v[128:131], v[28:31], v[176:179], v[128:131]
	v_mfma_f32_16x16x32_bf16 v[142:145], v[116:119], v[184:187], v[142:145]
	v_mfma_f32_16x16x32_bf16 v[146:149], v[28:31], v[192:195], v[146:149]
	v_mfma_f32_16x16x32_bf16 v[150:153], v[116:119], v[192:195], v[150:153]
	v_mfma_f32_16x16x32_bf16 v[8:11], v[120:123], v[168:171], v[8:11]
	v_mfma_f32_16x16x32_bf16 v[12:15], v[154:157], v[168:171], v[12:15]
	v_mfma_f32_16x16x32_bf16 v[24:27], v[120:123], v[180:183], v[60:63]
	v_mfma_f32_16x16x32_bf16 v[28:31], v[154:157], v[180:183], v[100:103]
	v_mfma_f32_16x16x32_bf16 v[60:63], v[120:123], v[188:191], v[104:107]
	v_mfma_f32_16x16x32_bf16 v[100:103], v[154:157], v[188:191], v[108:111]
	v_mfma_f32_16x16x32_bf16 v[16:19], v[120:123], v[200:203], v[16:19]
	v_mfma_f32_16x16x32_bf16 v[20:23], v[154:157], v[200:203], v[20:23]
	v_mfma_f32_16x16x32_bf16 v[8:11], v[124:127], v[176:179], v[8:11]
	v_mfma_f32_16x16x32_bf16 v[12:15], v[164:167], v[176:179], v[12:15]
	v_mfma_f32_16x16x32_bf16 v[24:27], v[124:127], v[184:187], v[24:27]
	v_mfma_f32_16x16x32_bf16 v[28:31], v[164:167], v[184:187], v[28:31]
	v_mfma_f32_16x16x32_bf16 v[60:63], v[124:127], v[192:195], v[60:63]
	v_mfma_f32_16x16x32_bf16 v[100:103], v[164:167], v[192:195], v[100:103]
	v_mfma_f32_16x16x32_bf16 v[16:19], v[124:127], v[206:209], v[16:19]
	v_mfma_f32_16x16x32_bf16 v[20:23], v[164:167], v[206:209], v[20:23]
	s_setprio 0
	s_barrier
	ds_read_b128 v[104:107], v212
	ds_read_b128 v[108:111], v212 offset:1024
	ds_read_b128 v[112:115], v212 offset:2048
	ds_read_b128 v[116:119], v212 offset:3072
	ds_read_b128 v[120:123], v213
	ds_read_b128 v[124:127], v213 offset:1024
	ds_read_b128 v[154:157], v213 offset:2048
	ds_read_b128 v[164:167], v213 offset:3072
	s_add_u32 s6, s6, 0x40180
	s_addc_u32 s7, s7, 0
	s_mov_b32 m0, s59
	v_lshl_add_u64 v[172:173], s[6:7], 0, v[162:163]
	ds_read_b128 v[168:171], v175
	ds_read_b128 v[176:179], v175 offset:1024
	ds_read_b128 v[180:183], v175 offset:2048
	ds_read_b128 v[184:187], v175 offset:3072
	ds_read_b128 v[188:191], v175 offset:4096
	ds_read_b128 v[192:195], v175 offset:5120
	ds_read_b128 v[200:203], v175 offset:6144
	ds_read_b128 v[206:209], v175 offset:7168
	global_load_lds_dwordx4 v[172:173], off
	v_lshl_add_u64 v[172:173], s[6:7], 0, v[160:161]
	s_mov_b32 m0, s24
	s_nop 0
	global_load_lds_dwordx4 v[172:173], off
	s_waitcnt vmcnt(8)
	s_waitcnt lgkmcnt(0)
	s_barrier
	s_setprio 1
	s_waitcnt lgkmcnt(0)
	v_mfma_f32_16x16x32_bf16 v[64:67], v[104:107], v[168:171], v[64:67]
	v_mfma_f32_16x16x32_bf16 v[68:71], v[112:115], v[168:171], v[68:71]
	v_mfma_f32_16x16x32_bf16 v[72:75], v[104:107], v[180:183], v[72:75]
	v_mfma_f32_16x16x32_bf16 v[76:79], v[112:115], v[180:183], v[76:79]
	v_mfma_f32_16x16x32_bf16 v[80:83], v[104:107], v[188:191], v[80:83]
	v_mfma_f32_16x16x32_bf16 v[84:87], v[112:115], v[188:191], v[84:87]
	v_mfma_f32_16x16x32_bf16 v[88:91], v[104:107], v[200:203], v[88:91]
	v_mfma_f32_16x16x32_bf16 v[64:67], v[108:111], v[176:179], v[64:67]
	v_mfma_f32_16x16x32_bf16 v[68:71], v[116:119], v[176:179], v[68:71]
	v_mfma_f32_16x16x32_bf16 v[72:75], v[108:111], v[184:187], v[72:75]
	v_mfma_f32_16x16x32_bf16 v[76:79], v[116:119], v[184:187], v[76:79]
	v_mfma_f32_16x16x32_bf16 v[80:83], v[108:111], v[192:195], v[80:83]
	v_mfma_f32_16x16x32_bf16 v[84:87], v[116:119], v[192:195], v[84:87]
	v_mfma_f32_16x16x32_bf16 v[210:213], v[108:111], v[206:209], v[88:91]
	v_mfma_f32_16x16x32_bf16 v[88:91], v[112:115], v[200:203], v[92:95]
	v_mfma_f32_16x16x32_bf16 v[214:217], v[116:119], v[206:209], v[88:91]
	v_mfma_f32_16x16x32_bf16 v[88:91], v[120:123], v[168:171], v[96:99]
	v_mfma_f32_16x16x32_bf16 v[32:35], v[154:157], v[168:171], v[32:35]
	v_mfma_f32_16x16x32_bf16 v[36:39], v[120:123], v[180:183], v[36:39]
	v_mfma_f32_16x16x32_bf16 v[40:43], v[154:157], v[180:183], v[40:43]
	v_mfma_f32_16x16x32_bf16 v[44:47], v[120:123], v[188:191], v[44:47]
	v_mfma_f32_16x16x32_bf16 v[48:51], v[154:157], v[188:191], v[48:51]
	v_mfma_f32_16x16x32_bf16 v[52:55], v[120:123], v[200:203], v[52:55]
	v_mfma_f32_16x16x32_bf16 v[56:59], v[154:157], v[200:203], v[56:59]
	v_mfma_f32_16x16x32_bf16 v[96:99], v[124:127], v[176:179], v[88:91]
	v_mfma_f32_16x16x32_bf16 v[32:35], v[164:167], v[176:179], v[32:35]
	v_mfma_f32_16x16x32_bf16 v[36:39], v[124:127], v[184:187], v[36:39]
	v_mfma_f32_16x16x32_bf16 v[40:43], v[164:167], v[184:187], v[40:43]
	v_mfma_f32_16x16x32_bf16 v[44:47], v[124:127], v[192:195], v[44:47]
	v_mfma_f32_16x16x32_bf16 v[48:51], v[164:167], v[192:195], v[48:51]
	v_mfma_f32_16x16x32_bf16 v[52:55], v[124:127], v[206:209], v[52:55]
	v_mfma_f32_16x16x32_bf16 v[56:59], v[164:167], v[206:209], v[56:59]
	s_setprio 0
	s_barrier
	s_mov_b32 m0, s55
	v_lshl_add_u64 v[172:173], s[10:11], 0, v[140:141]
	s_add_u32 s6, s10, 0x10000
	ds_read_b128 v[88:91], v175 offset:16384
	ds_read_b128 v[92:95], v175 offset:17408
	ds_read_b128 v[168:171], v175 offset:18432
	ds_read_b128 v[176:179], v175 offset:19456
	ds_read_b128 v[180:183], v175 offset:20480
	ds_read_b128 v[184:187], v175 offset:21504
	ds_read_b128 v[188:191], v175 offset:22528
	ds_read_b128 v[192:195], v175 offset:23552
	global_load_lds_dwordx4 v[172:173], off
	v_lshl_add_u64 v[196:197], s[10:11], 0, v[158:159]
	s_mov_b32 m0, s35
	s_addc_u32 s7, s11, 0
	global_load_lds_dwordx4 v[196:197], off
	v_lshl_add_u64 v[198:199], s[6:7], 0, v[140:141]
	s_mov_b32 m0, s38
	v_lshl_add_u64 v[204:205], s[42:43], 0, v[160:161]
	global_load_lds_dwordx4 v[198:199], off
	v_lshl_add_u64 v[198:199], s[6:7], 0, v[158:159]
	s_mov_b32 m0, s53
	s_nop 0
	global_load_lds_dwordx4 v[198:199], off
	v_lshl_add_u64 v[198:199], s[42:43], 0, v[162:163]
	s_mov_b32 m0, s26
	s_nop 0
	global_load_lds_dwordx4 v[198:199], off
	s_mov_b32 m0, s27
	s_nop 0
	global_load_lds_dwordx4 v[204:205], off
	s_waitcnt vmcnt(8)
	s_waitcnt lgkmcnt(0)
	s_barrier
	s_setprio 1
	s_waitcnt lgkmcnt(0)
	v_mfma_f32_16x16x32_bf16 v[132:135], v[112:115], v[88:91], v[132:135]
	v_mfma_f32_16x16x32_bf16 v[200:203], v[116:119], v[92:95], v[132:135]
	v_mfma_f32_16x16x32_bf16 v[132:135], v[104:107], v[168:171], v[136:139]
	v_mfma_f32_16x16x32_bf16 v[206:209], v[108:111], v[176:179], v[132:135]
	v_mfma_f32_16x16x32_bf16 v[132:135], v[112:115], v[168:171], v[142:145]
	v_mfma_f32_16x16x32_bf16 v[142:145], v[116:119], v[176:179], v[132:135]
	v_mfma_f32_16x16x32_bf16 v[132:135], v[104:107], v[180:183], v[146:149]
	v_mfma_f32_16x16x32_bf16 v[0:3], v[104:107], v[188:191], v[0:3]
	v_mfma_f32_16x16x32_bf16 v[4:7], v[112:115], v[188:191], v[4:7]
	v_mfma_f32_16x16x32_bf16 v[128:131], v[104:107], v[88:91], v[128:131]
	v_mfma_f32_16x16x32_bf16 v[146:149], v[108:111], v[184:187], v[132:135]
	v_mfma_f32_16x16x32_bf16 v[132:135], v[112:115], v[180:183], v[150:153]
	v_mfma_f32_16x16x32_bf16 v[0:3], v[108:111], v[192:195], v[0:3]
	v_mfma_f32_16x16x32_bf16 v[4:7], v[116:119], v[192:195], v[4:7]
	v_mfma_f32_16x16x32_bf16 v[128:131], v[108:111], v[92:95], v[128:131]
	v_mfma_f32_16x16x32_bf16 v[150:153], v[116:119], v[184:187], v[132:135]
	v_mfma_f32_16x16x32_bf16 v[8:11], v[120:123], v[88:91], v[8:11]
	v_mfma_f32_16x16x32_bf16 v[112:115], v[124:127], v[92:95], v[8:11]
	v_mfma_f32_16x16x32_bf16 v[8:11], v[154:157], v[88:91], v[12:15]
	v_mfma_f32_16x16x32_bf16 v[116:119], v[164:167], v[92:95], v[8:11]
	v_mfma_f32_16x16x32_bf16 v[8:11], v[120:123], v[168:171], v[24:27]
	v_mfma_f32_16x16x32_bf16 v[218:221], v[124:127], v[176:179], v[8:11]
	v_mfma_f32_16x16x32_bf16 v[8:11], v[154:157], v[168:171], v[28:31]
	v_mfma_f32_16x16x32_bf16 v[168:171], v[164:167], v[176:179], v[8:11]
	v_mfma_f32_16x16x32_bf16 v[8:11], v[120:123], v[180:183], v[60:63]
	v_mfma_f32_16x16x32_bf16 v[176:179], v[124:127], v[184:187], v[8:11]
	v_mfma_f32_16x16x32_bf16 v[8:11], v[154:157], v[180:183], v[100:103]
	v_mfma_f32_16x16x32_bf16 v[180:183], v[164:167], v[184:187], v[8:11]
	v_mfma_f32_16x16x32_bf16 v[8:11], v[120:123], v[188:191], v[16:19]
	v_mfma_f32_16x16x32_bf16 v[184:187], v[124:127], v[192:195], v[8:11]
	v_mfma_f32_16x16x32_bf16 v[8:11], v[154:157], v[188:191], v[20:23]
	v_mfma_f32_16x16x32_bf16 v[154:157], v[164:167], v[192:195], v[8:11]
	s_setprio 0
	s_barrier
	s_nop 4
	ds_read_b128 v[8:11], v222
	ds_read_b128 v[12:15], v222 offset:1024
	ds_read_b128 v[16:19], v222 offset:2048
	ds_read_b128 v[20:23], v222 offset:3072
	ds_read_b128 v[164:167], v223
	ds_read_b128 v[188:191], v223 offset:1024
	ds_read_b128 v[192:195], v223 offset:2048
	ds_read_b128 v[222:225], v223 offset:3072
	s_add_u32 s6, s42, 0x40000
	s_addc_u32 s7, s43, 0
	s_mov_b32 m0, s28
	v_lshl_add_u64 v[88:89], s[6:7], 0, v[162:163]
	ds_read_b128 v[24:27], v175 offset:32768
	ds_read_b128 v[28:31], v175 offset:33792
	ds_read_b128 v[60:63], v175 offset:34816
	ds_read_b128 v[226:229], v175 offset:35840
	ds_read_b128 v[230:233], v175 offset:36864
	ds_read_b128 v[234:237], v175 offset:37888
	ds_read_b128 v[238:241], v175 offset:38912
	ds_read_b128 v[242:245], v175 offset:39936
	global_load_lds_dwordx4 v[88:89], off
	v_lshl_add_u64 v[88:89], s[6:7], 0, v[160:161]
	s_mov_b32 m0, s29
	s_nop 0
	global_load_lds_dwordx4 v[88:89], off
	s_waitcnt vmcnt(8)
	s_waitcnt lgkmcnt(0)
	s_barrier
	s_setprio 1
	s_waitcnt lgkmcnt(0)
	v_mfma_f32_16x16x32_bf16 v[64:67], v[8:11], v[24:27], v[64:67]
	v_mfma_f32_16x16x32_bf16 v[132:135], v[12:15], v[28:31], v[64:67]
	v_mfma_f32_16x16x32_bf16 v[64:67], v[16:19], v[24:27], v[68:71]
	v_mfma_f32_16x16x32_bf16 v[136:139], v[20:23], v[28:31], v[64:67]
	v_mfma_f32_16x16x32_bf16 v[64:67], v[8:11], v[60:63], v[72:75]
	v_mfma_f32_16x16x32_bf16 v[108:111], v[12:15], v[226:229], v[64:67]
	v_mfma_f32_16x16x32_bf16 v[64:67], v[16:19], v[60:63], v[76:79]
	v_mfma_f32_16x16x32_bf16 v[104:107], v[20:23], v[226:229], v[64:67]
	v_mfma_f32_16x16x32_bf16 v[64:67], v[8:11], v[230:233], v[80:83]
	v_mfma_f32_16x16x32_bf16 v[88:91], v[12:15], v[234:237], v[64:67]
	v_mfma_f32_16x16x32_bf16 v[64:67], v[16:19], v[230:233], v[84:87]
	v_mfma_f32_16x16x32_bf16 v[92:95], v[20:23], v[234:237], v[64:67]
	v_mfma_f32_16x16x32_bf16 v[64:67], v[8:11], v[238:241], v[210:213]
	v_mfma_f32_16x16x32_bf16 v[76:79], v[12:15], v[242:245], v[64:67]
	v_mfma_f32_16x16x32_bf16 v[64:67], v[16:19], v[238:241], v[214:217]
	v_mfma_f32_16x16x32_bf16 v[72:75], v[20:23], v[242:245], v[64:67]
	v_mfma_f32_16x16x32_bf16 v[64:67], v[164:167], v[24:27], v[96:99]
	v_mfma_f32_16x16x32_bf16 v[24:27], v[192:195], v[24:27], v[32:35]
	v_mfma_f32_16x16x32_bf16 v[120:123], v[222:225], v[28:31], v[24:27]
	v_mfma_f32_16x16x32_bf16 v[24:27], v[164:167], v[60:63], v[36:39]
	v_mfma_f32_16x16x32_bf16 v[100:103], v[188:191], v[226:229], v[24:27]
	v_mfma_f32_16x16x32_bf16 v[24:27], v[192:195], v[60:63], v[40:43]
	v_mfma_f32_16x16x32_bf16 v[96:99], v[222:225], v[226:229], v[24:27]
	v_mfma_f32_16x16x32_bf16 v[24:27], v[164:167], v[230:233], v[44:47]
	v_mfma_f32_16x16x32_bf16 v[84:87], v[188:191], v[234:237], v[24:27]
	v_mfma_f32_16x16x32_bf16 v[24:27], v[192:195], v[230:233], v[48:51]
	v_mfma_f32_16x16x32_bf16 v[80:83], v[222:225], v[234:237], v[24:27]
	v_mfma_f32_16x16x32_bf16 v[24:27], v[164:167], v[238:241], v[52:55]
	v_mfma_f32_16x16x32_bf16 v[68:71], v[188:191], v[242:245], v[24:27]
	v_mfma_f32_16x16x32_bf16 v[24:27], v[192:195], v[238:241], v[56:59]
	v_mfma_f32_16x16x32_bf16 v[124:127], v[188:191], v[28:31], v[64:67]
	v_mfma_f32_16x16x32_bf16 v[64:67], v[222:225], v[242:245], v[24:27]
	s_setprio 0
	s_barrier
	s_mov_b32 m0, s60
	s_nop 2
	v_lshl_add_u64 v[24:25], v[172:173], 0, s[36:37]
	s_add_u32 s6, s10, 0x10080
	ds_read_b128 v[32:35], v175 offset:49152
	ds_read_b128 v[36:39], v175 offset:50176
	ds_read_b128 v[210:213], v175 offset:51200
	ds_read_b128 v[214:217], v175 offset:52224
	ds_read_b128 v[226:229], v175 offset:53248
	ds_read_b128 v[230:233], v175 offset:54272
	ds_read_b128 v[234:237], v175 offset:55296
	ds_read_b128 v[238:241], v175 offset:56320
	global_load_lds_dwordx4 v[24:25], off
	v_lshl_add_u64 v[24:25], v[196:197], 0, s[36:37]
	s_mov_b32 m0, s58
	s_addc_u32 s7, s11, 0
	global_load_lds_dwordx4 v[24:25], off
	v_lshl_add_u64 v[24:25], s[6:7], 0, v[140:141]
	s_mov_b32 m0, s8
	s_nop 0
	global_load_lds_dwordx4 v[24:25], off
	v_lshl_add_u64 v[24:25], s[6:7], 0, v[158:159]
	s_mov_b32 m0, s9
	s_nop 0
	global_load_lds_dwordx4 v[24:25], off
	v_lshl_add_u64 v[24:25], v[198:199], 0, s[36:37]
	s_mov_b32 m0, s74
	s_nop 0
	global_load_lds_dwordx4 v[24:25], off
	v_lshl_add_u64 v[24:25], v[204:205], 0, s[36:37]
	s_mov_b32 m0, s75
	s_nop 0
	global_load_lds_dwordx4 v[24:25], off
	s_waitcnt vmcnt(8)
	s_waitcnt lgkmcnt(0)
	s_barrier
	s_setprio 1
	s_waitcnt lgkmcnt(0)
	v_mfma_f32_16x16x32_bf16 v[24:27], v[8:11], v[32:35], v[128:131]
	v_mfma_f32_16x16x32_bf16 v[56:59], v[12:15], v[36:39], v[24:27]
	v_mfma_f32_16x16x32_bf16 v[24:27], v[16:19], v[32:35], v[200:203]
	v_mfma_f32_16x16x32_bf16 v[60:63], v[20:23], v[36:39], v[24:27]
	v_mfma_f32_16x16x32_bf16 v[24:27], v[8:11], v[210:213], v[206:209]
	v_mfma_f32_16x16x32_bf16 v[44:47], v[12:15], v[214:217], v[24:27]
	v_mfma_f32_16x16x32_bf16 v[24:27], v[16:19], v[210:213], v[142:145]
	v_mfma_f32_16x16x32_bf16 v[40:43], v[20:23], v[214:217], v[24:27]
	v_mfma_f32_16x16x32_bf16 v[24:27], v[8:11], v[226:229], v[146:149]
	v_mfma_f32_16x16x32_bf16 v[0:3], v[8:11], v[234:237], v[0:3]
	v_mfma_f32_16x16x32_bf16 v[24:27], v[12:15], v[230:233], v[24:27]
	v_mfma_f32_16x16x32_bf16 v[28:31], v[16:19], v[226:229], v[150:153]
	v_mfma_f32_16x16x32_bf16 v[12:15], v[12:15], v[238:241], v[0:3]
	v_mfma_f32_16x16x32_bf16 v[0:3], v[16:19], v[234:237], v[4:7]
	v_mfma_f32_16x16x32_bf16 v[28:31], v[20:23], v[230:233], v[28:31]
	v_mfma_f32_16x16x32_bf16 v[8:11], v[20:23], v[238:241], v[0:3]
	v_mfma_f32_16x16x32_bf16 v[0:3], v[164:167], v[32:35], v[112:115]
	v_mfma_f32_16x16x32_bf16 v[52:55], v[188:191], v[36:39], v[0:3]
	v_mfma_f32_16x16x32_bf16 v[0:3], v[192:195], v[32:35], v[116:119]
	v_mfma_f32_16x16x32_bf16 v[48:51], v[222:225], v[36:39], v[0:3]
	v_mfma_f32_16x16x32_bf16 v[0:3], v[164:167], v[210:213], v[218:221]
	v_mfma_f32_16x16x32_bf16 v[36:39], v[188:191], v[214:217], v[0:3]
	v_mfma_f32_16x16x32_bf16 v[0:3], v[192:195], v[210:213], v[168:171]
	v_mfma_f32_16x16x32_bf16 v[32:35], v[222:225], v[214:217], v[0:3]
	v_mfma_f32_16x16x32_bf16 v[0:3], v[164:167], v[226:229], v[176:179]
	v_mfma_f32_16x16x32_bf16 v[20:23], v[188:191], v[230:233], v[0:3]
	v_mfma_f32_16x16x32_bf16 v[0:3], v[192:195], v[226:229], v[180:183]
	v_mfma_f32_16x16x32_bf16 v[16:19], v[222:225], v[230:233], v[0:3]
	v_mfma_f32_16x16x32_bf16 v[0:3], v[164:167], v[234:237], v[184:187]
	v_mfma_f32_16x16x32_bf16 v[4:7], v[188:191], v[238:241], v[0:3]
	v_mfma_f32_16x16x32_bf16 v[0:3], v[192:195], v[234:237], v[154:157]
	v_mfma_f32_16x16x32_bf16 v[0:3], v[222:225], v[238:241], v[0:3]
	s_setprio 0
	s_barrier
	s_andn2_b64 vcc, exec, s[48:49]
	s_cbranch_vccnz .LBB0_419
	s_barrier

.LBB0_457:
	s_lshl_b64 s[10:11], s[52:53], 17
	s_add_u32 s56, s12, s10
	s_addc_u32 s57, s13, s11
	s_and_b64 s[10:11], s[40:41], exec
	s_cselect_b32 s11, s57, s9
	s_cselect_b32 s10, s56, s8
	s_add_i32 s55, 0, 0x10000
	s_add_i32 s38, 0, 0x14000
	v_add_u32_e32 v212, s55, v138
	v_add_u32_e32 v213, s38, v138
	ds_read_b128 v[0:3], v212
	ds_read_b128 v[4:7], v212 offset:1024
	ds_read_b128 v[8:11], v212 offset:2048
	ds_read_b128 v[12:15], v212 offset:3072
	ds_read_b128 v[16:19], v213
	ds_read_b128 v[20:23], v213 offset:1024
	ds_read_b128 v[24:27], v213 offset:2048
	ds_read_b128 v[28:31], v213 offset:3072
	s_add_u32 s74, s6, 0x40080
	s_addc_u32 s75, s7, 0
	s_add_i32 s61, s26, 0xc000
	v_lshl_add_u64 v[64:65], s[74:75], 0, v[132:133]
	s_mov_b32 m0, s61
	s_add_i32 s24, s26, 0xe000
	ds_read_b128 v[32:35], v139
	ds_read_b128 v[36:39], v139 offset:1024
	ds_read_b128 v[40:43], v139 offset:2048
	ds_read_b128 v[44:47], v139 offset:3072
	ds_read_b128 v[48:51], v139 offset:4096
	ds_read_b128 v[52:55], v139 offset:5120
	ds_read_b128 v[56:59], v139 offset:6144
	ds_read_b128 v[60:63], v139 offset:7168
	global_load_lds_dwordx4 v[64:65], off
	v_lshl_add_u64 v[64:65], s[74:75], 0, v[130:131]
	s_mov_b32 m0, s24
	s_nop 0
	global_load_lds_dwordx4 v[64:65], off
	s_waitcnt vmcnt(8)
	s_waitcnt lgkmcnt(0)
	s_barrier
	s_setprio 1
	s_waitcnt lgkmcnt(0)
	v_mfma_f32_16x16x32_bf16 v[64:67], v[0:3], v[32:35], 0
	v_mfma_f32_16x16x32_bf16 v[68:71], v[8:11], v[32:35], 0
	v_mfma_f32_16x16x32_bf16 v[72:75], v[0:3], v[40:43], 0
	v_mfma_f32_16x16x32_bf16 v[76:79], v[8:11], v[40:43], 0
	v_mfma_f32_16x16x32_bf16 v[80:83], v[0:3], v[48:51], 0
	v_mfma_f32_16x16x32_bf16 v[84:87], v[8:11], v[48:51], 0
	v_mfma_f32_16x16x32_bf16 v[88:91], v[0:3], v[56:59], 0
	v_mfma_f32_16x16x32_bf16 v[92:95], v[8:11], v[56:59], 0
	v_mfma_f32_16x16x32_bf16 v[64:67], v[4:7], v[36:39], v[64:67]
	v_mfma_f32_16x16x32_bf16 v[68:71], v[12:15], v[36:39], v[68:71]
	v_mfma_f32_16x16x32_bf16 v[72:75], v[4:7], v[44:47], v[72:75]
	v_mfma_f32_16x16x32_bf16 v[76:79], v[12:15], v[44:47], v[76:79]
	v_mfma_f32_16x16x32_bf16 v[80:83], v[4:7], v[52:55], v[80:83]
	v_mfma_f32_16x16x32_bf16 v[84:87], v[12:15], v[52:55], v[84:87]
	v_mfma_f32_16x16x32_bf16 v[88:91], v[4:7], v[60:63], v[88:91]
	v_mfma_f32_16x16x32_bf16 v[92:95], v[12:15], v[60:63], v[92:95]
	v_mfma_f32_16x16x32_bf16 v[96:99], v[16:19], v[32:35], 0
	v_mfma_f32_16x16x32_bf16 v[32:35], v[24:27], v[32:35], 0
	v_mfma_f32_16x16x32_bf16 v[96:99], v[20:23], v[36:39], v[96:99]
	v_mfma_f32_16x16x32_bf16 v[32:35], v[28:31], v[36:39], v[32:35]
	v_mfma_f32_16x16x32_bf16 v[36:39], v[16:19], v[40:43], 0
	v_mfma_f32_16x16x32_bf16 v[40:43], v[24:27], v[40:43], 0
	v_mfma_f32_16x16x32_bf16 v[36:39], v[20:23], v[44:47], v[36:39]
	v_mfma_f32_16x16x32_bf16 v[40:43], v[28:31], v[44:47], v[40:43]
	v_mfma_f32_16x16x32_bf16 v[44:47], v[16:19], v[48:51], 0
	v_mfma_f32_16x16x32_bf16 v[48:51], v[24:27], v[48:51], 0
	v_mfma_f32_16x16x32_bf16 v[44:47], v[20:23], v[52:55], v[44:47]
	v_mfma_f32_16x16x32_bf16 v[48:51], v[28:31], v[52:55], v[48:51]
	v_mfma_f32_16x16x32_bf16 v[52:55], v[16:19], v[56:59], 0
	v_mfma_f32_16x16x32_bf16 v[56:59], v[24:27], v[56:59], 0
	v_mfma_f32_16x16x32_bf16 v[52:55], v[20:23], v[60:63], v[52:55]
	v_mfma_f32_16x16x32_bf16 v[56:59], v[28:31], v[60:63], v[56:59]
	s_setprio 0
	s_barrier
	s_add_i32 s55, s55, s15
	v_lshl_add_u64 v[198:199], s[8:9], 0, v[140:141]
	s_mov_b64 s[2:3], 0x100
	s_add_i32 s35, s55, 0x2000
	v_lshl_add_u64 v[134:135], v[198:199], 0, s[2:3]
	s_mov_b32 m0, s55
	v_lshl_add_u64 v[204:205], s[8:9], 0, v[128:129]
	s_add_u32 s74, s8, 0x10100
	ds_read_b128 v[60:63], v139 offset:16384
	ds_read_b128 v[100:103], v139 offset:17408
	ds_read_b128 v[104:107], v139 offset:18432
	ds_read_b128 v[108:111], v139 offset:19456
	ds_read_b128 v[112:115], v139 offset:20480
	ds_read_b128 v[116:119], v139 offset:21504
	ds_read_b128 v[120:123], v139 offset:22528
	ds_read_b128 v[124:127], v139 offset:23552
	global_load_lds_dwordx4 v[134:135], off
	v_lshl_add_u64 v[134:135], v[204:205], 0, s[2:3]
	s_mov_b32 m0, s35
	s_addc_u32 s75, s9, 0
	s_add_i32 s38, s38, s15
	global_load_lds_dwordx4 v[134:135], off
	v_lshl_add_u64 v[134:135], s[74:75], 0, v[140:141]
	s_mov_b32 m0, s38
	s_add_i32 s53, s38, 0x2000
	global_load_lds_dwordx4 v[134:135], off
	v_lshl_add_u64 v[134:135], s[74:75], 0, v[128:129]
	s_mov_b32 m0, s53
	v_lshl_add_u64 v[206:207], s[6:7], 0, v[132:133]
	global_load_lds_dwordx4 v[134:135], off
	v_lshl_add_u64 v[134:135], v[206:207], 0, s[2:3]
	s_mov_b32 m0, s26
	v_lshl_add_u64 v[208:209], s[6:7], 0, v[130:131]
	global_load_lds_dwordx4 v[134:135], off
	v_lshl_add_u64 v[134:135], v[208:209], 0, s[2:3]
	s_mov_b32 m0, s27
	s_nop 0
	global_load_lds_dwordx4 v[134:135], off
	s_waitcnt vmcnt(8)
	s_waitcnt lgkmcnt(0)
	s_barrier
	s_setprio 1
	s_waitcnt lgkmcnt(0)
	v_mfma_f32_16x16x32_bf16 v[134:137], v[0:3], v[60:63], 0
	v_mfma_f32_16x16x32_bf16 v[146:149], v[0:3], v[104:107], 0
	v_mfma_f32_16x16x32_bf16 v[154:157], v[0:3], v[112:115], 0
	v_mfma_f32_16x16x32_bf16 v[0:3], v[0:3], v[120:123], 0
	v_mfma_f32_16x16x32_bf16 v[134:137], v[4:7], v[100:103], v[134:137]
	v_mfma_f32_16x16x32_bf16 v[146:149], v[4:7], v[108:111], v[146:149]
	v_mfma_f32_16x16x32_bf16 v[154:157], v[4:7], v[116:119], v[154:157]
	v_mfma_f32_16x16x32_bf16 v[0:3], v[4:7], v[124:127], v[0:3]
	v_mfma_f32_16x16x32_bf16 v[4:7], v[8:11], v[120:123], 0
	v_mfma_f32_16x16x32_bf16 v[142:145], v[8:11], v[60:63], 0
	v_mfma_f32_16x16x32_bf16 v[150:153], v[8:11], v[104:107], 0
	v_mfma_f32_16x16x32_bf16 v[158:161], v[8:11], v[112:115], 0
	v_mfma_f32_16x16x32_bf16 v[4:7], v[12:15], v[124:127], v[4:7]
	v_mfma_f32_16x16x32_bf16 v[142:145], v[12:15], v[100:103], v[142:145]
	v_mfma_f32_16x16x32_bf16 v[150:153], v[12:15], v[108:111], v[150:153]
	v_mfma_f32_16x16x32_bf16 v[158:161], v[12:15], v[116:119], v[158:161]
	v_mfma_f32_16x16x32_bf16 v[8:11], v[16:19], v[60:63], 0
	v_mfma_f32_16x16x32_bf16 v[12:15], v[24:27], v[60:63], 0
	v_mfma_f32_16x16x32_bf16 v[8:11], v[20:23], v[100:103], v[8:11]
	v_mfma_f32_16x16x32_bf16 v[12:15], v[28:31], v[100:103], v[12:15]
	v_mfma_f32_16x16x32_bf16 v[60:63], v[16:19], v[104:107], 0
	v_mfma_f32_16x16x32_bf16 v[100:103], v[24:27], v[104:107], 0
	v_mfma_f32_16x16x32_bf16 v[104:107], v[16:19], v[112:115], 0
	v_mfma_f32_16x16x32_bf16 v[16:19], v[16:19], v[120:123], 0
	v_mfma_f32_16x16x32_bf16 v[60:63], v[20:23], v[108:111], v[60:63]
	v_mfma_f32_16x16x32_bf16 v[100:103], v[28:31], v[108:111], v[100:103]
	v_mfma_f32_16x16x32_bf16 v[104:107], v[20:23], v[116:119], v[104:107]
	v_mfma_f32_16x16x32_bf16 v[108:111], v[24:27], v[112:115], 0
	v_mfma_f32_16x16x32_bf16 v[16:19], v[20:23], v[124:127], v[16:19]
	v_mfma_f32_16x16x32_bf16 v[20:23], v[24:27], v[120:123], 0
	v_mfma_f32_16x16x32_bf16 v[108:111], v[28:31], v[116:119], v[108:111]
	v_mfma_f32_16x16x32_bf16 v[20:23], v[28:31], v[124:127], v[20:23]
	s_setprio 0
	s_barrier
	s_add_i32 s60, 0, 0x18000
	s_add_i32 s76, 0, 0x1c000
	v_add_u32_e32 v218, s60, v138
	v_add_u32_e32 v219, s76, v138
	ds_read_b128 v[24:27], v218
	ds_read_b128 v[28:31], v218 offset:1024
	ds_read_b128 v[112:115], v218 offset:2048
	ds_read_b128 v[116:119], v218 offset:3072
	ds_read_b128 v[120:123], v219
	ds_read_b128 v[124:127], v219 offset:1024
	ds_read_b128 v[162:165], v219 offset:2048
	ds_read_b128 v[166:169], v219 offset:3072
	s_add_u32 s74, s6, 0x40100
	s_addc_u32 s75, s7, 0
	s_mov_b32 m0, s28
	v_lshl_add_u64 v[210:211], s[74:75], 0, v[132:133]
	ds_read_b128 v[170:173], v139 offset:32768
	ds_read_b128 v[174:177], v139 offset:33792
	ds_read_b128 v[178:181], v139 offset:34816
	ds_read_b128 v[182:185], v139 offset:35840
	ds_read_b128 v[186:189], v139 offset:36864
	ds_read_b128 v[190:193], v139 offset:37888
	ds_read_b128 v[194:197], v139 offset:38912
	ds_read_b128 v[200:203], v139 offset:39936
	global_load_lds_dwordx4 v[210:211], off
	v_lshl_add_u64 v[210:211], s[74:75], 0, v[130:131]
	s_mov_b32 m0, s29
	s_nop 0
	global_load_lds_dwordx4 v[210:211], off
	s_waitcnt vmcnt(8)
	s_waitcnt lgkmcnt(0)
	s_barrier
	s_setprio 1
	s_waitcnt lgkmcnt(0)
	v_mfma_f32_16x16x32_bf16 v[64:67], v[24:27], v[170:173], v[64:67]
	v_mfma_f32_16x16x32_bf16 v[68:71], v[112:115], v[170:173], v[68:71]
	v_mfma_f32_16x16x32_bf16 v[72:75], v[24:27], v[178:181], v[72:75]
	v_mfma_f32_16x16x32_bf16 v[76:79], v[112:115], v[178:181], v[76:79]
	v_mfma_f32_16x16x32_bf16 v[80:83], v[24:27], v[186:189], v[80:83]
	v_mfma_f32_16x16x32_bf16 v[84:87], v[112:115], v[186:189], v[84:87]
	v_mfma_f32_16x16x32_bf16 v[88:91], v[24:27], v[194:197], v[88:91]
	v_mfma_f32_16x16x32_bf16 v[92:95], v[112:115], v[194:197], v[92:95]
	v_mfma_f32_16x16x32_bf16 v[64:67], v[28:31], v[174:177], v[64:67]
	v_mfma_f32_16x16x32_bf16 v[68:71], v[116:119], v[174:177], v[68:71]
	v_mfma_f32_16x16x32_bf16 v[72:75], v[28:31], v[182:185], v[72:75]
	v_mfma_f32_16x16x32_bf16 v[76:79], v[116:119], v[182:185], v[76:79]
	v_mfma_f32_16x16x32_bf16 v[80:83], v[28:31], v[190:193], v[80:83]
	v_mfma_f32_16x16x32_bf16 v[84:87], v[116:119], v[190:193], v[84:87]
	v_mfma_f32_16x16x32_bf16 v[88:91], v[28:31], v[200:203], v[88:91]
	v_mfma_f32_16x16x32_bf16 v[92:95], v[116:119], v[200:203], v[92:95]
	v_mfma_f32_16x16x32_bf16 v[96:99], v[120:123], v[170:173], v[96:99]
	v_mfma_f32_16x16x32_bf16 v[32:35], v[162:165], v[170:173], v[32:35]
	v_mfma_f32_16x16x32_bf16 v[36:39], v[120:123], v[178:181], v[36:39]
	v_mfma_f32_16x16x32_bf16 v[40:43], v[162:165], v[178:181], v[40:43]
	v_mfma_f32_16x16x32_bf16 v[44:47], v[120:123], v[186:189], v[44:47]
	v_mfma_f32_16x16x32_bf16 v[48:51], v[162:165], v[186:189], v[48:51]
	v_mfma_f32_16x16x32_bf16 v[52:55], v[120:123], v[194:197], v[52:55]
	v_mfma_f32_16x16x32_bf16 v[56:59], v[162:165], v[194:197], v[56:59]
	v_mfma_f32_16x16x32_bf16 v[96:99], v[124:127], v[174:177], v[96:99]
	v_mfma_f32_16x16x32_bf16 v[32:35], v[166:169], v[174:177], v[32:35]
	v_mfma_f32_16x16x32_bf16 v[36:39], v[124:127], v[182:185], v[36:39]
	v_mfma_f32_16x16x32_bf16 v[40:43], v[166:169], v[182:185], v[40:43]
	v_mfma_f32_16x16x32_bf16 v[44:47], v[124:127], v[190:193], v[44:47]
	v_mfma_f32_16x16x32_bf16 v[48:51], v[166:169], v[190:193], v[48:51]
	v_mfma_f32_16x16x32_bf16 v[52:55], v[124:127], v[200:203], v[52:55]
	v_mfma_f32_16x16x32_bf16 v[56:59], v[166:169], v[200:203], v[56:59]
	s_setprio 0
	s_barrier
	s_add_i32 s74, s60, s15
	s_mov_b64 s[2:3], 0x180
	s_add_i32 s60, s74, 0x2000
	v_lshl_add_u64 v[198:199], v[198:199], 0, s[2:3]
	s_mov_b32 m0, s74
	s_add_u32 s84, s8, 0x10180
	ds_read_b128 v[170:173], v139 offset:49152
	ds_read_b128 v[174:177], v139 offset:50176
	ds_read_b128 v[178:181], v139 offset:51200
	ds_read_b128 v[182:185], v139 offset:52224
	ds_read_b128 v[186:189], v139 offset:53248
	ds_read_b128 v[190:193], v139 offset:54272
	ds_read_b128 v[194:197], v139 offset:55296
	ds_read_b128 v[200:203], v139 offset:56320
	global_load_lds_dwordx4 v[198:199], off
	v_lshl_add_u64 v[198:199], v[204:205], 0, s[2:3]
	s_mov_b32 m0, s60
	s_addc_u32 s85, s9, 0
	s_add_i32 s8, s76, s15
	global_load_lds_dwordx4 v[198:199], off
	v_lshl_add_u64 v[198:199], s[84:85], 0, v[140:141]
	s_mov_b32 m0, s8
	s_add_i32 s9, s8, 0x2000
	global_load_lds_dwordx4 v[198:199], off
	v_lshl_add_u64 v[198:199], s[84:85], 0, v[128:129]
	s_mov_b32 m0, s9
	s_nop 0
	global_load_lds_dwordx4 v[198:199], off
	v_lshl_add_u64 v[198:199], v[206:207], 0, s[2:3]
	s_mov_b32 m0, s58
	s_nop 0
	global_load_lds_dwordx4 v[198:199], off
	v_lshl_add_u64 v[198:199], v[208:209], 0, s[2:3]
	s_mov_b32 m0, s59
	s_nop 0
	global_load_lds_dwordx4 v[198:199], off
	s_waitcnt vmcnt(8)
	s_waitcnt lgkmcnt(0)
	s_barrier
	s_setprio 1
	s_waitcnt lgkmcnt(0)
	v_mfma_f32_16x16x32_bf16 v[0:3], v[24:27], v[194:197], v[0:3]
	v_mfma_f32_16x16x32_bf16 v[4:7], v[112:115], v[194:197], v[4:7]
	v_mfma_f32_16x16x32_bf16 v[134:137], v[24:27], v[170:173], v[134:137]
	v_mfma_f32_16x16x32_bf16 v[142:145], v[112:115], v[170:173], v[142:145]
	v_mfma_f32_16x16x32_bf16 v[146:149], v[24:27], v[178:181], v[146:149]
	v_mfma_f32_16x16x32_bf16 v[150:153], v[112:115], v[178:181], v[150:153]
	v_mfma_f32_16x16x32_bf16 v[154:157], v[24:27], v[186:189], v[154:157]
	v_mfma_f32_16x16x32_bf16 v[158:161], v[112:115], v[186:189], v[158:161]
	v_mfma_f32_16x16x32_bf16 v[0:3], v[28:31], v[200:203], v[0:3]
	v_mfma_f32_16x16x32_bf16 v[4:7], v[116:119], v[200:203], v[4:7]
	v_mfma_f32_16x16x32_bf16 v[134:137], v[28:31], v[174:177], v[134:137]
	v_mfma_f32_16x16x32_bf16 v[142:145], v[116:119], v[174:177], v[142:145]
	v_mfma_f32_16x16x32_bf16 v[146:149], v[28:31], v[182:185], v[146:149]
	v_mfma_f32_16x16x32_bf16 v[150:153], v[116:119], v[182:185], v[150:153]
	v_mfma_f32_16x16x32_bf16 v[154:157], v[28:31], v[190:193], v[154:157]
	v_mfma_f32_16x16x32_bf16 v[158:161], v[116:119], v[190:193], v[158:161]
	v_mfma_f32_16x16x32_bf16 v[8:11], v[120:123], v[170:173], v[8:11]
	v_mfma_f32_16x16x32_bf16 v[12:15], v[162:165], v[170:173], v[12:15]
	v_mfma_f32_16x16x32_bf16 v[24:27], v[120:123], v[178:181], v[60:63]
	v_mfma_f32_16x16x32_bf16 v[28:31], v[162:165], v[178:181], v[100:103]
	v_mfma_f32_16x16x32_bf16 v[60:63], v[120:123], v[186:189], v[104:107]
	v_mfma_f32_16x16x32_bf16 v[100:103], v[162:165], v[186:189], v[108:111]
	v_mfma_f32_16x16x32_bf16 v[16:19], v[120:123], v[194:197], v[16:19]
	v_mfma_f32_16x16x32_bf16 v[20:23], v[162:165], v[194:197], v[20:23]
	v_mfma_f32_16x16x32_bf16 v[8:11], v[124:127], v[174:177], v[8:11]
	v_mfma_f32_16x16x32_bf16 v[12:15], v[166:169], v[174:177], v[12:15]
	v_mfma_f32_16x16x32_bf16 v[24:27], v[124:127], v[182:185], v[24:27]
	v_mfma_f32_16x16x32_bf16 v[28:31], v[166:169], v[182:185], v[28:31]
	v_mfma_f32_16x16x32_bf16 v[60:63], v[124:127], v[190:193], v[60:63]
	v_mfma_f32_16x16x32_bf16 v[100:103], v[166:169], v[190:193], v[100:103]
	v_mfma_f32_16x16x32_bf16 v[16:19], v[124:127], v[200:203], v[16:19]
	v_mfma_f32_16x16x32_bf16 v[20:23], v[166:169], v[200:203], v[20:23]
	s_setprio 0
	s_barrier
	ds_read_b128 v[104:107], v212
	ds_read_b128 v[108:111], v212 offset:1024
	ds_read_b128 v[112:115], v212 offset:2048
	ds_read_b128 v[116:119], v212 offset:3072
	ds_read_b128 v[120:123], v213
	ds_read_b128 v[124:127], v213 offset:1024
	ds_read_b128 v[162:165], v213 offset:2048
	ds_read_b128 v[166:169], v213 offset:3072
	s_add_u32 s6, s6, 0x40180
	s_addc_u32 s7, s7, 0
	s_mov_b32 m0, s61
	v_lshl_add_u64 v[198:199], s[6:7], 0, v[132:133]
	ds_read_b128 v[170:173], v139
	ds_read_b128 v[174:177], v139 offset:1024
	ds_read_b128 v[178:181], v139 offset:2048
	ds_read_b128 v[182:185], v139 offset:3072
	ds_read_b128 v[186:189], v139 offset:4096
	ds_read_b128 v[190:193], v139 offset:5120
	ds_read_b128 v[194:197], v139 offset:6144
	ds_read_b128 v[200:203], v139 offset:7168
	global_load_lds_dwordx4 v[198:199], off
	v_lshl_add_u64 v[198:199], s[6:7], 0, v[130:131]
	s_mov_b32 m0, s24
	s_nop 0
	global_load_lds_dwordx4 v[198:199], off
	s_waitcnt vmcnt(8)
	s_waitcnt lgkmcnt(0)
	s_barrier
	s_setprio 1
	s_waitcnt lgkmcnt(0)
	v_mfma_f32_16x16x32_bf16 v[64:67], v[104:107], v[170:173], v[64:67]
	v_mfma_f32_16x16x32_bf16 v[68:71], v[112:115], v[170:173], v[68:71]
	v_mfma_f32_16x16x32_bf16 v[72:75], v[104:107], v[178:181], v[72:75]
	v_mfma_f32_16x16x32_bf16 v[76:79], v[112:115], v[178:181], v[76:79]
	v_mfma_f32_16x16x32_bf16 v[80:83], v[104:107], v[186:189], v[80:83]
	v_mfma_f32_16x16x32_bf16 v[84:87], v[112:115], v[186:189], v[84:87]
	v_mfma_f32_16x16x32_bf16 v[88:91], v[104:107], v[194:197], v[88:91]
	v_mfma_f32_16x16x32_bf16 v[64:67], v[108:111], v[174:177], v[64:67]
	v_mfma_f32_16x16x32_bf16 v[68:71], v[116:119], v[174:177], v[68:71]
	v_mfma_f32_16x16x32_bf16 v[72:75], v[108:111], v[182:185], v[72:75]
	v_mfma_f32_16x16x32_bf16 v[76:79], v[116:119], v[182:185], v[76:79]
	v_mfma_f32_16x16x32_bf16 v[80:83], v[108:111], v[190:193], v[80:83]
	v_mfma_f32_16x16x32_bf16 v[84:87], v[116:119], v[190:193], v[84:87]
	v_mfma_f32_16x16x32_bf16 v[206:209], v[108:111], v[200:203], v[88:91]
	v_mfma_f32_16x16x32_bf16 v[88:91], v[112:115], v[194:197], v[92:95]
	v_mfma_f32_16x16x32_bf16 v[210:213], v[116:119], v[200:203], v[88:91]
	v_mfma_f32_16x16x32_bf16 v[88:91], v[120:123], v[170:173], v[96:99]
	v_mfma_f32_16x16x32_bf16 v[32:35], v[162:165], v[170:173], v[32:35]
	v_mfma_f32_16x16x32_bf16 v[36:39], v[120:123], v[178:181], v[36:39]
	v_mfma_f32_16x16x32_bf16 v[40:43], v[162:165], v[178:181], v[40:43]
	v_mfma_f32_16x16x32_bf16 v[44:47], v[120:123], v[186:189], v[44:47]
	v_mfma_f32_16x16x32_bf16 v[48:51], v[162:165], v[186:189], v[48:51]
	v_mfma_f32_16x16x32_bf16 v[52:55], v[120:123], v[194:197], v[52:55]
	v_mfma_f32_16x16x32_bf16 v[56:59], v[162:165], v[194:197], v[56:59]
	v_mfma_f32_16x16x32_bf16 v[96:99], v[124:127], v[174:177], v[88:91]
	v_mfma_f32_16x16x32_bf16 v[32:35], v[166:169], v[174:177], v[32:35]
	v_mfma_f32_16x16x32_bf16 v[36:39], v[124:127], v[182:185], v[36:39]
	v_mfma_f32_16x16x32_bf16 v[40:43], v[166:169], v[182:185], v[40:43]
	v_mfma_f32_16x16x32_bf16 v[44:47], v[124:127], v[190:193], v[44:47]
	v_mfma_f32_16x16x32_bf16 v[48:51], v[166:169], v[190:193], v[48:51]
	v_mfma_f32_16x16x32_bf16 v[52:55], v[124:127], v[200:203], v[52:55]
	v_mfma_f32_16x16x32_bf16 v[56:59], v[166:169], v[200:203], v[56:59]
	s_setprio 0
	s_barrier
	s_mov_b32 m0, s55
	v_lshl_add_u64 v[198:199], s[10:11], 0, v[140:141]
	s_add_u32 s6, s10, 0x10000
	ds_read_b128 v[88:91], v139 offset:16384
	ds_read_b128 v[92:95], v139 offset:17408
	ds_read_b128 v[170:173], v139 offset:18432
	ds_read_b128 v[174:177], v139 offset:19456
	ds_read_b128 v[178:181], v139 offset:20480
	ds_read_b128 v[182:185], v139 offset:21504
	ds_read_b128 v[186:189], v139 offset:22528
	ds_read_b128 v[190:193], v139 offset:23552
	global_load_lds_dwordx4 v[198:199], off
	v_lshl_add_u64 v[204:205], s[10:11], 0, v[128:129]
	s_mov_b32 m0, s35
	s_addc_u32 s7, s11, 0
	global_load_lds_dwordx4 v[204:205], off
	v_lshl_add_u64 v[194:195], s[6:7], 0, v[140:141]
	s_mov_b32 m0, s38
	v_lshl_add_u64 v[242:243], s[42:43], 0, v[132:133]
	global_load_lds_dwordx4 v[194:195], off
	v_lshl_add_u64 v[194:195], s[6:7], 0, v[128:129]
	s_mov_b32 m0, s53
	v_lshl_add_u64 v[244:245], s[42:43], 0, v[130:131]
	global_load_lds_dwordx4 v[194:195], off
	s_mov_b32 m0, s26
	s_nop 0
	global_load_lds_dwordx4 v[242:243], off
	s_mov_b32 m0, s27
	s_nop 0
	global_load_lds_dwordx4 v[244:245], off
	s_waitcnt vmcnt(8)
	s_waitcnt lgkmcnt(0)
	s_barrier
	s_setprio 1
	s_waitcnt lgkmcnt(0)
	v_mfma_f32_16x16x32_bf16 v[0:3], v[104:107], v[186:189], v[0:3]
	v_mfma_f32_16x16x32_bf16 v[4:7], v[112:115], v[186:189], v[4:7]
	v_mfma_f32_16x16x32_bf16 v[134:137], v[104:107], v[88:91], v[134:137]
	v_mfma_f32_16x16x32_bf16 v[142:145], v[112:115], v[88:91], v[142:145]
	v_mfma_f32_16x16x32_bf16 v[146:149], v[104:107], v[170:173], v[146:149]
	v_mfma_f32_16x16x32_bf16 v[150:153], v[112:115], v[170:173], v[150:153]
	v_mfma_f32_16x16x32_bf16 v[154:157], v[104:107], v[178:181], v[154:157]
	v_mfma_f32_16x16x32_bf16 v[158:161], v[112:115], v[178:181], v[158:161]
	v_mfma_f32_16x16x32_bf16 v[0:3], v[108:111], v[190:193], v[0:3]
	v_mfma_f32_16x16x32_bf16 v[4:7], v[116:119], v[190:193], v[4:7]
	v_mfma_f32_16x16x32_bf16 v[134:137], v[108:111], v[92:95], v[134:137]
	v_mfma_f32_16x16x32_bf16 v[142:145], v[116:119], v[92:95], v[142:145]
	v_mfma_f32_16x16x32_bf16 v[146:149], v[108:111], v[174:177], v[146:149]
	v_mfma_f32_16x16x32_bf16 v[150:153], v[116:119], v[174:177], v[150:153]
	v_mfma_f32_16x16x32_bf16 v[154:157], v[108:111], v[182:185], v[154:157]
	v_mfma_f32_16x16x32_bf16 v[158:161], v[116:119], v[182:185], v[158:161]
	v_mfma_f32_16x16x32_bf16 v[8:11], v[120:123], v[88:91], v[8:11]
	v_mfma_f32_16x16x32_bf16 v[194:197], v[124:127], v[92:95], v[8:11]
	v_mfma_f32_16x16x32_bf16 v[8:11], v[162:165], v[88:91], v[12:15]
	v_mfma_f32_16x16x32_bf16 v[200:203], v[166:169], v[92:95], v[8:11]
	v_mfma_f32_16x16x32_bf16 v[8:11], v[120:123], v[170:173], v[24:27]
	v_mfma_f32_16x16x32_bf16 v[214:217], v[124:127], v[174:177], v[8:11]
	v_mfma_f32_16x16x32_bf16 v[8:11], v[162:165], v[170:173], v[28:31]
	v_mfma_f32_16x16x32_bf16 v[170:173], v[166:169], v[174:177], v[8:11]
	v_mfma_f32_16x16x32_bf16 v[8:11], v[120:123], v[178:181], v[60:63]
	v_mfma_f32_16x16x32_bf16 v[174:177], v[124:127], v[182:185], v[8:11]
	v_mfma_f32_16x16x32_bf16 v[8:11], v[162:165], v[178:181], v[100:103]
	v_mfma_f32_16x16x32_bf16 v[178:181], v[166:169], v[182:185], v[8:11]
	v_mfma_f32_16x16x32_bf16 v[8:11], v[120:123], v[186:189], v[16:19]
	v_mfma_f32_16x16x32_bf16 v[182:185], v[124:127], v[190:193], v[8:11]
	v_mfma_f32_16x16x32_bf16 v[8:11], v[162:165], v[186:189], v[20:23]
	v_mfma_f32_16x16x32_bf16 v[162:165], v[166:169], v[190:193], v[8:11]
	s_setprio 0
	s_barrier
	s_nop 4
	ds_read_b128 v[8:11], v218
	ds_read_b128 v[12:15], v218 offset:1024
	ds_read_b128 v[16:19], v218 offset:2048
	ds_read_b128 v[20:23], v218 offset:3072
	ds_read_b128 v[166:169], v219
	ds_read_b128 v[186:189], v219 offset:1024
	ds_read_b128 v[190:193], v219 offset:2048
	ds_read_b128 v[218:221], v219 offset:3072
	s_add_u32 s6, s42, 0x40000
	s_addc_u32 s7, s43, 0
	s_mov_b32 m0, s28
	v_lshl_add_u64 v[88:89], s[6:7], 0, v[132:133]
	ds_read_b128 v[24:27], v139 offset:32768
	ds_read_b128 v[28:31], v139 offset:33792
	ds_read_b128 v[60:63], v139 offset:34816
	ds_read_b128 v[222:225], v139 offset:35840
	ds_read_b128 v[226:229], v139 offset:36864
	ds_read_b128 v[230:233], v139 offset:37888
	ds_read_b128 v[234:237], v139 offset:38912
	ds_read_b128 v[238:241], v139 offset:39936
	global_load_lds_dwordx4 v[88:89], off
	v_lshl_add_u64 v[88:89], s[6:7], 0, v[130:131]
	s_mov_b32 m0, s29
	s_nop 0
	global_load_lds_dwordx4 v[88:89], off
	s_waitcnt vmcnt(8)
	s_waitcnt lgkmcnt(0)
	s_barrier
	s_setprio 1
	s_waitcnt lgkmcnt(0)
	v_mfma_f32_16x16x32_bf16 v[64:67], v[8:11], v[24:27], v[64:67]
	v_mfma_f32_16x16x32_bf16 v[120:123], v[12:15], v[28:31], v[64:67]
	v_mfma_f32_16x16x32_bf16 v[64:67], v[16:19], v[24:27], v[68:71]
	v_mfma_f32_16x16x32_bf16 v[124:127], v[20:23], v[28:31], v[64:67]
	v_mfma_f32_16x16x32_bf16 v[64:67], v[8:11], v[60:63], v[72:75]
	v_mfma_f32_16x16x32_bf16 v[104:107], v[12:15], v[222:225], v[64:67]
	v_mfma_f32_16x16x32_bf16 v[64:67], v[16:19], v[60:63], v[76:79]
	v_mfma_f32_16x16x32_bf16 v[108:111], v[20:23], v[222:225], v[64:67]
	v_mfma_f32_16x16x32_bf16 v[64:67], v[8:11], v[226:229], v[80:83]
	v_mfma_f32_16x16x32_bf16 v[88:91], v[12:15], v[230:233], v[64:67]
	v_mfma_f32_16x16x32_bf16 v[64:67], v[16:19], v[226:229], v[84:87]
	v_mfma_f32_16x16x32_bf16 v[92:95], v[20:23], v[230:233], v[64:67]
	v_mfma_f32_16x16x32_bf16 v[64:67], v[8:11], v[234:237], v[206:209]
	v_mfma_f32_16x16x32_bf16 v[72:75], v[12:15], v[238:241], v[64:67]
	v_mfma_f32_16x16x32_bf16 v[64:67], v[16:19], v[234:237], v[210:213]
	v_mfma_f32_16x16x32_bf16 v[76:79], v[20:23], v[238:241], v[64:67]
	v_mfma_f32_16x16x32_bf16 v[64:67], v[166:169], v[24:27], v[96:99]
	v_mfma_f32_16x16x32_bf16 v[24:27], v[190:193], v[24:27], v[32:35]
	v_mfma_f32_16x16x32_bf16 v[112:115], v[218:221], v[28:31], v[24:27]
	v_mfma_f32_16x16x32_bf16 v[24:27], v[166:169], v[60:63], v[36:39]
	v_mfma_f32_16x16x32_bf16 v[100:103], v[186:189], v[222:225], v[24:27]
	v_mfma_f32_16x16x32_bf16 v[24:27], v[190:193], v[60:63], v[40:43]
	v_mfma_f32_16x16x32_bf16 v[96:99], v[218:221], v[222:225], v[24:27]
	v_mfma_f32_16x16x32_bf16 v[24:27], v[166:169], v[226:229], v[44:47]
	v_mfma_f32_16x16x32_bf16 v[84:87], v[186:189], v[230:233], v[24:27]
	v_mfma_f32_16x16x32_bf16 v[24:27], v[190:193], v[226:229], v[48:51]
	v_mfma_f32_16x16x32_bf16 v[80:83], v[218:221], v[230:233], v[24:27]
	v_mfma_f32_16x16x32_bf16 v[24:27], v[166:169], v[234:237], v[52:55]
	v_mfma_f32_16x16x32_bf16 v[68:71], v[186:189], v[238:241], v[24:27]
	v_mfma_f32_16x16x32_bf16 v[24:27], v[190:193], v[234:237], v[56:59]
	v_mfma_f32_16x16x32_bf16 v[116:119], v[186:189], v[28:31], v[64:67]
	v_mfma_f32_16x16x32_bf16 v[64:67], v[218:221], v[238:241], v[24:27]
	s_setprio 0
	s_barrier
	s_mov_b32 m0, s74
	s_nop 2
	v_lshl_add_u64 v[24:25], v[198:199], 0, s[36:37]
	s_add_u32 s6, s10, 0x10080
	ds_read_b128 v[32:35], v139 offset:49152
	ds_read_b128 v[36:39], v139 offset:50176
	ds_read_b128 v[206:209], v139 offset:51200
	ds_read_b128 v[210:213], v139 offset:52224
	ds_read_b128 v[222:225], v139 offset:53248
	ds_read_b128 v[226:229], v139 offset:54272
	ds_read_b128 v[230:233], v139 offset:55296
	ds_read_b128 v[234:237], v139 offset:56320
	global_load_lds_dwordx4 v[24:25], off
	v_lshl_add_u64 v[24:25], v[204:205], 0, s[36:37]
	s_mov_b32 m0, s60
	s_addc_u32 s7, s11, 0
	global_load_lds_dwordx4 v[24:25], off
	v_lshl_add_u64 v[24:25], s[6:7], 0, v[140:141]
	s_mov_b32 m0, s8
	s_nop 0
	global_load_lds_dwordx4 v[24:25], off
	v_lshl_add_u64 v[24:25], s[6:7], 0, v[128:129]
	s_mov_b32 m0, s9
	s_nop 0
	global_load_lds_dwordx4 v[24:25], off
	v_lshl_add_u64 v[24:25], v[242:243], 0, s[36:37]
	s_mov_b32 m0, s58
	s_nop 0
	global_load_lds_dwordx4 v[24:25], off
	v_lshl_add_u64 v[24:25], v[244:245], 0, s[36:37]
	s_mov_b32 m0, s59
	s_nop 0
	global_load_lds_dwordx4 v[24:25], off
	s_waitcnt vmcnt(8)
	s_waitcnt lgkmcnt(0)
	s_barrier
	s_setprio 1
	s_waitcnt lgkmcnt(0)
	v_mfma_f32_16x16x32_bf16 v[24:27], v[8:11], v[32:35], v[134:137]
	v_mfma_f32_16x16x32_bf16 v[56:59], v[12:15], v[36:39], v[24:27]
	v_mfma_f32_16x16x32_bf16 v[24:27], v[16:19], v[32:35], v[142:145]
	v_mfma_f32_16x16x32_bf16 v[60:63], v[20:23], v[36:39], v[24:27]
	v_mfma_f32_16x16x32_bf16 v[24:27], v[8:11], v[206:209], v[146:149]
	v_mfma_f32_16x16x32_bf16 v[40:43], v[12:15], v[210:213], v[24:27]
	v_mfma_f32_16x16x32_bf16 v[24:27], v[16:19], v[206:209], v[150:153]
	v_mfma_f32_16x16x32_bf16 v[0:3], v[8:11], v[230:233], v[0:3]
	v_mfma_f32_16x16x32_bf16 v[44:47], v[20:23], v[210:213], v[24:27]
	v_mfma_f32_16x16x32_bf16 v[24:27], v[8:11], v[222:225], v[154:157]
	v_mfma_f32_16x16x32_bf16 v[28:31], v[16:19], v[222:225], v[158:161]
	v_mfma_f32_16x16x32_bf16 v[8:11], v[12:15], v[234:237], v[0:3]
	v_mfma_f32_16x16x32_bf16 v[0:3], v[16:19], v[230:233], v[4:7]
	v_mfma_f32_16x16x32_bf16 v[24:27], v[12:15], v[226:229], v[24:27]
	v_mfma_f32_16x16x32_bf16 v[28:31], v[20:23], v[226:229], v[28:31]
	v_mfma_f32_16x16x32_bf16 v[12:15], v[20:23], v[234:237], v[0:3]
	v_mfma_f32_16x16x32_bf16 v[0:3], v[166:169], v[32:35], v[194:197]
	v_mfma_f32_16x16x32_bf16 v[52:55], v[186:189], v[36:39], v[0:3]
	v_mfma_f32_16x16x32_bf16 v[0:3], v[190:193], v[32:35], v[200:203]
	v_mfma_f32_16x16x32_bf16 v[48:51], v[218:221], v[36:39], v[0:3]
	v_mfma_f32_16x16x32_bf16 v[0:3], v[166:169], v[206:209], v[214:217]
	v_mfma_f32_16x16x32_bf16 v[36:39], v[186:189], v[210:213], v[0:3]
	v_mfma_f32_16x16x32_bf16 v[0:3], v[190:193], v[206:209], v[170:173]
	v_mfma_f32_16x16x32_bf16 v[32:35], v[218:221], v[210:213], v[0:3]
	v_mfma_f32_16x16x32_bf16 v[0:3], v[166:169], v[222:225], v[174:177]
	v_mfma_f32_16x16x32_bf16 v[20:23], v[186:189], v[226:229], v[0:3]
	v_mfma_f32_16x16x32_bf16 v[0:3], v[190:193], v[222:225], v[178:181]
	v_mfma_f32_16x16x32_bf16 v[16:19], v[218:221], v[226:229], v[0:3]
	v_mfma_f32_16x16x32_bf16 v[0:3], v[166:169], v[230:233], v[182:185]
	v_mfma_f32_16x16x32_bf16 v[4:7], v[186:189], v[234:237], v[0:3]
	v_mfma_f32_16x16x32_bf16 v[0:3], v[190:193], v[230:233], v[162:165]
	v_mfma_f32_16x16x32_bf16 v[0:3], v[218:221], v[234:237], v[0:3]
	s_setprio 0
	s_barrier
	s_andn2_b64 vcc, exec, s[48:49]
	s_cbranch_vccnz .LBB0_459
	s_barrier

.LBB0_552:
	s_add_u32 s8, s6, 0xfffc0080
	s_addc_u32 s9, s7, -1
	s_add_i32 s35, 0, 0x10000
	s_cmp_eq_u32 s56, 12
	s_cselect_b32 s11, s4, s9
	s_cselect_b32 s10, s5, s8
	v_add_u32_e32 v140, s35, v165
	s_cselect_b32 s9, s24, s51
	s_cselect_b32 s8, s38, s47
	s_add_i32 s57, 0, 0x14000
	ds_read_b128 v[158:161], v140
	ds_read_b128 v[168:171], v140 offset:1024
	ds_read_b128 v[172:175], v140 offset:2048
	ds_read_b128 v[176:179], v140 offset:3072
	v_add_u32_e32 v140, s57, v165
	ds_read_b128 v[180:183], v140
	ds_read_b128 v[184:187], v140 offset:1024
	ds_read_b128 v[206:209], v140 offset:2048
	ds_read_b128 v[210:213], v140 offset:3072
	v_lshl_add_u64 v[142:143], s[6:7], 0, v[136:137]
	s_add_i32 m0, s66, 0xc000
	ds_read_b128 v[214:217], v166
	ds_read_b128 v[218:221], v166 offset:1024
	ds_read_b128 v[222:225], v166 offset:2048
	ds_read_b128 v[226:229], v166 offset:3072
	ds_read_b128 v[230:233], v166 offset:4096
	ds_read_b128 v[234:237], v166 offset:5120
	ds_read_b128 v[238:241], v166 offset:6144
	ds_read_b128 v[242:245], v166 offset:7168
	global_load_lds_dwordx4 v[142:143], off
	v_lshl_add_u64 v[142:143], s[6:7], 0, v[138:139]
	s_add_i32 m0, s66, 0xe000
	s_nop 0
	global_load_lds_dwordx4 v[142:143], off
	s_waitcnt vmcnt(8)
	s_waitcnt lgkmcnt(0)
	s_barrier
	s_setprio 1
	s_waitcnt lgkmcnt(0)
	v_mfma_f32_16x16x32_bf16 v[124:127], v[158:161], v[214:217], v[124:127]
	v_mfma_f32_16x16x32_bf16 v[120:123], v[172:175], v[214:217], v[120:123]
	v_mfma_f32_16x16x32_bf16 v[108:111], v[158:161], v[222:225], v[108:111]
	v_mfma_f32_16x16x32_bf16 v[104:107], v[172:175], v[222:225], v[104:107]
	v_mfma_f32_16x16x32_bf16 v[92:95], v[158:161], v[230:233], v[92:95]
	v_mfma_f32_16x16x32_bf16 v[88:91], v[172:175], v[230:233], v[88:91]
	v_mfma_f32_16x16x32_bf16 v[76:79], v[158:161], v[238:241], v[76:79]
	v_mfma_f32_16x16x32_bf16 v[72:75], v[172:175], v[238:241], v[72:75]
	v_mfma_f32_16x16x32_bf16 v[124:127], v[168:171], v[218:221], v[124:127]
	v_mfma_f32_16x16x32_bf16 v[120:123], v[176:179], v[218:221], v[120:123]
	v_mfma_f32_16x16x32_bf16 v[108:111], v[168:171], v[226:229], v[108:111]
	v_mfma_f32_16x16x32_bf16 v[104:107], v[176:179], v[226:229], v[104:107]
	v_mfma_f32_16x16x32_bf16 v[92:95], v[168:171], v[234:237], v[92:95]
	v_mfma_f32_16x16x32_bf16 v[88:91], v[176:179], v[234:237], v[88:91]
	v_mfma_f32_16x16x32_bf16 v[76:79], v[168:171], v[242:245], v[76:79]
	v_mfma_f32_16x16x32_bf16 v[72:75], v[176:179], v[242:245], v[72:75]
	v_mfma_f32_16x16x32_bf16 v[116:119], v[180:183], v[214:217], v[116:119]
	v_mfma_f32_16x16x32_bf16 v[112:115], v[206:209], v[214:217], v[112:115]
	v_mfma_f32_16x16x32_bf16 v[100:103], v[180:183], v[222:225], v[100:103]
	v_mfma_f32_16x16x32_bf16 v[96:99], v[206:209], v[222:225], v[96:99]
	v_mfma_f32_16x16x32_bf16 v[84:87], v[180:183], v[230:233], v[84:87]
	v_mfma_f32_16x16x32_bf16 v[80:83], v[206:209], v[230:233], v[80:83]
	v_mfma_f32_16x16x32_bf16 v[68:71], v[180:183], v[238:241], v[68:71]
	v_mfma_f32_16x16x32_bf16 v[64:67], v[206:209], v[238:241], v[64:67]
	v_mfma_f32_16x16x32_bf16 v[116:119], v[184:187], v[218:221], v[116:119]
	v_mfma_f32_16x16x32_bf16 v[112:115], v[210:213], v[218:221], v[112:115]
	v_mfma_f32_16x16x32_bf16 v[100:103], v[184:187], v[226:229], v[100:103]
	v_mfma_f32_16x16x32_bf16 v[96:99], v[210:213], v[226:229], v[96:99]
	v_mfma_f32_16x16x32_bf16 v[84:87], v[184:187], v[234:237], v[84:87]
	v_mfma_f32_16x16x32_bf16 v[80:83], v[210:213], v[234:237], v[80:83]
	v_mfma_f32_16x16x32_bf16 v[68:71], v[184:187], v[242:245], v[68:71]
	v_mfma_f32_16x16x32_bf16 v[64:67], v[210:213], v[242:245], v[64:67]
	s_setprio 0
	s_barrier
	s_add_i32 s35, s35, s12
	v_lshl_add_u64 v[142:143], s[8:9], 0, v[132:133]
	s_mov_b32 m0, s35
	ds_read_b128 v[214:217], v166 offset:16384
	ds_read_b128 v[218:221], v166 offset:17408
	ds_read_b128 v[222:225], v166 offset:18432
	ds_read_b128 v[226:229], v166 offset:19456
	ds_read_b128 v[230:233], v166 offset:20480
	ds_read_b128 v[234:237], v166 offset:21504
	ds_read_b128 v[238:241], v166 offset:22528
	ds_read_b128 v[242:245], v166 offset:23552
	global_load_lds_dwordx4 v[142:143], off
	s_add_i32 m0, s35, 0x2000
	s_add_u32 s58, s8, 0x40000
	v_lshl_add_u64 v[144:145], s[8:9], 0, v[128:129]
	s_addc_u32 s59, s9, 0
	s_add_i32 s35, s57, s12
	global_load_lds_dwordx4 v[144:145], off
	v_lshl_add_u64 v[146:147], s[58:59], 0, v[132:133]
	s_mov_b32 m0, s35
	v_lshl_add_u64 v[148:149], s[10:11], 0, v[130:131]
	global_load_lds_dwordx4 v[146:147], off
	v_lshl_add_u64 v[146:147], s[58:59], 0, v[128:129]
	s_add_i32 m0, s35, 0x2000
	s_nop 0
	global_load_lds_dwordx4 v[146:147], off
	v_lshl_add_u64 v[146:147], s[10:11], 0, v[134:135]
	s_mov_b32 m0, s66
	s_nop 0
	global_load_lds_dwordx4 v[146:147], off
	s_mov_b32 m0, s67
	s_nop 0
	global_load_lds_dwordx4 v[148:149], off
	s_waitcnt vmcnt(8)
	s_waitcnt lgkmcnt(0)
	s_barrier
	s_setprio 1
	s_waitcnt lgkmcnt(0)
	v_mfma_f32_16x16x32_bf16 v[60:63], v[158:161], v[214:217], v[60:63]
	v_mfma_f32_16x16x32_bf16 v[56:59], v[172:175], v[214:217], v[56:59]
	v_mfma_f32_16x16x32_bf16 v[44:47], v[158:161], v[222:225], v[44:47]
	v_mfma_f32_16x16x32_bf16 v[40:43], v[172:175], v[222:225], v[40:43]
	v_mfma_f32_16x16x32_bf16 v[28:31], v[158:161], v[230:233], v[28:31]
	v_mfma_f32_16x16x32_bf16 v[24:27], v[172:175], v[230:233], v[24:27]
	v_mfma_f32_16x16x32_bf16 v[12:15], v[158:161], v[238:241], v[12:15]
	v_mfma_f32_16x16x32_bf16 v[8:11], v[172:175], v[238:241], v[8:11]
	v_mfma_f32_16x16x32_bf16 v[60:63], v[168:171], v[218:221], v[60:63]
	v_mfma_f32_16x16x32_bf16 v[56:59], v[176:179], v[218:221], v[56:59]
	v_mfma_f32_16x16x32_bf16 v[44:47], v[168:171], v[226:229], v[44:47]
	v_mfma_f32_16x16x32_bf16 v[40:43], v[176:179], v[226:229], v[40:43]
	v_mfma_f32_16x16x32_bf16 v[28:31], v[168:171], v[234:237], v[28:31]
	v_mfma_f32_16x16x32_bf16 v[24:27], v[176:179], v[234:237], v[24:27]
	v_mfma_f32_16x16x32_bf16 v[12:15], v[168:171], v[242:245], v[12:15]
	v_mfma_f32_16x16x32_bf16 v[8:11], v[176:179], v[242:245], v[8:11]
	v_mfma_f32_16x16x32_bf16 v[52:55], v[180:183], v[214:217], v[52:55]
	v_mfma_f32_16x16x32_bf16 v[48:51], v[206:209], v[214:217], v[48:51]
	v_mfma_f32_16x16x32_bf16 v[36:39], v[180:183], v[222:225], v[36:39]
	v_mfma_f32_16x16x32_bf16 v[32:35], v[206:209], v[222:225], v[32:35]
	v_mfma_f32_16x16x32_bf16 v[20:23], v[180:183], v[230:233], v[20:23]
	v_mfma_f32_16x16x32_bf16 v[16:19], v[206:209], v[230:233], v[16:19]
	v_mfma_f32_16x16x32_bf16 v[4:7], v[180:183], v[238:241], v[4:7]
	v_mfma_f32_16x16x32_bf16 v[0:3], v[206:209], v[238:241], v[0:3]
	v_mfma_f32_16x16x32_bf16 v[52:55], v[184:187], v[218:221], v[52:55]
	v_mfma_f32_16x16x32_bf16 v[48:51], v[210:213], v[218:221], v[48:51]
	v_mfma_f32_16x16x32_bf16 v[36:39], v[184:187], v[226:229], v[36:39]
	v_mfma_f32_16x16x32_bf16 v[32:35], v[210:213], v[226:229], v[32:35]
	v_mfma_f32_16x16x32_bf16 v[20:23], v[184:187], v[234:237], v[20:23]
	v_mfma_f32_16x16x32_bf16 v[16:19], v[210:213], v[234:237], v[16:19]
	v_mfma_f32_16x16x32_bf16 v[4:7], v[184:187], v[242:245], v[4:7]
	v_mfma_f32_16x16x32_bf16 v[0:3], v[210:213], v[242:245], v[0:3]
	s_setprio 0
	s_barrier
	s_add_i32 s35, 0, 0x18000
	v_add_u32_e32 v140, s35, v165
	s_add_i32 s57, 0, 0x1c000
	ds_read_b128 v[158:161], v140
	ds_read_b128 v[168:171], v140 offset:1024
	ds_read_b128 v[172:175], v140 offset:2048
	ds_read_b128 v[176:179], v140 offset:3072
	v_add_u32_e32 v140, s57, v165
	ds_read_b128 v[180:183], v140
	ds_read_b128 v[184:187], v140 offset:1024
	ds_read_b128 v[206:209], v140 offset:2048
	ds_read_b128 v[210:213], v140 offset:3072
	s_add_u32 s10, s10, 0x40000
	s_addc_u32 s11, s11, 0
	s_mov_b32 m0, s74
	v_lshl_add_u64 v[150:151], s[10:11], 0, v[134:135]
	ds_read_b128 v[214:217], v166 offset:32768
	ds_read_b128 v[218:221], v166 offset:33792
	ds_read_b128 v[222:225], v166 offset:34816
	ds_read_b128 v[226:229], v166 offset:35840
	ds_read_b128 v[230:233], v166 offset:36864
	ds_read_b128 v[234:237], v166 offset:37888
	ds_read_b128 v[238:241], v166 offset:38912
	ds_read_b128 v[242:245], v166 offset:39936
	global_load_lds_dwordx4 v[150:151], off
	v_lshl_add_u64 v[150:151], s[10:11], 0, v[130:131]
	s_mov_b32 m0, s75
	s_nop 0
	global_load_lds_dwordx4 v[150:151], off
	s_waitcnt vmcnt(8)
	s_waitcnt lgkmcnt(0)
	s_barrier
	s_setprio 1
	s_waitcnt lgkmcnt(0)
	v_mfma_f32_16x16x32_bf16 v[124:127], v[158:161], v[214:217], v[124:127]
	v_mfma_f32_16x16x32_bf16 v[120:123], v[172:175], v[214:217], v[120:123]
	v_mfma_f32_16x16x32_bf16 v[108:111], v[158:161], v[222:225], v[108:111]
	v_mfma_f32_16x16x32_bf16 v[104:107], v[172:175], v[222:225], v[104:107]
	v_mfma_f32_16x16x32_bf16 v[92:95], v[158:161], v[230:233], v[92:95]
	v_mfma_f32_16x16x32_bf16 v[88:91], v[172:175], v[230:233], v[88:91]
	v_mfma_f32_16x16x32_bf16 v[76:79], v[158:161], v[238:241], v[76:79]
	v_mfma_f32_16x16x32_bf16 v[72:75], v[172:175], v[238:241], v[72:75]
	v_mfma_f32_16x16x32_bf16 v[124:127], v[168:171], v[218:221], v[124:127]
	v_mfma_f32_16x16x32_bf16 v[120:123], v[176:179], v[218:221], v[120:123]
	v_mfma_f32_16x16x32_bf16 v[108:111], v[168:171], v[226:229], v[108:111]
	v_mfma_f32_16x16x32_bf16 v[104:107], v[176:179], v[226:229], v[104:107]
	v_mfma_f32_16x16x32_bf16 v[92:95], v[168:171], v[234:237], v[92:95]
	v_mfma_f32_16x16x32_bf16 v[88:91], v[176:179], v[234:237], v[88:91]
	v_mfma_f32_16x16x32_bf16 v[76:79], v[168:171], v[242:245], v[76:79]
	v_mfma_f32_16x16x32_bf16 v[72:75], v[176:179], v[242:245], v[72:75]
	v_mfma_f32_16x16x32_bf16 v[116:119], v[180:183], v[214:217], v[116:119]
	v_mfma_f32_16x16x32_bf16 v[112:115], v[206:209], v[214:217], v[112:115]
	v_mfma_f32_16x16x32_bf16 v[100:103], v[180:183], v[222:225], v[100:103]
	v_mfma_f32_16x16x32_bf16 v[96:99], v[206:209], v[222:225], v[96:99]
	v_mfma_f32_16x16x32_bf16 v[84:87], v[180:183], v[230:233], v[84:87]
	v_mfma_f32_16x16x32_bf16 v[80:83], v[206:209], v[230:233], v[80:83]
	v_mfma_f32_16x16x32_bf16 v[68:71], v[180:183], v[238:241], v[68:71]
	v_mfma_f32_16x16x32_bf16 v[64:67], v[206:209], v[238:241], v[64:67]
	v_mfma_f32_16x16x32_bf16 v[116:119], v[184:187], v[218:221], v[116:119]
	v_mfma_f32_16x16x32_bf16 v[112:115], v[210:213], v[218:221], v[112:115]
	v_mfma_f32_16x16x32_bf16 v[100:103], v[184:187], v[226:229], v[100:103]
	v_mfma_f32_16x16x32_bf16 v[96:99], v[210:213], v[226:229], v[96:99]
	v_mfma_f32_16x16x32_bf16 v[84:87], v[184:187], v[234:237], v[84:87]
	v_mfma_f32_16x16x32_bf16 v[80:83], v[210:213], v[234:237], v[80:83]
	v_mfma_f32_16x16x32_bf16 v[68:71], v[184:187], v[242:245], v[68:71]
	v_mfma_f32_16x16x32_bf16 v[64:67], v[210:213], v[242:245], v[64:67]
	s_setprio 0
	s_barrier
	s_add_i32 s10, s35, s12
	v_lshl_add_u64 v[142:143], v[142:143], 0, s[36:37]
	s_mov_b32 m0, s10
	ds_read_b128 v[214:217], v166 offset:49152
	ds_read_b128 v[218:221], v166 offset:50176
	ds_read_b128 v[222:225], v166 offset:51200
	ds_read_b128 v[226:229], v166 offset:52224
	ds_read_b128 v[230:233], v166 offset:53248
	ds_read_b128 v[234:237], v166 offset:54272
	ds_read_b128 v[238:241], v166 offset:55296
	ds_read_b128 v[242:245], v166 offset:56320
	global_load_lds_dwordx4 v[142:143], off
	s_add_i32 m0, s10, 0x2000
	s_add_u32 s8, s8, 0x40080
	v_lshl_add_u64 v[142:143], v[144:145], 0, s[36:37]
	s_addc_u32 s9, s9, 0
	s_add_i32 s10, s57, s12
	global_load_lds_dwordx4 v[142:143], off
	v_lshl_add_u64 v[142:143], s[8:9], 0, v[132:133]
	s_mov_b32 m0, s10
	s_nop 0
	global_load_lds_dwordx4 v[142:143], off
	v_lshl_add_u64 v[142:143], s[8:9], 0, v[128:129]
	s_add_i32 m0, s10, 0x2000
	s_nop 0
	global_load_lds_dwordx4 v[142:143], off
	v_lshl_add_u64 v[142:143], v[146:147], 0, s[36:37]
	s_mov_b32 m0, s26
	s_nop 0
	global_load_lds_dwordx4 v[142:143], off
	v_lshl_add_u64 v[142:143], v[148:149], 0, s[36:37]
	s_mov_b32 m0, s27
	s_nop 0
	global_load_lds_dwordx4 v[142:143], off
	s_waitcnt vmcnt(8)
	s_waitcnt lgkmcnt(0)
	s_barrier
	s_setprio 1
	s_waitcnt lgkmcnt(0)
	v_mfma_f32_16x16x32_bf16 v[60:63], v[158:161], v[214:217], v[60:63]
	v_mfma_f32_16x16x32_bf16 v[56:59], v[172:175], v[214:217], v[56:59]
	v_mfma_f32_16x16x32_bf16 v[44:47], v[158:161], v[222:225], v[44:47]
	v_mfma_f32_16x16x32_bf16 v[40:43], v[172:175], v[222:225], v[40:43]
	v_mfma_f32_16x16x32_bf16 v[28:31], v[158:161], v[230:233], v[28:31]
	v_mfma_f32_16x16x32_bf16 v[24:27], v[172:175], v[230:233], v[24:27]
	v_mfma_f32_16x16x32_bf16 v[12:15], v[158:161], v[238:241], v[12:15]
	v_mfma_f32_16x16x32_bf16 v[8:11], v[172:175], v[238:241], v[8:11]
	v_mfma_f32_16x16x32_bf16 v[60:63], v[168:171], v[218:221], v[60:63]
	v_mfma_f32_16x16x32_bf16 v[56:59], v[176:179], v[218:221], v[56:59]
	v_mfma_f32_16x16x32_bf16 v[44:47], v[168:171], v[226:229], v[44:47]
	v_mfma_f32_16x16x32_bf16 v[40:43], v[176:179], v[226:229], v[40:43]
	v_mfma_f32_16x16x32_bf16 v[28:31], v[168:171], v[234:237], v[28:31]
	v_mfma_f32_16x16x32_bf16 v[24:27], v[176:179], v[234:237], v[24:27]
	v_mfma_f32_16x16x32_bf16 v[12:15], v[168:171], v[242:245], v[12:15]
	v_mfma_f32_16x16x32_bf16 v[8:11], v[176:179], v[242:245], v[8:11]
	v_mfma_f32_16x16x32_bf16 v[52:55], v[180:183], v[214:217], v[52:55]
	v_mfma_f32_16x16x32_bf16 v[48:51], v[206:209], v[214:217], v[48:51]
	v_mfma_f32_16x16x32_bf16 v[36:39], v[180:183], v[222:225], v[36:39]
	v_mfma_f32_16x16x32_bf16 v[32:35], v[206:209], v[222:225], v[32:35]
	v_mfma_f32_16x16x32_bf16 v[20:23], v[180:183], v[230:233], v[20:23]
	v_mfma_f32_16x16x32_bf16 v[16:19], v[206:209], v[230:233], v[16:19]
	v_mfma_f32_16x16x32_bf16 v[4:7], v[180:183], v[238:241], v[4:7]
	v_mfma_f32_16x16x32_bf16 v[0:3], v[206:209], v[238:241], v[0:3]
	v_mfma_f32_16x16x32_bf16 v[52:55], v[184:187], v[218:221], v[52:55]
	v_mfma_f32_16x16x32_bf16 v[48:51], v[210:213], v[218:221], v[48:51]
	v_mfma_f32_16x16x32_bf16 v[36:39], v[184:187], v[226:229], v[36:39]
	v_mfma_f32_16x16x32_bf16 v[32:35], v[210:213], v[226:229], v[32:35]
	v_mfma_f32_16x16x32_bf16 v[20:23], v[184:187], v[234:237], v[20:23]
	v_mfma_f32_16x16x32_bf16 v[16:19], v[210:213], v[234:237], v[16:19]
	v_mfma_f32_16x16x32_bf16 v[4:7], v[184:187], v[242:245], v[4:7]
	v_mfma_f32_16x16x32_bf16 v[0:3], v[210:213], v[242:245], v[0:3]
	s_setprio 0
	s_barrier
	s_add_i32 s56, s56, 2
	s_add_u32 s6, s6, 0x100
	s_addc_u32 s7, s7, 0
	s_add_u32 s47, s47, 0x100
	s_addc_u32 s51, s51, 0
	s_cmp_gt_u32 s56, 13
	s_cbranch_scc0 .LBB0_552
	s_and_b64 vcc, exec, s[44:45]
	s_cbranch_vccz .LBB0_555
	s_barrier

.LBB0_676:
	s_lshl_b32 s12, s61, 22
	s_and_b32 s35, s12, 0x3c00000
	s_ashr_i32 s12, s61, 4
	s_ashr_i32 s13, s12, 31
	s_lshl_b64 s[12:13], s[12:13], 9
	s_add_u32 s35, s14, s35
	s_addc_u32 s53, s15, 0
	s_add_u32 s54, s35, s12
	s_addc_u32 s55, s53, s13
	s_and_b64 s[56:57], s[42:43], exec
	s_cselect_b32 s59, s55, s9
	s_cselect_b32 s58, s54, s8
	s_ashr_i32 s53, s52, 31
	s_lshl_b64 s[56:57], s[52:53], 19
	s_add_u32 s35, s26, s56
	s_addc_u32 s53, s27, s57
	s_add_u32 s56, s35, s12
	s_addc_u32 s57, s53, s13
	s_and_b64 s[12:13], s[42:43], exec
	s_cselect_b32 s13, s57, s11
	s_cselect_b32 s12, s56, s10
	s_add_i32 s70, 0, 0x10000
	s_add_i32 s71, 0, 0x14000
	v_add_u32_e32 v152, s70, v138
	v_add_u32_e32 v153, s71, v138
	ds_read_b128 v[0:3], v152
	ds_read_b128 v[4:7], v152 offset:1024
	ds_read_b128 v[8:11], v152 offset:2048
	ds_read_b128 v[12:15], v152 offset:3072
	ds_read_b128 v[16:19], v153
	ds_read_b128 v[20:23], v153 offset:1024
	ds_read_b128 v[24:27], v153 offset:2048
	ds_read_b128 v[28:31], v153 offset:3072
	v_mov_b32_e32 v204, 0x358637bd
	v_mov_b32_e32 v250, 0x260
	v_mov_b32_e32 v251, 0x3e124925
	s_add_u32 s68, s8, 0x200080
	s_addc_u32 s69, s9, 0
	s_add_i32 s72, s4, 0xc000
	v_lshl_add_u64 v[64:65], s[68:69], 0, v[132:133]
	s_mov_b32 m0, s72
	s_add_i32 s35, s4, 0xe000
	ds_read_b128 v[32:35], v139
	ds_read_b128 v[36:39], v139 offset:1024
	ds_read_b128 v[40:43], v139 offset:2048
	ds_read_b128 v[44:47], v139 offset:3072
	ds_read_b128 v[48:51], v139 offset:4096
	ds_read_b128 v[52:55], v139 offset:5120
	ds_read_b128 v[56:59], v139 offset:6144
	ds_read_b128 v[60:63], v139 offset:7168
	global_load_lds_dwordx4 v[64:65], off
	v_lshl_add_u64 v[64:65], s[68:69], 0, v[130:131]
	s_mov_b32 m0, s35
	s_nop 0
	global_load_lds_dwordx4 v[64:65], off
	s_waitcnt vmcnt(8)
	s_waitcnt lgkmcnt(0)
	s_barrier
	s_setprio 1
	s_waitcnt lgkmcnt(0)
	v_mfma_f32_16x16x32_bf16 v[64:67], v[0:3], v[32:35], 0
	v_mfma_f32_16x16x32_bf16 v[68:71], v[8:11], v[32:35], 0
	v_mfma_f32_16x16x32_bf16 v[72:75], v[0:3], v[40:43], 0
	v_mfma_f32_16x16x32_bf16 v[76:79], v[8:11], v[40:43], 0
	v_mfma_f32_16x16x32_bf16 v[80:83], v[0:3], v[48:51], 0
	v_mfma_f32_16x16x32_bf16 v[84:87], v[8:11], v[48:51], 0
	v_mfma_f32_16x16x32_bf16 v[88:91], v[0:3], v[56:59], 0
	v_mfma_f32_16x16x32_bf16 v[92:95], v[8:11], v[56:59], 0
	v_mfma_f32_16x16x32_bf16 v[64:67], v[4:7], v[36:39], v[64:67]
	v_mfma_f32_16x16x32_bf16 v[68:71], v[12:15], v[36:39], v[68:71]
	v_mfma_f32_16x16x32_bf16 v[72:75], v[4:7], v[44:47], v[72:75]
	v_mfma_f32_16x16x32_bf16 v[76:79], v[12:15], v[44:47], v[76:79]
	v_mfma_f32_16x16x32_bf16 v[80:83], v[4:7], v[52:55], v[80:83]
	v_mfma_f32_16x16x32_bf16 v[84:87], v[12:15], v[52:55], v[84:87]
	v_mfma_f32_16x16x32_bf16 v[88:91], v[4:7], v[60:63], v[88:91]
	v_mfma_f32_16x16x32_bf16 v[92:95], v[12:15], v[60:63], v[92:95]
	v_mfma_f32_16x16x32_bf16 v[96:99], v[16:19], v[32:35], 0
	v_mfma_f32_16x16x32_bf16 v[32:35], v[24:27], v[32:35], 0
	v_mfma_f32_16x16x32_bf16 v[96:99], v[20:23], v[36:39], v[96:99]
	v_mfma_f32_16x16x32_bf16 v[32:35], v[28:31], v[36:39], v[32:35]
	v_mfma_f32_16x16x32_bf16 v[36:39], v[16:19], v[40:43], 0
	v_mfma_f32_16x16x32_bf16 v[40:43], v[24:27], v[40:43], 0
	v_mfma_f32_16x16x32_bf16 v[36:39], v[20:23], v[44:47], v[36:39]
	v_mfma_f32_16x16x32_bf16 v[40:43], v[28:31], v[44:47], v[40:43]
	v_mfma_f32_16x16x32_bf16 v[44:47], v[16:19], v[48:51], 0
	v_mfma_f32_16x16x32_bf16 v[48:51], v[24:27], v[48:51], 0
	v_mfma_f32_16x16x32_bf16 v[44:47], v[20:23], v[52:55], v[44:47]
	v_mfma_f32_16x16x32_bf16 v[48:51], v[28:31], v[52:55], v[48:51]
	v_mfma_f32_16x16x32_bf16 v[52:55], v[16:19], v[56:59], 0
	v_mfma_f32_16x16x32_bf16 v[56:59], v[24:27], v[56:59], 0
	v_mfma_f32_16x16x32_bf16 v[52:55], v[20:23], v[60:63], v[52:55]
	v_mfma_f32_16x16x32_bf16 v[56:59], v[28:31], v[60:63], v[56:59]
	s_setprio 0
	s_barrier
	s_add_i32 s70, s70, s28
	v_lshl_add_u64 v[142:143], s[10:11], 0, v[140:141]
	s_mov_b64 s[2:3], 0x100
	s_add_i32 s53, s70, 0x2000
	v_lshl_add_u64 v[134:135], v[142:143], 0, s[2:3]
	s_mov_b32 m0, s70
	v_lshl_add_u64 v[144:145], s[10:11], 0, v[128:129]
	s_add_u32 s74, s10, 0x40100
	ds_read_b128 v[60:63], v139 offset:16384
	ds_read_b128 v[100:103], v139 offset:17408
	ds_read_b128 v[104:107], v139 offset:18432
	ds_read_b128 v[108:111], v139 offset:19456
	ds_read_b128 v[112:115], v139 offset:20480
	ds_read_b128 v[116:119], v139 offset:21504
	ds_read_b128 v[120:123], v139 offset:22528
	ds_read_b128 v[124:127], v139 offset:23552
	global_load_lds_dwordx4 v[134:135], off
	v_lshl_add_u64 v[134:135], v[144:145], 0, s[2:3]
	s_mov_b32 m0, s53
	s_addc_u32 s75, s11, 0
	s_add_i32 s68, s71, s28
	global_load_lds_dwordx4 v[134:135], off
	v_lshl_add_u64 v[134:135], s[74:75], 0, v[140:141]
	s_mov_b32 m0, s68
	s_add_i32 s69, s68, 0x2000
	global_load_lds_dwordx4 v[134:135], off
	v_lshl_add_u64 v[134:135], s[74:75], 0, v[128:129]
	s_mov_b32 m0, s69
	v_lshl_add_u64 v[146:147], s[8:9], 0, v[132:133]
	global_load_lds_dwordx4 v[134:135], off
	v_lshl_add_u64 v[134:135], v[146:147], 0, s[2:3]
	s_mov_b32 m0, s4
	v_lshl_add_u64 v[148:149], s[8:9], 0, v[130:131]
	global_load_lds_dwordx4 v[134:135], off
	v_lshl_add_u64 v[134:135], v[148:149], 0, s[2:3]
	s_mov_b32 m0, s5
	s_nop 0
	global_load_lds_dwordx4 v[134:135], off
	s_waitcnt vmcnt(8)
	s_waitcnt lgkmcnt(0)
	s_barrier
	s_setprio 1
	s_waitcnt lgkmcnt(0)
	v_mfma_f32_16x16x32_bf16 v[134:137], v[0:3], v[60:63], 0
	v_mfma_f32_16x16x32_bf16 v[162:165], v[0:3], v[104:107], 0
	v_mfma_f32_16x16x32_bf16 v[170:173], v[0:3], v[112:115], 0
	v_mfma_f32_16x16x32_bf16 v[0:3], v[0:3], v[120:123], 0
	v_mfma_f32_16x16x32_bf16 v[134:137], v[4:7], v[100:103], v[134:137]
	v_mfma_f32_16x16x32_bf16 v[162:165], v[4:7], v[108:111], v[162:165]
	v_mfma_f32_16x16x32_bf16 v[170:173], v[4:7], v[116:119], v[170:173]
	v_mfma_f32_16x16x32_bf16 v[0:3], v[4:7], v[124:127], v[0:3]
	v_mfma_f32_16x16x32_bf16 v[4:7], v[8:11], v[120:123], 0
	v_mfma_f32_16x16x32_bf16 v[158:161], v[8:11], v[60:63], 0
	v_mfma_f32_16x16x32_bf16 v[166:169], v[8:11], v[104:107], 0
	v_mfma_f32_16x16x32_bf16 v[174:177], v[8:11], v[112:115], 0
	v_mfma_f32_16x16x32_bf16 v[4:7], v[12:15], v[124:127], v[4:7]
	v_mfma_f32_16x16x32_bf16 v[158:161], v[12:15], v[100:103], v[158:161]
	v_mfma_f32_16x16x32_bf16 v[166:169], v[12:15], v[108:111], v[166:169]
	v_mfma_f32_16x16x32_bf16 v[174:177], v[12:15], v[116:119], v[174:177]
	v_mfma_f32_16x16x32_bf16 v[8:11], v[16:19], v[60:63], 0
	v_mfma_f32_16x16x32_bf16 v[12:15], v[24:27], v[60:63], 0
	v_mfma_f32_16x16x32_bf16 v[8:11], v[20:23], v[100:103], v[8:11]
	v_mfma_f32_16x16x32_bf16 v[12:15], v[28:31], v[100:103], v[12:15]
	v_mfma_f32_16x16x32_bf16 v[60:63], v[16:19], v[104:107], 0
	v_mfma_f32_16x16x32_bf16 v[100:103], v[24:27], v[104:107], 0
	v_mfma_f32_16x16x32_bf16 v[104:107], v[16:19], v[112:115], 0
	v_mfma_f32_16x16x32_bf16 v[16:19], v[16:19], v[120:123], 0
	v_mfma_f32_16x16x32_bf16 v[60:63], v[20:23], v[108:111], v[60:63]
	v_mfma_f32_16x16x32_bf16 v[100:103], v[28:31], v[108:111], v[100:103]
	v_mfma_f32_16x16x32_bf16 v[104:107], v[20:23], v[116:119], v[104:107]
	v_mfma_f32_16x16x32_bf16 v[108:111], v[24:27], v[112:115], 0
	v_mfma_f32_16x16x32_bf16 v[16:19], v[20:23], v[124:127], v[16:19]
	v_mfma_f32_16x16x32_bf16 v[20:23], v[24:27], v[120:123], 0
	v_mfma_f32_16x16x32_bf16 v[108:111], v[28:31], v[116:119], v[108:111]
	v_mfma_f32_16x16x32_bf16 v[20:23], v[28:31], v[124:127], v[20:23]
	s_setprio 0
	s_barrier
	s_add_i32 s73, 0, 0x18000
	s_add_i32 s76, 0, 0x1c000
	v_add_u32_e32 v154, s73, v138
	v_add_u32_e32 v155, s76, v138
	ds_read_b128 v[24:27], v154
	ds_read_b128 v[28:31], v154 offset:1024
	ds_read_b128 v[112:115], v154 offset:2048
	ds_read_b128 v[116:119], v154 offset:3072
	ds_read_b128 v[120:123], v155
	ds_read_b128 v[124:127], v155 offset:1024
	ds_read_b128 v[178:181], v155 offset:2048
	ds_read_b128 v[182:185], v155 offset:3072
	s_add_u32 s74, s8, 0x200100
	s_addc_u32 s75, s9, 0
	s_mov_b32 m0, s24
	v_lshl_add_u64 v[150:151], s[74:75], 0, v[132:133]
	ds_read_b128 v[206:209], v139 offset:32768
	ds_read_b128 v[210:213], v139 offset:33792
	ds_read_b128 v[214:217], v139 offset:34816
	ds_read_b128 v[218:221], v139 offset:35840
	ds_read_b128 v[222:225], v139 offset:36864
	ds_read_b128 v[226:229], v139 offset:37888
	ds_read_b128 v[230:233], v139 offset:38912
	ds_read_b128 v[234:237], v139 offset:39936
	global_load_lds_dwordx4 v[150:151], off
	v_lshl_add_u64 v[150:151], s[74:75], 0, v[130:131]
	s_mov_b32 m0, s29
	s_nop 0
	global_load_lds_dwordx4 v[150:151], off
	s_waitcnt vmcnt(8)
	s_waitcnt lgkmcnt(0)
	s_barrier
	s_setprio 1
	s_waitcnt lgkmcnt(0)
	v_mfma_f32_16x16x32_bf16 v[64:67], v[24:27], v[206:209], v[64:67]
	v_mfma_f32_16x16x32_bf16 v[68:71], v[112:115], v[206:209], v[68:71]
	v_mfma_f32_16x16x32_bf16 v[72:75], v[24:27], v[214:217], v[72:75]
	v_mfma_f32_16x16x32_bf16 v[76:79], v[112:115], v[214:217], v[76:79]
	v_mfma_f32_16x16x32_bf16 v[80:83], v[24:27], v[222:225], v[80:83]
	v_mfma_f32_16x16x32_bf16 v[84:87], v[112:115], v[222:225], v[84:87]
	v_mfma_f32_16x16x32_bf16 v[88:91], v[24:27], v[230:233], v[88:91]
	v_mfma_f32_16x16x32_bf16 v[92:95], v[112:115], v[230:233], v[92:95]
	v_mfma_f32_16x16x32_bf16 v[64:67], v[28:31], v[210:213], v[64:67]
	v_mfma_f32_16x16x32_bf16 v[68:71], v[116:119], v[210:213], v[68:71]
	v_mfma_f32_16x16x32_bf16 v[72:75], v[28:31], v[218:221], v[72:75]
	v_mfma_f32_16x16x32_bf16 v[76:79], v[116:119], v[218:221], v[76:79]
	v_mfma_f32_16x16x32_bf16 v[80:83], v[28:31], v[226:229], v[80:83]
	v_mfma_f32_16x16x32_bf16 v[84:87], v[116:119], v[226:229], v[84:87]
	v_mfma_f32_16x16x32_bf16 v[88:91], v[28:31], v[234:237], v[88:91]
	v_mfma_f32_16x16x32_bf16 v[92:95], v[116:119], v[234:237], v[92:95]
	v_mfma_f32_16x16x32_bf16 v[96:99], v[120:123], v[206:209], v[96:99]
	v_mfma_f32_16x16x32_bf16 v[32:35], v[178:181], v[206:209], v[32:35]
	v_mfma_f32_16x16x32_bf16 v[36:39], v[120:123], v[214:217], v[36:39]
	v_mfma_f32_16x16x32_bf16 v[40:43], v[178:181], v[214:217], v[40:43]
	v_mfma_f32_16x16x32_bf16 v[44:47], v[120:123], v[222:225], v[44:47]
	v_mfma_f32_16x16x32_bf16 v[48:51], v[178:181], v[222:225], v[48:51]
	v_mfma_f32_16x16x32_bf16 v[52:55], v[120:123], v[230:233], v[52:55]
	v_mfma_f32_16x16x32_bf16 v[56:59], v[178:181], v[230:233], v[56:59]
	v_mfma_f32_16x16x32_bf16 v[96:99], v[124:127], v[210:213], v[96:99]
	v_mfma_f32_16x16x32_bf16 v[32:35], v[182:185], v[210:213], v[32:35]
	v_mfma_f32_16x16x32_bf16 v[36:39], v[124:127], v[218:221], v[36:39]
	v_mfma_f32_16x16x32_bf16 v[40:43], v[182:185], v[218:221], v[40:43]
	v_mfma_f32_16x16x32_bf16 v[44:47], v[124:127], v[226:229], v[44:47]
	v_mfma_f32_16x16x32_bf16 v[48:51], v[182:185], v[226:229], v[48:51]
	v_mfma_f32_16x16x32_bf16 v[52:55], v[124:127], v[234:237], v[52:55]
	v_mfma_f32_16x16x32_bf16 v[56:59], v[182:185], v[234:237], v[56:59]
	s_setprio 0
	s_barrier
	s_add_i32 s73, s73, s28
	s_mov_b64 s[2:3], 0x180
	s_add_i32 s71, s73, 0x2000
	v_lshl_add_u64 v[142:143], v[142:143], 0, s[2:3]
	s_mov_b32 m0, s73
	s_add_u32 s74, s10, 0x40180
	ds_read_b128 v[206:209], v139 offset:49152
	ds_read_b128 v[210:213], v139 offset:50176
	ds_read_b128 v[214:217], v139 offset:51200
	ds_read_b128 v[218:221], v139 offset:52224
	ds_read_b128 v[222:225], v139 offset:53248
	ds_read_b128 v[226:229], v139 offset:54272
	ds_read_b128 v[230:233], v139 offset:55296
	ds_read_b128 v[234:237], v139 offset:56320
	global_load_lds_dwordx4 v[142:143], off
	v_lshl_add_u64 v[142:143], v[144:145], 0, s[2:3]
	s_mov_b32 m0, s71
	s_addc_u32 s75, s11, 0
	s_add_i32 s10, s76, s28
	global_load_lds_dwordx4 v[142:143], off
	v_lshl_add_u64 v[142:143], s[74:75], 0, v[140:141]
	s_mov_b32 m0, s10
	s_add_i32 s11, s10, 0x2000
	global_load_lds_dwordx4 v[142:143], off
	v_lshl_add_u64 v[142:143], s[74:75], 0, v[128:129]
	s_mov_b32 m0, s11
	s_nop 0
	global_load_lds_dwordx4 v[142:143], off
	v_lshl_add_u64 v[142:143], v[146:147], 0, s[2:3]
	s_mov_b32 m0, s38
	s_nop 0
	global_load_lds_dwordx4 v[142:143], off
	v_lshl_add_u64 v[142:143], v[148:149], 0, s[2:3]
	s_mov_b32 m0, s60
	s_nop 0
	global_load_lds_dwordx4 v[142:143], off
	s_waitcnt vmcnt(8)
	s_waitcnt lgkmcnt(0)
	s_barrier
	s_setprio 1
	s_waitcnt lgkmcnt(0)
	v_mfma_f32_16x16x32_bf16 v[0:3], v[24:27], v[230:233], v[0:3]
	v_mfma_f32_16x16x32_bf16 v[4:7], v[112:115], v[230:233], v[4:7]
	v_mfma_f32_16x16x32_bf16 v[134:137], v[24:27], v[206:209], v[134:137]
	v_mfma_f32_16x16x32_bf16 v[158:161], v[112:115], v[206:209], v[158:161]
	v_mfma_f32_16x16x32_bf16 v[162:165], v[24:27], v[214:217], v[162:165]
	v_mfma_f32_16x16x32_bf16 v[166:169], v[112:115], v[214:217], v[166:169]
	v_mfma_f32_16x16x32_bf16 v[170:173], v[24:27], v[222:225], v[170:173]
	v_mfma_f32_16x16x32_bf16 v[174:177], v[112:115], v[222:225], v[174:177]
	v_mfma_f32_16x16x32_bf16 v[0:3], v[28:31], v[234:237], v[0:3]
	v_mfma_f32_16x16x32_bf16 v[4:7], v[116:119], v[234:237], v[4:7]
	v_mfma_f32_16x16x32_bf16 v[134:137], v[28:31], v[210:213], v[134:137]
	v_mfma_f32_16x16x32_bf16 v[158:161], v[116:119], v[210:213], v[158:161]
	v_mfma_f32_16x16x32_bf16 v[162:165], v[28:31], v[218:221], v[162:165]
	v_mfma_f32_16x16x32_bf16 v[166:169], v[116:119], v[218:221], v[166:169]
	v_mfma_f32_16x16x32_bf16 v[170:173], v[28:31], v[226:229], v[170:173]
	v_mfma_f32_16x16x32_bf16 v[174:177], v[116:119], v[226:229], v[174:177]
	v_mfma_f32_16x16x32_bf16 v[8:11], v[120:123], v[206:209], v[8:11]
	v_mfma_f32_16x16x32_bf16 v[12:15], v[178:181], v[206:209], v[12:15]
	v_mfma_f32_16x16x32_bf16 v[24:27], v[120:123], v[214:217], v[60:63]
	v_mfma_f32_16x16x32_bf16 v[28:31], v[178:181], v[214:217], v[100:103]
	v_mfma_f32_16x16x32_bf16 v[60:63], v[120:123], v[222:225], v[104:107]
	v_mfma_f32_16x16x32_bf16 v[100:103], v[178:181], v[222:225], v[108:111]
	v_mfma_f32_16x16x32_bf16 v[16:19], v[120:123], v[230:233], v[16:19]
	v_mfma_f32_16x16x32_bf16 v[20:23], v[178:181], v[230:233], v[20:23]
	v_mfma_f32_16x16x32_bf16 v[8:11], v[124:127], v[210:213], v[8:11]
	v_mfma_f32_16x16x32_bf16 v[12:15], v[182:185], v[210:213], v[12:15]
	v_mfma_f32_16x16x32_bf16 v[24:27], v[124:127], v[218:221], v[24:27]
	v_mfma_f32_16x16x32_bf16 v[28:31], v[182:185], v[218:221], v[28:31]
	v_mfma_f32_16x16x32_bf16 v[60:63], v[124:127], v[226:229], v[60:63]
	v_mfma_f32_16x16x32_bf16 v[100:103], v[182:185], v[226:229], v[100:103]
	v_mfma_f32_16x16x32_bf16 v[16:19], v[124:127], v[234:237], v[16:19]
	v_mfma_f32_16x16x32_bf16 v[20:23], v[182:185], v[234:237], v[20:23]
	s_setprio 0
	s_barrier
	ds_read_b128 v[104:107], v152
	ds_read_b128 v[108:111], v152 offset:1024
	ds_read_b128 v[112:115], v152 offset:2048
	ds_read_b128 v[116:119], v152 offset:3072
	ds_read_b128 v[120:123], v153
	ds_read_b128 v[124:127], v153 offset:1024
	ds_read_b128 v[178:181], v153 offset:2048
	ds_read_b128 v[182:185], v153 offset:3072
	s_add_u32 s8, s8, 0x200180
	s_addc_u32 s9, s9, 0
	s_mov_b32 m0, s72
	v_lshl_add_u64 v[142:143], s[8:9], 0, v[132:133]
	ds_read_b128 v[206:209], v139
	ds_read_b128 v[210:213], v139 offset:1024
	ds_read_b128 v[214:217], v139 offset:2048
	ds_read_b128 v[218:221], v139 offset:3072
	ds_read_b128 v[222:225], v139 offset:4096
	ds_read_b128 v[226:229], v139 offset:5120
	ds_read_b128 v[230:233], v139 offset:6144
	ds_read_b128 v[234:237], v139 offset:7168
	global_load_lds_dwordx4 v[142:143], off
	v_lshl_add_u64 v[142:143], s[8:9], 0, v[130:131]
	s_mov_b32 m0, s35
	s_nop 0
	global_load_lds_dwordx4 v[142:143], off
	s_waitcnt vmcnt(8)
	s_waitcnt lgkmcnt(0)
	s_barrier
	s_setprio 1
	s_waitcnt lgkmcnt(0)
	v_mfma_f32_16x16x32_bf16 v[64:67], v[104:107], v[206:209], v[64:67]
	v_mfma_f32_16x16x32_bf16 v[68:71], v[112:115], v[206:209], v[68:71]
	v_mfma_f32_16x16x32_bf16 v[72:75], v[104:107], v[214:217], v[72:75]
	v_mfma_f32_16x16x32_bf16 v[76:79], v[112:115], v[214:217], v[76:79]
	v_mfma_f32_16x16x32_bf16 v[80:83], v[104:107], v[222:225], v[80:83]
	v_mfma_f32_16x16x32_bf16 v[84:87], v[112:115], v[222:225], v[84:87]
	v_mfma_f32_16x16x32_bf16 v[88:91], v[104:107], v[230:233], v[88:91]
	v_mfma_f32_16x16x32_bf16 v[64:67], v[108:111], v[210:213], v[64:67]
	v_mfma_f32_16x16x32_bf16 v[68:71], v[116:119], v[210:213], v[68:71]
	v_mfma_f32_16x16x32_bf16 v[72:75], v[108:111], v[218:221], v[72:75]
	v_mfma_f32_16x16x32_bf16 v[76:79], v[116:119], v[218:221], v[76:79]
	v_mfma_f32_16x16x32_bf16 v[80:83], v[108:111], v[226:229], v[80:83]
	v_mfma_f32_16x16x32_bf16 v[84:87], v[116:119], v[226:229], v[84:87]
	v_mfma_f32_16x16x32_bf16 v[238:241], v[108:111], v[234:237], v[88:91]
	v_mfma_f32_16x16x32_bf16 v[88:91], v[112:115], v[230:233], v[92:95]
	v_mfma_f32_16x16x32_bf16 v[242:245], v[116:119], v[234:237], v[88:91]
	v_mfma_f32_16x16x32_bf16 v[88:91], v[120:123], v[206:209], v[96:99]
	v_mfma_f32_16x16x32_bf16 v[32:35], v[178:181], v[206:209], v[32:35]
	v_mfma_f32_16x16x32_bf16 v[36:39], v[120:123], v[214:217], v[36:39]
	v_mfma_f32_16x16x32_bf16 v[40:43], v[178:181], v[214:217], v[40:43]
	v_mfma_f32_16x16x32_bf16 v[44:47], v[120:123], v[222:225], v[44:47]
	v_mfma_f32_16x16x32_bf16 v[48:51], v[178:181], v[222:225], v[48:51]
	v_mfma_f32_16x16x32_bf16 v[52:55], v[120:123], v[230:233], v[52:55]
	v_mfma_f32_16x16x32_bf16 v[56:59], v[178:181], v[230:233], v[56:59]
	v_mfma_f32_16x16x32_bf16 v[96:99], v[124:127], v[210:213], v[88:91]
	v_mfma_f32_16x16x32_bf16 v[32:35], v[182:185], v[210:213], v[32:35]
	v_mfma_f32_16x16x32_bf16 v[36:39], v[124:127], v[218:221], v[36:39]
	v_mfma_f32_16x16x32_bf16 v[40:43], v[182:185], v[218:221], v[40:43]
	v_mfma_f32_16x16x32_bf16 v[44:47], v[124:127], v[226:229], v[44:47]
	v_mfma_f32_16x16x32_bf16 v[48:51], v[182:185], v[226:229], v[48:51]
	v_mfma_f32_16x16x32_bf16 v[52:55], v[124:127], v[234:237], v[52:55]
	v_mfma_f32_16x16x32_bf16 v[56:59], v[182:185], v[234:237], v[56:59]
	s_setprio 0
	s_barrier
	s_mov_b32 m0, s70
	v_lshl_add_u64 v[190:191], s[12:13], 0, v[140:141]
	s_add_u32 s8, s12, 0x40000
	ds_read_b128 v[88:91], v139 offset:16384
	ds_read_b128 v[92:95], v139 offset:17408
	ds_read_b128 v[206:209], v139 offset:18432
	ds_read_b128 v[210:213], v139 offset:19456
	ds_read_b128 v[214:217], v139 offset:20480
	ds_read_b128 v[218:221], v139 offset:21504
	ds_read_b128 v[222:225], v139 offset:22528
	ds_read_b128 v[226:229], v139 offset:23552
	global_load_lds_dwordx4 v[190:191], off
	v_lshl_add_u64 v[192:193], s[12:13], 0, v[128:129]
	s_mov_b32 m0, s53
	s_addc_u32 s9, s13, 0
	global_load_lds_dwordx4 v[192:193], off
	v_lshl_add_u64 v[142:143], s[8:9], 0, v[140:141]
	s_mov_b32 m0, s68
	v_lshl_add_u64 v[194:195], s[58:59], 0, v[132:133]
	global_load_lds_dwordx4 v[142:143], off
	v_lshl_add_u64 v[142:143], s[8:9], 0, v[128:129]
	s_mov_b32 m0, s69
	v_lshl_add_u64 v[196:197], s[58:59], 0, v[130:131]
	global_load_lds_dwordx4 v[142:143], off
	s_mov_b32 m0, s4
	s_nop 0
	global_load_lds_dwordx4 v[194:195], off
	s_mov_b32 m0, s5
	s_nop 0
	global_load_lds_dwordx4 v[196:197], off
	s_waitcnt vmcnt(8)
	s_waitcnt lgkmcnt(0)
	s_barrier
	s_setprio 1
	s_waitcnt lgkmcnt(0)
	v_mfma_f32_16x16x32_bf16 v[0:3], v[104:107], v[222:225], v[0:3]
	v_mfma_f32_16x16x32_bf16 v[4:7], v[112:115], v[222:225], v[4:7]
	v_mfma_f32_16x16x32_bf16 v[134:137], v[104:107], v[88:91], v[134:137]
	v_mfma_f32_16x16x32_bf16 v[158:161], v[112:115], v[88:91], v[158:161]
	v_mfma_f32_16x16x32_bf16 v[162:165], v[104:107], v[206:209], v[162:165]
	v_mfma_f32_16x16x32_bf16 v[166:169], v[112:115], v[206:209], v[166:169]
	v_mfma_f32_16x16x32_bf16 v[170:173], v[104:107], v[214:217], v[170:173]
	v_mfma_f32_16x16x32_bf16 v[174:177], v[112:115], v[214:217], v[174:177]
	v_mfma_f32_16x16x32_bf16 v[0:3], v[108:111], v[226:229], v[0:3]
	v_mfma_f32_16x16x32_bf16 v[4:7], v[116:119], v[226:229], v[4:7]
	v_mfma_f32_16x16x32_bf16 v[134:137], v[108:111], v[92:95], v[134:137]
	v_mfma_f32_16x16x32_bf16 v[158:161], v[116:119], v[92:95], v[158:161]
	v_mfma_f32_16x16x32_bf16 v[162:165], v[108:111], v[210:213], v[162:165]
	v_mfma_f32_16x16x32_bf16 v[166:169], v[116:119], v[210:213], v[166:169]
	v_mfma_f32_16x16x32_bf16 v[170:173], v[108:111], v[218:221], v[170:173]
	v_mfma_f32_16x16x32_bf16 v[174:177], v[116:119], v[218:221], v[174:177]
	v_mfma_f32_16x16x32_bf16 v[8:11], v[120:123], v[88:91], v[8:11]
	v_mfma_f32_16x16x32_bf16 v[230:233], v[124:127], v[92:95], v[8:11]
	v_mfma_f32_16x16x32_bf16 v[8:11], v[178:181], v[88:91], v[12:15]
	v_mfma_f32_16x16x32_bf16 v[234:237], v[182:185], v[92:95], v[8:11]
	v_mfma_f32_16x16x32_bf16 v[8:11], v[120:123], v[206:209], v[24:27]
	v_mfma_f32_16x16x32_bf16 v[246:249], v[124:127], v[210:213], v[8:11]
	v_mfma_f32_16x16x32_bf16 v[8:11], v[178:181], v[206:209], v[28:31]
	v_mfma_f32_16x16x32_bf16 v[206:209], v[182:185], v[210:213], v[8:11]
	v_mfma_f32_16x16x32_bf16 v[8:11], v[120:123], v[214:217], v[60:63]
	v_mfma_f32_16x16x32_bf16 v[210:213], v[124:127], v[218:221], v[8:11]
	v_mfma_f32_16x16x32_bf16 v[8:11], v[178:181], v[214:217], v[100:103]
	v_mfma_f32_16x16x32_bf16 v[214:217], v[182:185], v[218:221], v[8:11]
	v_mfma_f32_16x16x32_bf16 v[8:11], v[120:123], v[222:225], v[16:19]
	v_mfma_f32_16x16x32_bf16 v[218:221], v[124:127], v[226:229], v[8:11]
	v_mfma_f32_16x16x32_bf16 v[8:11], v[178:181], v[222:225], v[20:23]
	v_mfma_f32_16x16x32_bf16 v[178:181], v[182:185], v[226:229], v[8:11]
	s_setprio 0
	s_barrier
	s_nop 4
	ds_read_b128 v[8:11], v154
	ds_read_b128 v[12:15], v154 offset:1024
	ds_read_b128 v[16:19], v154 offset:2048
	ds_read_b128 v[20:23], v154 offset:3072
	ds_read_b128 v[182:185], v155
	ds_read_b128 v[222:225], v155 offset:1024
	ds_read_b128 v[226:229], v155 offset:2048
	ds_read_b128 v[142:145], v155 offset:3072
	s_add_u32 s8, s58, 0x200000
	s_addc_u32 s9, s59, 0
	s_mov_b32 m0, s24
	v_lshl_add_u64 v[88:89], s[8:9], 0, v[132:133]
	ds_read_b128 v[24:27], v139 offset:32768
	ds_read_b128 v[28:31], v139 offset:33792
	ds_read_b128 v[60:63], v139 offset:34816
	ds_read_b128 v[146:149], v139 offset:35840
	ds_read_b128 v[150:153], v139 offset:36864
	ds_read_b128 v[154:157], v139 offset:37888
	ds_read_b128 v[200:203], v139 offset:38912
	ds_read_b128 v[186:189], v139 offset:39936
	global_load_lds_dwordx4 v[88:89], off
	v_lshl_add_u64 v[88:89], s[8:9], 0, v[130:131]
	s_mov_b32 m0, s29
	s_nop 0
	global_load_lds_dwordx4 v[88:89], off
	s_waitcnt vmcnt(8)
	s_waitcnt lgkmcnt(0)
	s_barrier
	s_setprio 1
	s_waitcnt lgkmcnt(0)
	v_mfma_f32_16x16x32_bf16 v[64:67], v[8:11], v[24:27], v[64:67]
	v_mfma_f32_16x16x32_bf16 v[124:127], v[12:15], v[28:31], v[64:67]
	v_mfma_f32_16x16x32_bf16 v[64:67], v[16:19], v[24:27], v[68:71]
	v_mfma_f32_16x16x32_bf16 v[120:123], v[20:23], v[28:31], v[64:67]
	v_mfma_f32_16x16x32_bf16 v[64:67], v[8:11], v[60:63], v[72:75]
	v_mfma_f32_16x16x32_bf16 v[108:111], v[12:15], v[146:149], v[64:67]
	v_mfma_f32_16x16x32_bf16 v[64:67], v[16:19], v[60:63], v[76:79]
	v_mfma_f32_16x16x32_bf16 v[104:107], v[20:23], v[146:149], v[64:67]
	v_mfma_f32_16x16x32_bf16 v[64:67], v[8:11], v[150:153], v[80:83]
	v_mfma_f32_16x16x32_bf16 v[92:95], v[12:15], v[154:157], v[64:67]
	v_mfma_f32_16x16x32_bf16 v[64:67], v[16:19], v[150:153], v[84:87]
	v_mfma_f32_16x16x32_bf16 v[88:91], v[20:23], v[154:157], v[64:67]
	v_mfma_f32_16x16x32_bf16 v[64:67], v[8:11], v[200:203], v[238:241]
	v_mfma_f32_16x16x32_bf16 v[68:71], v[12:15], v[186:189], v[64:67]
	v_mfma_f32_16x16x32_bf16 v[64:67], v[16:19], v[200:203], v[242:245]
	v_mfma_f32_16x16x32_bf16 v[64:67], v[20:23], v[186:189], v[64:67]
	v_mfma_f32_16x16x32_bf16 v[72:75], v[182:185], v[24:27], v[96:99]
	v_mfma_f32_16x16x32_bf16 v[24:27], v[226:229], v[24:27], v[32:35]
	v_mfma_f32_16x16x32_bf16 v[112:115], v[142:145], v[28:31], v[24:27]
	v_mfma_f32_16x16x32_bf16 v[24:27], v[182:185], v[60:63], v[36:39]
	v_mfma_f32_16x16x32_bf16 v[100:103], v[222:225], v[146:149], v[24:27]
	v_mfma_f32_16x16x32_bf16 v[24:27], v[226:229], v[60:63], v[40:43]
	v_mfma_f32_16x16x32_bf16 v[96:99], v[142:145], v[146:149], v[24:27]
	v_mfma_f32_16x16x32_bf16 v[24:27], v[182:185], v[150:153], v[44:47]
	v_mfma_f32_16x16x32_bf16 v[84:87], v[222:225], v[154:157], v[24:27]
	v_mfma_f32_16x16x32_bf16 v[24:27], v[226:229], v[150:153], v[48:51]
	v_mfma_f32_16x16x32_bf16 v[80:83], v[142:145], v[154:157], v[24:27]
	v_mfma_f32_16x16x32_bf16 v[24:27], v[182:185], v[200:203], v[52:55]
	v_mfma_f32_16x16x32_bf16 v[52:55], v[222:225], v[186:189], v[24:27]
	v_mfma_f32_16x16x32_bf16 v[24:27], v[226:229], v[200:203], v[56:59]
	v_mfma_f32_16x16x32_bf16 v[116:119], v[222:225], v[28:31], v[72:75]
	v_mfma_f32_16x16x32_bf16 v[48:51], v[142:145], v[186:189], v[24:27]
	s_setprio 0
	s_barrier
	s_mov_b32 m0, s73
	s_nop 2
	v_lshl_add_u64 v[24:25], v[190:191], 0, s[36:37]
	s_add_u32 s8, s12, 0x40080
	ds_read_b128 v[32:35], v139 offset:49152
	ds_read_b128 v[36:39], v139 offset:50176
	ds_read_b128 v[146:149], v139 offset:51200
	ds_read_b128 v[150:153], v139 offset:52224
	ds_read_b128 v[154:157], v139 offset:53248
	ds_read_b128 v[186:189], v139 offset:54272
	ds_read_b128 v[200:203], v139 offset:55296
	ds_read_b128 v[238:241], v139 offset:56320
	global_load_lds_dwordx4 v[24:25], off
	v_lshl_add_u64 v[24:25], v[192:193], 0, s[36:37]
	s_mov_b32 m0, s71
	s_addc_u32 s9, s13, 0
	global_load_lds_dwordx4 v[24:25], off
	v_lshl_add_u64 v[24:25], s[8:9], 0, v[140:141]
	s_mov_b32 m0, s10
	s_nop 0
	global_load_lds_dwordx4 v[24:25], off
	v_lshl_add_u64 v[24:25], s[8:9], 0, v[128:129]
	s_mov_b32 m0, s11
	s_nop 0
	global_load_lds_dwordx4 v[24:25], off
	v_lshl_add_u64 v[24:25], v[194:195], 0, s[36:37]
	s_mov_b32 m0, s38
	s_nop 0
	global_load_lds_dwordx4 v[24:25], off
	v_lshl_add_u64 v[24:25], v[196:197], 0, s[36:37]
	s_mov_b32 m0, s60
	s_nop 0
	global_load_lds_dwordx4 v[24:25], off
	s_waitcnt vmcnt(8)
	s_waitcnt lgkmcnt(0)
	s_barrier
	s_setprio 1
	s_waitcnt lgkmcnt(0)
	v_mfma_f32_16x16x32_bf16 v[24:27], v[8:11], v[32:35], v[134:137]
	v_mfma_f32_16x16x32_bf16 v[76:79], v[12:15], v[36:39], v[24:27]
	v_mfma_f32_16x16x32_bf16 v[24:27], v[16:19], v[32:35], v[158:161]
	v_mfma_f32_16x16x32_bf16 v[72:75], v[20:23], v[36:39], v[24:27]
	v_mfma_f32_16x16x32_bf16 v[24:27], v[8:11], v[146:149], v[162:165]
	v_mfma_f32_16x16x32_bf16 v[44:47], v[12:15], v[150:153], v[24:27]
	v_mfma_f32_16x16x32_bf16 v[24:27], v[16:19], v[146:149], v[166:169]
	v_mfma_f32_16x16x32_bf16 v[40:43], v[20:23], v[150:153], v[24:27]
	v_mfma_f32_16x16x32_bf16 v[24:27], v[8:11], v[154:157], v[170:173]
	v_mfma_f32_16x16x32_bf16 v[0:3], v[8:11], v[200:203], v[0:3]
	v_mfma_f32_16x16x32_bf16 v[28:31], v[12:15], v[186:189], v[24:27]
	v_mfma_f32_16x16x32_bf16 v[24:27], v[16:19], v[154:157], v[174:177]
	v_mfma_f32_16x16x32_bf16 v[12:15], v[12:15], v[238:241], v[0:3]
	v_mfma_f32_16x16x32_bf16 v[0:3], v[16:19], v[200:203], v[4:7]
	v_mfma_f32_16x16x32_bf16 v[24:27], v[20:23], v[186:189], v[24:27]
	v_mfma_f32_16x16x32_bf16 v[8:11], v[20:23], v[238:241], v[0:3]
	v_mfma_f32_16x16x32_bf16 v[0:3], v[182:185], v[32:35], v[230:233]
	v_mfma_f32_16x16x32_bf16 v[60:63], v[222:225], v[36:39], v[0:3]
	v_mfma_f32_16x16x32_bf16 v[0:3], v[226:229], v[32:35], v[234:237]
	v_mfma_f32_16x16x32_bf16 v[56:59], v[142:145], v[36:39], v[0:3]
	v_mfma_f32_16x16x32_bf16 v[0:3], v[182:185], v[146:149], v[246:249]
	v_mfma_f32_16x16x32_bf16 v[36:39], v[222:225], v[150:153], v[0:3]
	v_mfma_f32_16x16x32_bf16 v[0:3], v[226:229], v[146:149], v[206:209]
	v_mfma_f32_16x16x32_bf16 v[32:35], v[142:145], v[150:153], v[0:3]
	v_mfma_f32_16x16x32_bf16 v[0:3], v[182:185], v[154:157], v[210:213]
	v_mfma_f32_16x16x32_bf16 v[20:23], v[222:225], v[186:189], v[0:3]
	v_mfma_f32_16x16x32_bf16 v[0:3], v[226:229], v[154:157], v[214:217]
	v_mfma_f32_16x16x32_bf16 v[16:19], v[142:145], v[186:189], v[0:3]
	v_mfma_f32_16x16x32_bf16 v[0:3], v[182:185], v[200:203], v[218:221]
	v_mfma_f32_16x16x32_bf16 v[4:7], v[222:225], v[238:241], v[0:3]
	v_mfma_f32_16x16x32_bf16 v[0:3], v[226:229], v[200:203], v[178:181]
	v_mfma_f32_16x16x32_bf16 v[0:3], v[142:145], v[238:241], v[0:3]
	s_setprio 0
	s_barrier
	s_andn2_b64 vcc, exec, s[48:49]
	s_cbranch_vccnz .LBB0_678
	s_barrier

.LBB0_694:
	s_ashr_i32 s48, s54, 4
	s_ashr_i32 s47, s46, 31
	s_ashr_i32 s49, s48, 31
	s_lshl_b64 s[12:13], s[46:47], 19
	s_lshl_b64 s[50:51], s[48:49], 9
	s_add_u32 s12, s4, s12
	s_addc_u32 s13, s5, s13
	s_add_u32 s48, s12, s50
	s_addc_u32 s49, s13, s51
	s_and_b64 s[12:13], s[40:41], exec
	s_cselect_b32 s53, s49, s9
	s_cselect_b32 s52, s48, s8
	s_lshl_b32 s12, s54, 22
	s_and_b32 s12, s12, 0x3c00000
	s_add_u32 s12, s14, s12
	s_addc_u32 s13, s15, 0
	s_add_u32 s50, s12, s50
	s_addc_u32 s51, s13, s51
	s_and_b64 s[12:13], s[40:41], exec
	s_cselect_b32 s13, s51, s11
	s_cselect_b32 s12, s50, s10
	s_add_i32 s47, 0, 0x10000
	s_add_i32 s57, 0, 0x14000
	v_add_u32_e32 v140, s47, v138
	v_add_u32_e32 v198, s57, v138
	ds_read_b128 v[0:3], v140
	ds_read_b128 v[4:7], v140 offset:1024
	ds_read_b128 v[8:11], v140 offset:2048
	ds_read_b128 v[12:15], v140 offset:3072
	ds_read_b128 v[16:19], v198
	ds_read_b128 v[20:23], v198 offset:1024
	ds_read_b128 v[24:27], v198 offset:2048
	ds_read_b128 v[28:31], v198 offset:3072
	v_mov_b32_e32 v252, 0x358637bd
	s_add_u32 s58, s8, 0x40080
	s_addc_u32 s59, s9, 0
	s_add_i32 s61, s25, 0xc000
	v_lshl_add_u64 v[64:65], s[58:59], 0, v[134:135]
	s_mov_b32 m0, s61
	s_add_i32 s35, s25, 0xe000
	ds_read_b128 v[32:35], v139
	ds_read_b128 v[36:39], v139 offset:1024
	ds_read_b128 v[40:43], v139 offset:2048
	ds_read_b128 v[44:47], v139 offset:3072
	ds_read_b128 v[48:51], v139 offset:4096
	ds_read_b128 v[52:55], v139 offset:5120
	ds_read_b128 v[56:59], v139 offset:6144
	ds_read_b128 v[60:63], v139 offset:7168
	global_load_lds_dwordx4 v[64:65], off
	v_lshl_add_u64 v[64:65], s[58:59], 0, v[130:131]
	s_mov_b32 m0, s35
	s_nop 0
	global_load_lds_dwordx4 v[64:65], off
	s_waitcnt vmcnt(8)
	s_waitcnt lgkmcnt(0)
	s_barrier
	s_setprio 1
	s_waitcnt lgkmcnt(0)
	v_mfma_f32_16x16x32_bf16 v[64:67], v[0:3], v[32:35], 0
	v_mfma_f32_16x16x32_bf16 v[68:71], v[8:11], v[32:35], 0
	v_mfma_f32_16x16x32_bf16 v[72:75], v[0:3], v[40:43], 0
	v_mfma_f32_16x16x32_bf16 v[76:79], v[8:11], v[40:43], 0
	v_mfma_f32_16x16x32_bf16 v[80:83], v[0:3], v[48:51], 0
	v_mfma_f32_16x16x32_bf16 v[84:87], v[8:11], v[48:51], 0
	v_mfma_f32_16x16x32_bf16 v[88:91], v[0:3], v[56:59], 0
	v_mfma_f32_16x16x32_bf16 v[92:95], v[8:11], v[56:59], 0
	v_mfma_f32_16x16x32_bf16 v[64:67], v[4:7], v[36:39], v[64:67]
	v_mfma_f32_16x16x32_bf16 v[68:71], v[12:15], v[36:39], v[68:71]
	v_mfma_f32_16x16x32_bf16 v[72:75], v[4:7], v[44:47], v[72:75]
	v_mfma_f32_16x16x32_bf16 v[76:79], v[12:15], v[44:47], v[76:79]
	v_mfma_f32_16x16x32_bf16 v[80:83], v[4:7], v[52:55], v[80:83]
	v_mfma_f32_16x16x32_bf16 v[84:87], v[12:15], v[52:55], v[84:87]
	v_mfma_f32_16x16x32_bf16 v[88:91], v[4:7], v[60:63], v[88:91]
	v_mfma_f32_16x16x32_bf16 v[92:95], v[12:15], v[60:63], v[92:95]
	v_mfma_f32_16x16x32_bf16 v[96:99], v[16:19], v[32:35], 0
	v_mfma_f32_16x16x32_bf16 v[32:35], v[24:27], v[32:35], 0
	v_mfma_f32_16x16x32_bf16 v[96:99], v[20:23], v[36:39], v[96:99]
	v_mfma_f32_16x16x32_bf16 v[32:35], v[28:31], v[36:39], v[32:35]
	v_mfma_f32_16x16x32_bf16 v[36:39], v[16:19], v[40:43], 0
	v_mfma_f32_16x16x32_bf16 v[40:43], v[24:27], v[40:43], 0
	v_mfma_f32_16x16x32_bf16 v[36:39], v[20:23], v[44:47], v[36:39]
	v_mfma_f32_16x16x32_bf16 v[40:43], v[28:31], v[44:47], v[40:43]
	v_mfma_f32_16x16x32_bf16 v[44:47], v[16:19], v[48:51], 0
	v_mfma_f32_16x16x32_bf16 v[48:51], v[24:27], v[48:51], 0
	v_mfma_f32_16x16x32_bf16 v[44:47], v[20:23], v[52:55], v[44:47]
	v_mfma_f32_16x16x32_bf16 v[48:51], v[28:31], v[52:55], v[48:51]
	v_mfma_f32_16x16x32_bf16 v[52:55], v[16:19], v[56:59], 0
	v_mfma_f32_16x16x32_bf16 v[56:59], v[24:27], v[56:59], 0
	v_mfma_f32_16x16x32_bf16 v[52:55], v[20:23], v[60:63], v[52:55]
	v_mfma_f32_16x16x32_bf16 v[56:59], v[28:31], v[60:63], v[56:59]
	s_setprio 0
	s_barrier
	s_add_i32 s59, s47, s24
	v_lshl_add_u64 v[136:137], s[10:11], 0, v[132:133]
	s_mov_b64 s[68:69], 0x100
	s_add_i32 s47, s59, 0x2000
	v_lshl_add_u64 v[142:143], v[136:137], 0, s[68:69]
	s_mov_b32 m0, s59
	v_lshl_add_u64 v[190:191], s[10:11], 0, v[128:129]
	s_add_u32 s66, s10, 0x200100
	ds_read_b128 v[60:63], v139 offset:16384
	ds_read_b128 v[100:103], v139 offset:17408
	ds_read_b128 v[104:107], v139 offset:18432
	ds_read_b128 v[108:111], v139 offset:19456
	ds_read_b128 v[112:115], v139 offset:20480
	ds_read_b128 v[116:119], v139 offset:21504
	ds_read_b128 v[120:123], v139 offset:22528
	ds_read_b128 v[124:127], v139 offset:23552
	global_load_lds_dwordx4 v[142:143], off
	v_lshl_add_u64 v[142:143], v[190:191], 0, s[68:69]
	s_mov_b32 m0, s47
	s_addc_u32 s67, s11, 0
	s_add_i32 s57, s57, s24
	global_load_lds_dwordx4 v[142:143], off
	v_lshl_add_u64 v[142:143], s[66:67], 0, v[132:133]
	s_mov_b32 m0, s57
	s_add_i32 s58, s57, 0x2000
	global_load_lds_dwordx4 v[142:143], off
	v_lshl_add_u64 v[142:143], s[66:67], 0, v[128:129]
	s_mov_b32 m0, s58
	v_lshl_add_u64 v[192:193], s[8:9], 0, v[134:135]
	global_load_lds_dwordx4 v[142:143], off
	v_lshl_add_u64 v[142:143], v[192:193], 0, s[68:69]
	s_mov_b32 m0, s25
	v_lshl_add_u64 v[194:195], s[8:9], 0, v[130:131]
	global_load_lds_dwordx4 v[142:143], off
	v_lshl_add_u64 v[142:143], v[194:195], 0, s[68:69]
	s_mov_b32 m0, s26
	s_nop 0
	global_load_lds_dwordx4 v[142:143], off
	s_waitcnt vmcnt(8)
	s_waitcnt lgkmcnt(0)
	s_barrier
	s_setprio 1
	s_waitcnt lgkmcnt(0)
	v_mfma_f32_16x16x32_bf16 v[142:145], v[0:3], v[60:63], 0
	v_mfma_f32_16x16x32_bf16 v[150:153], v[0:3], v[104:107], 0
	v_mfma_f32_16x16x32_bf16 v[158:161], v[0:3], v[112:115], 0
	v_mfma_f32_16x16x32_bf16 v[0:3], v[0:3], v[120:123], 0
	v_mfma_f32_16x16x32_bf16 v[142:145], v[4:7], v[100:103], v[142:145]
	v_mfma_f32_16x16x32_bf16 v[150:153], v[4:7], v[108:111], v[150:153]
	v_mfma_f32_16x16x32_bf16 v[158:161], v[4:7], v[116:119], v[158:161]
	v_mfma_f32_16x16x32_bf16 v[0:3], v[4:7], v[124:127], v[0:3]
	v_mfma_f32_16x16x32_bf16 v[4:7], v[8:11], v[120:123], 0
	v_mfma_f32_16x16x32_bf16 v[146:149], v[8:11], v[60:63], 0
	v_mfma_f32_16x16x32_bf16 v[154:157], v[8:11], v[104:107], 0
	v_mfma_f32_16x16x32_bf16 v[162:165], v[8:11], v[112:115], 0
	v_mfma_f32_16x16x32_bf16 v[4:7], v[12:15], v[124:127], v[4:7]
	v_mfma_f32_16x16x32_bf16 v[146:149], v[12:15], v[100:103], v[146:149]
	v_mfma_f32_16x16x32_bf16 v[154:157], v[12:15], v[108:111], v[154:157]
	v_mfma_f32_16x16x32_bf16 v[162:165], v[12:15], v[116:119], v[162:165]
	v_mfma_f32_16x16x32_bf16 v[8:11], v[16:19], v[60:63], 0
	v_mfma_f32_16x16x32_bf16 v[12:15], v[24:27], v[60:63], 0
	v_mfma_f32_16x16x32_bf16 v[8:11], v[20:23], v[100:103], v[8:11]
	v_mfma_f32_16x16x32_bf16 v[12:15], v[28:31], v[100:103], v[12:15]
	v_mfma_f32_16x16x32_bf16 v[60:63], v[16:19], v[104:107], 0
	v_mfma_f32_16x16x32_bf16 v[100:103], v[24:27], v[104:107], 0
	v_mfma_f32_16x16x32_bf16 v[104:107], v[16:19], v[112:115], 0
	v_mfma_f32_16x16x32_bf16 v[16:19], v[16:19], v[120:123], 0
	v_mfma_f32_16x16x32_bf16 v[60:63], v[20:23], v[108:111], v[60:63]
	v_mfma_f32_16x16x32_bf16 v[100:103], v[28:31], v[108:111], v[100:103]
	v_mfma_f32_16x16x32_bf16 v[104:107], v[20:23], v[116:119], v[104:107]
	v_mfma_f32_16x16x32_bf16 v[108:111], v[24:27], v[112:115], 0
	v_mfma_f32_16x16x32_bf16 v[16:19], v[20:23], v[124:127], v[16:19]
	v_mfma_f32_16x16x32_bf16 v[20:23], v[24:27], v[120:123], 0
	v_mfma_f32_16x16x32_bf16 v[108:111], v[28:31], v[116:119], v[108:111]
	v_mfma_f32_16x16x32_bf16 v[20:23], v[28:31], v[124:127], v[20:23]
	s_setprio 0
	s_barrier
	s_add_i32 s60, 0, 0x18000
	s_add_i32 s70, 0, 0x1c000
	v_add_u32_e32 v230, s60, v138
	v_add_u32_e32 v238, s70, v138
	ds_read_b128 v[24:27], v230
	ds_read_b128 v[28:31], v230 offset:1024
	ds_read_b128 v[112:115], v230 offset:2048
	ds_read_b128 v[116:119], v230 offset:3072
	ds_read_b128 v[120:123], v238
	ds_read_b128 v[124:127], v238 offset:1024
	ds_read_b128 v[166:169], v238 offset:2048
	ds_read_b128 v[170:173], v238 offset:3072
	s_add_u32 s66, s8, 0x40100
	s_addc_u32 s67, s9, 0
	s_mov_b32 m0, s27
	v_lshl_add_u64 v[196:197], s[66:67], 0, v[134:135]
	ds_read_b128 v[174:177], v139 offset:32768
	ds_read_b128 v[178:181], v139 offset:33792
	ds_read_b128 v[182:185], v139 offset:34816
	ds_read_b128 v[186:189], v139 offset:35840
	ds_read_b128 v[200:203], v139 offset:36864
	ds_read_b128 v[206:209], v139 offset:37888
	ds_read_b128 v[210:213], v139 offset:38912
	ds_read_b128 v[214:217], v139 offset:39936
	global_load_lds_dwordx4 v[196:197], off
	v_lshl_add_u64 v[196:197], s[66:67], 0, v[130:131]
	s_mov_b32 m0, s28
	s_nop 0
	global_load_lds_dwordx4 v[196:197], off
	s_waitcnt vmcnt(8)
	s_waitcnt lgkmcnt(0)
	s_barrier
	s_setprio 1
	s_waitcnt lgkmcnt(0)
	v_mfma_f32_16x16x32_bf16 v[64:67], v[24:27], v[174:177], v[64:67]
	v_mfma_f32_16x16x32_bf16 v[68:71], v[112:115], v[174:177], v[68:71]
	v_mfma_f32_16x16x32_bf16 v[72:75], v[24:27], v[182:185], v[72:75]
	v_mfma_f32_16x16x32_bf16 v[76:79], v[112:115], v[182:185], v[76:79]
	v_mfma_f32_16x16x32_bf16 v[80:83], v[24:27], v[200:203], v[80:83]
	v_mfma_f32_16x16x32_bf16 v[84:87], v[112:115], v[200:203], v[84:87]
	v_mfma_f32_16x16x32_bf16 v[88:91], v[24:27], v[210:213], v[88:91]
	v_mfma_f32_16x16x32_bf16 v[92:95], v[112:115], v[210:213], v[92:95]
	v_mfma_f32_16x16x32_bf16 v[64:67], v[28:31], v[178:181], v[64:67]
	v_mfma_f32_16x16x32_bf16 v[68:71], v[116:119], v[178:181], v[68:71]
	v_mfma_f32_16x16x32_bf16 v[72:75], v[28:31], v[186:189], v[72:75]
	v_mfma_f32_16x16x32_bf16 v[76:79], v[116:119], v[186:189], v[76:79]
	v_mfma_f32_16x16x32_bf16 v[80:83], v[28:31], v[206:209], v[80:83]
	v_mfma_f32_16x16x32_bf16 v[84:87], v[116:119], v[206:209], v[84:87]
	v_mfma_f32_16x16x32_bf16 v[88:91], v[28:31], v[214:217], v[88:91]
	v_mfma_f32_16x16x32_bf16 v[92:95], v[116:119], v[214:217], v[92:95]
	v_mfma_f32_16x16x32_bf16 v[96:99], v[120:123], v[174:177], v[96:99]
	v_mfma_f32_16x16x32_bf16 v[32:35], v[166:169], v[174:177], v[32:35]
	v_mfma_f32_16x16x32_bf16 v[36:39], v[120:123], v[182:185], v[36:39]
	v_mfma_f32_16x16x32_bf16 v[40:43], v[166:169], v[182:185], v[40:43]
	v_mfma_f32_16x16x32_bf16 v[44:47], v[120:123], v[200:203], v[44:47]
	v_mfma_f32_16x16x32_bf16 v[48:51], v[166:169], v[200:203], v[48:51]
	v_mfma_f32_16x16x32_bf16 v[52:55], v[120:123], v[210:213], v[52:55]
	v_mfma_f32_16x16x32_bf16 v[56:59], v[166:169], v[210:213], v[56:59]
	v_mfma_f32_16x16x32_bf16 v[96:99], v[124:127], v[178:181], v[96:99]
	v_mfma_f32_16x16x32_bf16 v[32:35], v[170:173], v[178:181], v[32:35]
	v_mfma_f32_16x16x32_bf16 v[36:39], v[124:127], v[186:189], v[36:39]
	v_mfma_f32_16x16x32_bf16 v[40:43], v[170:173], v[186:189], v[40:43]
	v_mfma_f32_16x16x32_bf16 v[44:47], v[124:127], v[206:209], v[44:47]
	v_mfma_f32_16x16x32_bf16 v[48:51], v[170:173], v[206:209], v[48:51]
	v_mfma_f32_16x16x32_bf16 v[52:55], v[124:127], v[214:217], v[52:55]
	v_mfma_f32_16x16x32_bf16 v[56:59], v[170:173], v[214:217], v[56:59]
	s_setprio 0
	s_barrier
	s_add_i32 s66, s60, s24
	s_mov_b64 s[74:75], 0x180
	s_add_i32 s60, s66, 0x2000
	v_lshl_add_u64 v[136:137], v[136:137], 0, s[74:75]
	s_mov_b32 m0, s66
	s_add_u32 s68, s10, 0x200180
	ds_read_b128 v[174:177], v139 offset:49152
	ds_read_b128 v[178:181], v139 offset:50176
	ds_read_b128 v[182:185], v139 offset:51200
	ds_read_b128 v[186:189], v139 offset:52224
	ds_read_b128 v[200:203], v139 offset:53248
	ds_read_b128 v[206:209], v139 offset:54272
	ds_read_b128 v[210:213], v139 offset:55296
	ds_read_b128 v[214:217], v139 offset:56320
	global_load_lds_dwordx4 v[136:137], off
	v_lshl_add_u64 v[136:137], v[190:191], 0, s[74:75]
	s_mov_b32 m0, s60
	s_addc_u32 s69, s11, 0
	s_add_i32 s10, s70, s24
	global_load_lds_dwordx4 v[136:137], off
	v_lshl_add_u64 v[136:137], s[68:69], 0, v[132:133]
	s_mov_b32 m0, s10
	s_add_i32 s11, s10, 0x2000
	global_load_lds_dwordx4 v[136:137], off
	v_lshl_add_u64 v[136:137], s[68:69], 0, v[128:129]
	s_mov_b32 m0, s11
	s_nop 0
	global_load_lds_dwordx4 v[136:137], off
	v_lshl_add_u64 v[136:137], v[192:193], 0, s[74:75]
	s_mov_b32 m0, s29
	s_nop 0
	global_load_lds_dwordx4 v[136:137], off
	v_lshl_add_u64 v[136:137], v[194:195], 0, s[74:75]
	s_mov_b32 m0, s38
	s_nop 0
	global_load_lds_dwordx4 v[136:137], off
	s_waitcnt vmcnt(8)
	s_waitcnt lgkmcnt(0)
	s_barrier
	s_setprio 1
	s_waitcnt lgkmcnt(0)
	v_mfma_f32_16x16x32_bf16 v[0:3], v[24:27], v[210:213], v[0:3]
	v_mfma_f32_16x16x32_bf16 v[4:7], v[112:115], v[210:213], v[4:7]
	v_mfma_f32_16x16x32_bf16 v[142:145], v[24:27], v[174:177], v[142:145]
	v_mfma_f32_16x16x32_bf16 v[146:149], v[112:115], v[174:177], v[146:149]
	v_mfma_f32_16x16x32_bf16 v[150:153], v[24:27], v[182:185], v[150:153]
	v_mfma_f32_16x16x32_bf16 v[154:157], v[112:115], v[182:185], v[154:157]
	v_mfma_f32_16x16x32_bf16 v[158:161], v[24:27], v[200:203], v[158:161]
	v_mfma_f32_16x16x32_bf16 v[162:165], v[112:115], v[200:203], v[162:165]
	v_mfma_f32_16x16x32_bf16 v[0:3], v[28:31], v[214:217], v[0:3]
	v_mfma_f32_16x16x32_bf16 v[4:7], v[116:119], v[214:217], v[4:7]
	v_mfma_f32_16x16x32_bf16 v[142:145], v[28:31], v[178:181], v[142:145]
	v_mfma_f32_16x16x32_bf16 v[146:149], v[116:119], v[178:181], v[146:149]
	v_mfma_f32_16x16x32_bf16 v[150:153], v[28:31], v[186:189], v[150:153]
	v_mfma_f32_16x16x32_bf16 v[154:157], v[116:119], v[186:189], v[154:157]
	v_mfma_f32_16x16x32_bf16 v[158:161], v[28:31], v[206:209], v[158:161]
	v_mfma_f32_16x16x32_bf16 v[162:165], v[116:119], v[206:209], v[162:165]
	v_mfma_f32_16x16x32_bf16 v[8:11], v[120:123], v[174:177], v[8:11]
	v_mfma_f32_16x16x32_bf16 v[12:15], v[166:169], v[174:177], v[12:15]
	v_mfma_f32_16x16x32_bf16 v[24:27], v[120:123], v[182:185], v[60:63]
	v_mfma_f32_16x16x32_bf16 v[28:31], v[166:169], v[182:185], v[100:103]
	v_mfma_f32_16x16x32_bf16 v[60:63], v[120:123], v[200:203], v[104:107]
	v_mfma_f32_16x16x32_bf16 v[100:103], v[166:169], v[200:203], v[108:111]
	v_mfma_f32_16x16x32_bf16 v[16:19], v[120:123], v[210:213], v[16:19]
	v_mfma_f32_16x16x32_bf16 v[20:23], v[166:169], v[210:213], v[20:23]
	v_mfma_f32_16x16x32_bf16 v[8:11], v[124:127], v[178:181], v[8:11]
	v_mfma_f32_16x16x32_bf16 v[12:15], v[170:173], v[178:181], v[12:15]
	v_mfma_f32_16x16x32_bf16 v[24:27], v[124:127], v[186:189], v[24:27]
	v_mfma_f32_16x16x32_bf16 v[28:31], v[170:173], v[186:189], v[28:31]
	v_mfma_f32_16x16x32_bf16 v[60:63], v[124:127], v[206:209], v[60:63]
	v_mfma_f32_16x16x32_bf16 v[100:103], v[170:173], v[206:209], v[100:103]
	v_mfma_f32_16x16x32_bf16 v[16:19], v[124:127], v[214:217], v[16:19]
	v_mfma_f32_16x16x32_bf16 v[20:23], v[170:173], v[214:217], v[20:23]
	s_setprio 0
	s_barrier
	ds_read_b128 v[104:107], v140
	ds_read_b128 v[108:111], v140 offset:1024
	ds_read_b128 v[112:115], v140 offset:2048
	ds_read_b128 v[116:119], v140 offset:3072
	ds_read_b128 v[120:123], v198
	ds_read_b128 v[124:127], v198 offset:1024
	ds_read_b128 v[166:169], v198 offset:2048
	ds_read_b128 v[170:173], v198 offset:3072
	s_add_u32 s8, s8, 0x40180
	s_addc_u32 s9, s9, 0
	s_mov_b32 m0, s61
	v_lshl_add_u64 v[136:137], s[8:9], 0, v[134:135]
	ds_read_b128 v[174:177], v139
	ds_read_b128 v[178:181], v139 offset:1024
	ds_read_b128 v[182:185], v139 offset:2048
	ds_read_b128 v[186:189], v139 offset:3072
	ds_read_b128 v[200:203], v139 offset:4096
	ds_read_b128 v[206:209], v139 offset:5120
	ds_read_b128 v[210:213], v139 offset:6144
	ds_read_b128 v[214:217], v139 offset:7168
	global_load_lds_dwordx4 v[136:137], off
	v_lshl_add_u64 v[136:137], s[8:9], 0, v[130:131]
	s_mov_b32 m0, s35
	s_nop 0
	global_load_lds_dwordx4 v[136:137], off
	s_waitcnt vmcnt(8)
	s_waitcnt lgkmcnt(0)
	s_barrier
	s_setprio 1
	s_waitcnt lgkmcnt(0)
	v_mfma_f32_16x16x32_bf16 v[88:91], v[104:107], v[210:213], v[88:91]
	v_mfma_f32_16x16x32_bf16 v[64:67], v[104:107], v[174:177], v[64:67]
	v_mfma_f32_16x16x32_bf16 v[68:71], v[112:115], v[174:177], v[68:71]
	v_mfma_f32_16x16x32_bf16 v[72:75], v[104:107], v[182:185], v[72:75]
	v_mfma_f32_16x16x32_bf16 v[76:79], v[112:115], v[182:185], v[76:79]
	v_mfma_f32_16x16x32_bf16 v[80:83], v[104:107], v[200:203], v[80:83]
	v_mfma_f32_16x16x32_bf16 v[84:87], v[112:115], v[200:203], v[84:87]
	v_mfma_f32_16x16x32_bf16 v[218:221], v[108:111], v[214:217], v[88:91]
	v_mfma_f32_16x16x32_bf16 v[88:91], v[112:115], v[210:213], v[92:95]
	v_mfma_f32_16x16x32_bf16 v[64:67], v[108:111], v[178:181], v[64:67]
	v_mfma_f32_16x16x32_bf16 v[68:71], v[116:119], v[178:181], v[68:71]
	v_mfma_f32_16x16x32_bf16 v[72:75], v[108:111], v[186:189], v[72:75]
	v_mfma_f32_16x16x32_bf16 v[76:79], v[116:119], v[186:189], v[76:79]
	v_mfma_f32_16x16x32_bf16 v[80:83], v[108:111], v[206:209], v[80:83]
	v_mfma_f32_16x16x32_bf16 v[84:87], v[116:119], v[206:209], v[84:87]
	v_mfma_f32_16x16x32_bf16 v[92:95], v[116:119], v[214:217], v[88:91]
	v_mfma_f32_16x16x32_bf16 v[48:51], v[166:169], v[200:203], v[48:51]
	v_mfma_f32_16x16x32_bf16 v[88:91], v[120:123], v[174:177], v[96:99]
	v_mfma_f32_16x16x32_bf16 v[32:35], v[166:169], v[174:177], v[32:35]
	v_mfma_f32_16x16x32_bf16 v[36:39], v[120:123], v[182:185], v[36:39]
	v_mfma_f32_16x16x32_bf16 v[40:43], v[166:169], v[182:185], v[40:43]
	v_mfma_f32_16x16x32_bf16 v[44:47], v[120:123], v[200:203], v[44:47]
	v_mfma_f32_16x16x32_bf16 v[174:177], v[170:173], v[206:209], v[48:51]
	v_mfma_f32_16x16x32_bf16 v[48:51], v[120:123], v[210:213], v[52:55]
	v_mfma_f32_16x16x32_bf16 v[32:35], v[170:173], v[178:181], v[32:35]
	v_mfma_f32_16x16x32_bf16 v[36:39], v[124:127], v[186:189], v[36:39]
	v_mfma_f32_16x16x32_bf16 v[40:43], v[170:173], v[186:189], v[40:43]
	v_mfma_f32_16x16x32_bf16 v[44:47], v[124:127], v[206:209], v[44:47]
	v_mfma_f32_16x16x32_bf16 v[52:55], v[124:127], v[214:217], v[48:51]
	v_mfma_f32_16x16x32_bf16 v[48:51], v[166:169], v[210:213], v[56:59]
	v_mfma_f32_16x16x32_bf16 v[222:225], v[124:127], v[178:181], v[88:91]
	v_mfma_f32_16x16x32_bf16 v[178:181], v[170:173], v[214:217], v[48:51]
	s_setprio 0
	s_barrier
	s_mov_b32 m0, s59
	v_lshl_add_u64 v[136:137], s[12:13], 0, v[132:133]
	s_add_u32 s8, s12, 0x200000
	s_nop 0
	ds_read_b128 v[48:51], v139 offset:16384
	ds_read_b128 v[56:59], v139 offset:17408
	ds_read_b128 v[88:91], v139 offset:18432
	ds_read_b128 v[96:99], v139 offset:19456
	ds_read_b128 v[182:185], v139 offset:20480
	ds_read_b128 v[186:189], v139 offset:21504
	ds_read_b128 v[200:203], v139 offset:22528
	ds_read_b128 v[206:209], v139 offset:23552
	global_load_lds_dwordx4 v[136:137], off
	v_lshl_add_u64 v[204:205], s[12:13], 0, v[128:129]
	s_mov_b32 m0, s47
	s_addc_u32 s9, s13, 0
	global_load_lds_dwordx4 v[204:205], off
	v_lshl_add_u64 v[190:191], s[8:9], 0, v[132:133]
	s_mov_b32 m0, s57
	v_lshl_add_u64 v[250:251], s[52:53], 0, v[134:135]
	global_load_lds_dwordx4 v[190:191], off
	v_lshl_add_u64 v[190:191], s[8:9], 0, v[128:129]
	s_mov_b32 m0, s58
	v_lshl_add_u64 v[198:199], s[52:53], 0, v[130:131]
	global_load_lds_dwordx4 v[190:191], off
	s_mov_b32 m0, s25
	s_nop 0
	global_load_lds_dwordx4 v[250:251], off
	s_mov_b32 m0, s26
	s_nop 0
	global_load_lds_dwordx4 v[198:199], off
	s_waitcnt vmcnt(8)
	s_waitcnt lgkmcnt(0)
	s_barrier
	s_setprio 1
	s_waitcnt lgkmcnt(0)
	v_mfma_f32_16x16x32_bf16 v[0:3], v[104:107], v[200:203], v[0:3]
	v_mfma_f32_16x16x32_bf16 v[4:7], v[112:115], v[200:203], v[4:7]
	v_mfma_f32_16x16x32_bf16 v[142:145], v[104:107], v[48:51], v[142:145]
	v_mfma_f32_16x16x32_bf16 v[146:149], v[112:115], v[48:51], v[146:149]
	v_mfma_f32_16x16x32_bf16 v[150:153], v[104:107], v[88:91], v[150:153]
	v_mfma_f32_16x16x32_bf16 v[154:157], v[112:115], v[88:91], v[154:157]
	v_mfma_f32_16x16x32_bf16 v[158:161], v[104:107], v[182:185], v[158:161]
	v_mfma_f32_16x16x32_bf16 v[162:165], v[112:115], v[182:185], v[162:165]
	v_mfma_f32_16x16x32_bf16 v[0:3], v[108:111], v[206:209], v[0:3]
	v_mfma_f32_16x16x32_bf16 v[4:7], v[116:119], v[206:209], v[4:7]
	v_mfma_f32_16x16x32_bf16 v[142:145], v[108:111], v[56:59], v[142:145]
	v_mfma_f32_16x16x32_bf16 v[146:149], v[116:119], v[56:59], v[146:149]
	v_mfma_f32_16x16x32_bf16 v[150:153], v[108:111], v[96:99], v[150:153]
	v_mfma_f32_16x16x32_bf16 v[154:157], v[116:119], v[96:99], v[154:157]
	v_mfma_f32_16x16x32_bf16 v[158:161], v[108:111], v[186:189], v[158:161]
	v_mfma_f32_16x16x32_bf16 v[162:165], v[116:119], v[186:189], v[162:165]
	v_mfma_f32_16x16x32_bf16 v[12:15], v[166:169], v[48:51], v[12:15]
	v_mfma_f32_16x16x32_bf16 v[210:213], v[170:173], v[56:59], v[12:15]
	v_mfma_f32_16x16x32_bf16 v[12:15], v[120:123], v[88:91], v[24:27]
	v_mfma_f32_16x16x32_bf16 v[24:27], v[124:127], v[96:99], v[12:15]
	v_mfma_f32_16x16x32_bf16 v[12:15], v[166:169], v[88:91], v[28:31]
	v_mfma_f32_16x16x32_bf16 v[214:217], v[170:173], v[96:99], v[12:15]
	v_mfma_f32_16x16x32_bf16 v[12:15], v[120:123], v[182:185], v[60:63]
	v_mfma_f32_16x16x32_bf16 v[226:229], v[124:127], v[186:189], v[12:15]
	v_mfma_f32_16x16x32_bf16 v[12:15], v[166:169], v[182:185], v[100:103]
	v_mfma_f32_16x16x32_bf16 v[8:11], v[120:123], v[48:51], v[8:11]
	v_mfma_f32_16x16x32_bf16 v[182:185], v[170:173], v[186:189], v[12:15]
	v_mfma_f32_16x16x32_bf16 v[12:15], v[120:123], v[200:203], v[16:19]
	v_mfma_f32_16x16x32_bf16 v[8:11], v[124:127], v[56:59], v[8:11]
	v_mfma_f32_16x16x32_bf16 v[186:189], v[124:127], v[206:209], v[12:15]
	v_mfma_f32_16x16x32_bf16 v[12:15], v[166:169], v[200:203], v[20:23]
	v_mfma_f32_16x16x32_bf16 v[166:169], v[170:173], v[206:209], v[12:15]
	s_setprio 0
	s_barrier
	s_nop 4
	ds_read_b128 v[12:15], v230
	ds_read_b128 v[16:19], v230 offset:1024
	ds_read_b128 v[170:173], v230 offset:2048
	ds_read_b128 v[200:203], v230 offset:3072
	ds_read_b128 v[206:209], v238
	ds_read_b128 v[230:233], v238 offset:1024
	ds_read_b128 v[234:237], v238 offset:2048
	ds_read_b128 v[238:241], v238 offset:3072
	s_add_u32 s8, s52, 0x40000
	s_addc_u32 s9, s53, 0
	s_mov_b32 m0, s27
	v_lshl_add_u64 v[48:49], s[8:9], 0, v[134:135]
	ds_read_b128 v[20:23], v139 offset:32768
	ds_read_b128 v[28:31], v139 offset:33792
	ds_read_b128 v[60:63], v139 offset:34816
	ds_read_b128 v[100:103], v139 offset:35840
	ds_read_b128 v[242:245], v139 offset:36864
	ds_read_b128 v[246:249], v139 offset:37888
	ds_read_b128 v[190:193], v139 offset:38912
	ds_read_b128 v[194:197], v139 offset:39936
	global_load_lds_dwordx4 v[48:49], off
	v_lshl_add_u64 v[48:49], s[8:9], 0, v[130:131]
	s_mov_b32 m0, s28
	s_nop 0
	global_load_lds_dwordx4 v[48:49], off
	s_waitcnt vmcnt(8)
	s_waitcnt lgkmcnt(0)
	s_barrier
	s_setprio 1
	s_waitcnt lgkmcnt(0)
	v_mfma_f32_16x16x32_bf16 v[48:51], v[12:15], v[20:23], v[64:67]
	v_mfma_f32_16x16x32_bf16 v[120:123], v[16:19], v[28:31], v[48:51]
	v_mfma_f32_16x16x32_bf16 v[48:51], v[170:173], v[20:23], v[68:71]
	v_mfma_f32_16x16x32_bf16 v[112:115], v[200:203], v[28:31], v[48:51]
	v_mfma_f32_16x16x32_bf16 v[48:51], v[12:15], v[60:63], v[72:75]
	v_mfma_f32_16x16x32_bf16 v[104:107], v[16:19], v[100:103], v[48:51]
	v_mfma_f32_16x16x32_bf16 v[48:51], v[170:173], v[60:63], v[76:79]
	v_mfma_f32_16x16x32_bf16 v[96:99], v[200:203], v[100:103], v[48:51]
	v_mfma_f32_16x16x32_bf16 v[48:51], v[12:15], v[242:245], v[80:83]
	v_mfma_f32_16x16x32_bf16 v[88:91], v[16:19], v[246:249], v[48:51]
	v_mfma_f32_16x16x32_bf16 v[48:51], v[170:173], v[242:245], v[84:87]
	v_mfma_f32_16x16x32_bf16 v[80:83], v[200:203], v[246:249], v[48:51]
	v_mfma_f32_16x16x32_bf16 v[48:51], v[12:15], v[190:193], v[218:221]
	v_mfma_f32_16x16x32_bf16 v[56:59], v[16:19], v[194:197], v[48:51]
	v_mfma_f32_16x16x32_bf16 v[48:51], v[170:173], v[190:193], v[92:95]
	v_mfma_f32_16x16x32_bf16 v[48:51], v[200:203], v[194:197], v[48:51]
	v_mfma_f32_16x16x32_bf16 v[64:67], v[206:209], v[20:23], v[222:225]
	v_mfma_f32_16x16x32_bf16 v[20:23], v[234:237], v[20:23], v[32:35]
	v_mfma_f32_16x16x32_bf16 v[116:119], v[238:241], v[28:31], v[20:23]
	v_mfma_f32_16x16x32_bf16 v[20:23], v[206:209], v[60:63], v[36:39]
	v_mfma_f32_16x16x32_bf16 v[108:111], v[230:233], v[100:103], v[20:23]
	v_mfma_f32_16x16x32_bf16 v[20:23], v[234:237], v[60:63], v[40:43]
	v_mfma_f32_16x16x32_bf16 v[100:103], v[238:241], v[100:103], v[20:23]
	v_mfma_f32_16x16x32_bf16 v[20:23], v[206:209], v[242:245], v[44:47]
	v_mfma_f32_16x16x32_bf16 v[92:95], v[230:233], v[246:249], v[20:23]
	v_mfma_f32_16x16x32_bf16 v[20:23], v[234:237], v[242:245], v[174:177]
	v_mfma_f32_16x16x32_bf16 v[84:87], v[238:241], v[246:249], v[20:23]
	v_mfma_f32_16x16x32_bf16 v[20:23], v[206:209], v[190:193], v[52:55]
	v_mfma_f32_16x16x32_bf16 v[60:63], v[230:233], v[194:197], v[20:23]
	v_mfma_f32_16x16x32_bf16 v[20:23], v[234:237], v[190:193], v[178:181]
	v_mfma_f32_16x16x32_bf16 v[124:127], v[230:233], v[28:31], v[64:67]
	v_mfma_f32_16x16x32_bf16 v[52:55], v[238:241], v[194:197], v[20:23]
	s_setprio 0
	s_barrier
	s_mov_b32 m0, s66
	s_nop 2
	v_lshl_add_u64 v[20:21], v[136:137], 0, s[36:37]
	s_add_u32 s8, s12, 0x200080
	ds_read_b128 v[32:35], v139 offset:49152
	ds_read_b128 v[40:43], v139 offset:50176
	ds_read_b128 v[174:177], v139 offset:51200
	ds_read_b128 v[178:181], v139 offset:52224
	ds_read_b128 v[190:193], v139 offset:53248
	ds_read_b128 v[194:197], v139 offset:54272
	ds_read_b128 v[218:221], v139 offset:55296
	ds_read_b128 v[222:225], v139 offset:56320
	global_load_lds_dwordx4 v[20:21], off
	v_lshl_add_u64 v[20:21], v[204:205], 0, s[36:37]
	s_mov_b32 m0, s60
	s_addc_u32 s9, s13, 0
	global_load_lds_dwordx4 v[20:21], off
	v_lshl_add_u64 v[20:21], s[8:9], 0, v[132:133]
	s_mov_b32 m0, s10
	s_nop 0
	global_load_lds_dwordx4 v[20:21], off
	v_lshl_add_u64 v[20:21], s[8:9], 0, v[128:129]
	s_mov_b32 m0, s11
	s_nop 0
	global_load_lds_dwordx4 v[20:21], off
	v_lshl_add_u64 v[20:21], v[250:251], 0, s[36:37]
	s_mov_b32 m0, s29
	s_nop 0
	global_load_lds_dwordx4 v[20:21], off
	v_lshl_add_u64 v[20:21], v[198:199], 0, s[36:37]
	s_mov_b32 m0, s38
	s_nop 0
	global_load_lds_dwordx4 v[20:21], off
	s_waitcnt vmcnt(8)
	s_waitcnt lgkmcnt(0)
	s_barrier
	s_setprio 1
	s_waitcnt lgkmcnt(0)
	v_mfma_f32_16x16x32_bf16 v[20:23], v[12:15], v[32:35], v[142:145]
	v_mfma_f32_16x16x32_bf16 v[76:79], v[16:19], v[40:43], v[20:23]
	v_mfma_f32_16x16x32_bf16 v[20:23], v[170:173], v[32:35], v[146:149]
	v_mfma_f32_16x16x32_bf16 v[68:71], v[200:203], v[40:43], v[20:23]
	v_mfma_f32_16x16x32_bf16 v[20:23], v[12:15], v[174:177], v[150:153]
	v_mfma_f32_16x16x32_bf16 v[44:47], v[16:19], v[178:181], v[20:23]
	v_mfma_f32_16x16x32_bf16 v[20:23], v[170:173], v[174:177], v[154:157]
	v_mfma_f32_16x16x32_bf16 v[36:39], v[200:203], v[178:181], v[20:23]
	v_mfma_f32_16x16x32_bf16 v[20:23], v[12:15], v[190:193], v[158:161]
	v_mfma_f32_16x16x32_bf16 v[0:3], v[12:15], v[218:221], v[0:3]
	v_mfma_f32_16x16x32_bf16 v[28:31], v[16:19], v[194:197], v[20:23]
	v_mfma_f32_16x16x32_bf16 v[20:23], v[170:173], v[190:193], v[162:165]
	v_mfma_f32_16x16x32_bf16 v[12:15], v[16:19], v[222:225], v[0:3]
	v_mfma_f32_16x16x32_bf16 v[0:3], v[170:173], v[218:221], v[4:7]
	v_mfma_f32_16x16x32_bf16 v[20:23], v[200:203], v[194:197], v[20:23]
	v_mfma_f32_16x16x32_bf16 v[4:7], v[200:203], v[222:225], v[0:3]
	v_mfma_f32_16x16x32_bf16 v[0:3], v[206:209], v[32:35], v[8:11]
	v_mfma_f32_16x16x32_bf16 v[72:75], v[230:233], v[40:43], v[0:3]
	v_mfma_f32_16x16x32_bf16 v[0:3], v[234:237], v[32:35], v[210:213]
	v_mfma_f32_16x16x32_bf16 v[64:67], v[238:241], v[40:43], v[0:3]
	v_mfma_f32_16x16x32_bf16 v[0:3], v[206:209], v[174:177], v[24:27]
	v_mfma_f32_16x16x32_bf16 v[40:43], v[230:233], v[178:181], v[0:3]
	v_mfma_f32_16x16x32_bf16 v[0:3], v[234:237], v[174:177], v[214:217]
	v_mfma_f32_16x16x32_bf16 v[32:35], v[238:241], v[178:181], v[0:3]
	v_mfma_f32_16x16x32_bf16 v[0:3], v[206:209], v[190:193], v[226:229]
	v_mfma_f32_16x16x32_bf16 v[24:27], v[230:233], v[194:197], v[0:3]
	v_mfma_f32_16x16x32_bf16 v[0:3], v[234:237], v[190:193], v[182:185]
	v_mfma_f32_16x16x32_bf16 v[16:19], v[238:241], v[194:197], v[0:3]
	v_mfma_f32_16x16x32_bf16 v[0:3], v[206:209], v[218:221], v[186:189]
	v_mfma_f32_16x16x32_bf16 v[8:11], v[230:233], v[222:225], v[0:3]
	v_mfma_f32_16x16x32_bf16 v[0:3], v[234:237], v[218:221], v[166:169]
	v_mfma_f32_16x16x32_bf16 v[0:3], v[238:241], v[222:225], v[0:3]
	s_setprio 0
	s_barrier
	s_andn2_b64 vcc, exec, s[42:43]
	s_cbranch_vccnz .LBB0_696
	s_barrier

.LBB0_714:
	s_add_u32 s8, s6, 0xfffc0080
	s_addc_u32 s9, s7, -1
	s_add_i32 s35, 0, 0x10000
	s_cmp_eq_u32 s59, 12
	s_cselect_b32 s11, s24, s9
	s_cselect_b32 s10, s51, s8
	v_add_u32_e32 v138, s35, v164
	s_cselect_b32 s9, s49, s58
	s_cselect_b32 s8, s56, s57
	s_add_i32 s66, 0, 0x14000
	ds_read_b128 v[158:161], v138
	ds_read_b128 v[166:169], v138 offset:1024
	ds_read_b128 v[170:173], v138 offset:2048
	ds_read_b128 v[174:177], v138 offset:3072
	v_add_u32_e32 v138, s66, v164
	ds_read_b128 v[178:181], v138
	ds_read_b128 v[182:185], v138 offset:1024
	ds_read_b128 v[206:209], v138 offset:2048
	ds_read_b128 v[210:213], v138 offset:3072
	v_lshl_add_u64 v[138:139], s[6:7], 0, v[134:135]
	s_add_i32 m0, s17, 0xc000
	ds_read_b128 v[214:217], v165
	ds_read_b128 v[218:221], v165 offset:1024
	ds_read_b128 v[222:225], v165 offset:2048
	ds_read_b128 v[226:229], v165 offset:3072
	ds_read_b128 v[230:233], v165 offset:4096
	ds_read_b128 v[234:237], v165 offset:5120
	ds_read_b128 v[238:241], v165 offset:6144
	ds_read_b128 v[242:245], v165 offset:7168
	global_load_lds_dwordx4 v[138:139], off
	v_lshl_add_u64 v[138:139], s[6:7], 0, v[136:137]
	s_add_i32 m0, s17, 0xe000
	s_nop 0
	global_load_lds_dwordx4 v[138:139], off
	s_waitcnt vmcnt(8)
	s_waitcnt lgkmcnt(0)
	s_barrier
	s_setprio 1
	s_waitcnt lgkmcnt(0)
	v_mfma_f32_16x16x32_bf16 v[124:127], v[158:161], v[214:217], v[124:127]
	v_mfma_f32_16x16x32_bf16 v[120:123], v[170:173], v[214:217], v[120:123]
	v_mfma_f32_16x16x32_bf16 v[108:111], v[158:161], v[222:225], v[108:111]
	v_mfma_f32_16x16x32_bf16 v[104:107], v[170:173], v[222:225], v[104:107]
	v_mfma_f32_16x16x32_bf16 v[92:95], v[158:161], v[230:233], v[92:95]
	v_mfma_f32_16x16x32_bf16 v[88:91], v[170:173], v[230:233], v[88:91]
	v_mfma_f32_16x16x32_bf16 v[76:79], v[158:161], v[238:241], v[76:79]
	v_mfma_f32_16x16x32_bf16 v[72:75], v[170:173], v[238:241], v[72:75]
	v_mfma_f32_16x16x32_bf16 v[124:127], v[166:169], v[218:221], v[124:127]
	v_mfma_f32_16x16x32_bf16 v[120:123], v[174:177], v[218:221], v[120:123]
	v_mfma_f32_16x16x32_bf16 v[108:111], v[166:169], v[226:229], v[108:111]
	v_mfma_f32_16x16x32_bf16 v[104:107], v[174:177], v[226:229], v[104:107]
	v_mfma_f32_16x16x32_bf16 v[92:95], v[166:169], v[234:237], v[92:95]
	v_mfma_f32_16x16x32_bf16 v[88:91], v[174:177], v[234:237], v[88:91]
	v_mfma_f32_16x16x32_bf16 v[76:79], v[166:169], v[242:245], v[76:79]
	v_mfma_f32_16x16x32_bf16 v[72:75], v[174:177], v[242:245], v[72:75]
	v_mfma_f32_16x16x32_bf16 v[116:119], v[178:181], v[214:217], v[116:119]
	v_mfma_f32_16x16x32_bf16 v[112:115], v[206:209], v[214:217], v[112:115]
	v_mfma_f32_16x16x32_bf16 v[100:103], v[178:181], v[222:225], v[100:103]
	v_mfma_f32_16x16x32_bf16 v[96:99], v[206:209], v[222:225], v[96:99]
	v_mfma_f32_16x16x32_bf16 v[84:87], v[178:181], v[230:233], v[84:87]
	v_mfma_f32_16x16x32_bf16 v[80:83], v[206:209], v[230:233], v[80:83]
	v_mfma_f32_16x16x32_bf16 v[68:71], v[178:181], v[238:241], v[68:71]
	v_mfma_f32_16x16x32_bf16 v[64:67], v[206:209], v[238:241], v[64:67]
	v_mfma_f32_16x16x32_bf16 v[116:119], v[182:185], v[218:221], v[116:119]
	v_mfma_f32_16x16x32_bf16 v[112:115], v[210:213], v[218:221], v[112:115]
	v_mfma_f32_16x16x32_bf16 v[100:103], v[182:185], v[226:229], v[100:103]
	v_mfma_f32_16x16x32_bf16 v[96:99], v[210:213], v[226:229], v[96:99]
	v_mfma_f32_16x16x32_bf16 v[84:87], v[182:185], v[234:237], v[84:87]
	v_mfma_f32_16x16x32_bf16 v[80:83], v[210:213], v[234:237], v[80:83]
	v_mfma_f32_16x16x32_bf16 v[68:71], v[182:185], v[242:245], v[68:71]
	v_mfma_f32_16x16x32_bf16 v[64:67], v[210:213], v[242:245], v[64:67]
	s_setprio 0
	s_barrier
	s_add_i32 s35, s35, s14
	v_lshl_add_u64 v[138:139], s[8:9], 0, v[140:141]
	s_mov_b32 m0, s35
	ds_read_b128 v[214:217], v165 offset:16384
	ds_read_b128 v[218:221], v165 offset:17408
	ds_read_b128 v[222:225], v165 offset:18432
	ds_read_b128 v[226:229], v165 offset:19456
	ds_read_b128 v[230:233], v165 offset:20480
	ds_read_b128 v[234:237], v165 offset:21504
	ds_read_b128 v[238:241], v165 offset:22528
	ds_read_b128 v[242:245], v165 offset:23552
	global_load_lds_dwordx4 v[138:139], off
	s_add_i32 m0, s35, 0x2000
	s_add_u32 s60, s8, 0x40000
	v_lshl_add_u64 v[142:143], s[8:9], 0, v[128:129]
	s_addc_u32 s61, s9, 0
	s_add_i32 s35, s66, s14
	global_load_lds_dwordx4 v[142:143], off
	v_lshl_add_u64 v[144:145], s[60:61], 0, v[140:141]
	s_mov_b32 m0, s35
	v_lshl_add_u64 v[146:147], s[10:11], 0, v[130:131]
	global_load_lds_dwordx4 v[144:145], off
	v_lshl_add_u64 v[144:145], s[60:61], 0, v[128:129]
	s_add_i32 m0, s35, 0x2000
	s_nop 0
	global_load_lds_dwordx4 v[144:145], off
	v_lshl_add_u64 v[144:145], s[10:11], 0, v[132:133]
	s_mov_b32 m0, s17
	s_nop 0
	global_load_lds_dwordx4 v[144:145], off
	s_mov_b32 m0, s25
	s_nop 0
	global_load_lds_dwordx4 v[146:147], off
	s_waitcnt vmcnt(8)
	s_waitcnt lgkmcnt(0)
	s_barrier
	s_setprio 1
	s_waitcnt lgkmcnt(0)
	v_mfma_f32_16x16x32_bf16 v[60:63], v[158:161], v[214:217], v[60:63]
	v_mfma_f32_16x16x32_bf16 v[56:59], v[170:173], v[214:217], v[56:59]
	v_mfma_f32_16x16x32_bf16 v[44:47], v[158:161], v[222:225], v[44:47]
	v_mfma_f32_16x16x32_bf16 v[40:43], v[170:173], v[222:225], v[40:43]
	v_mfma_f32_16x16x32_bf16 v[28:31], v[158:161], v[230:233], v[28:31]
	v_mfma_f32_16x16x32_bf16 v[24:27], v[170:173], v[230:233], v[24:27]
	v_mfma_f32_16x16x32_bf16 v[12:15], v[158:161], v[238:241], v[12:15]
	v_mfma_f32_16x16x32_bf16 v[8:11], v[170:173], v[238:241], v[8:11]
	v_mfma_f32_16x16x32_bf16 v[60:63], v[166:169], v[218:221], v[60:63]
	v_mfma_f32_16x16x32_bf16 v[56:59], v[174:177], v[218:221], v[56:59]
	v_mfma_f32_16x16x32_bf16 v[44:47], v[166:169], v[226:229], v[44:47]
	v_mfma_f32_16x16x32_bf16 v[40:43], v[174:177], v[226:229], v[40:43]
	v_mfma_f32_16x16x32_bf16 v[28:31], v[166:169], v[234:237], v[28:31]
	v_mfma_f32_16x16x32_bf16 v[24:27], v[174:177], v[234:237], v[24:27]
	v_mfma_f32_16x16x32_bf16 v[12:15], v[166:169], v[242:245], v[12:15]
	v_mfma_f32_16x16x32_bf16 v[8:11], v[174:177], v[242:245], v[8:11]
	v_mfma_f32_16x16x32_bf16 v[52:55], v[178:181], v[214:217], v[52:55]
	v_mfma_f32_16x16x32_bf16 v[48:51], v[206:209], v[214:217], v[48:51]
	v_mfma_f32_16x16x32_bf16 v[36:39], v[178:181], v[222:225], v[36:39]
	v_mfma_f32_16x16x32_bf16 v[32:35], v[206:209], v[222:225], v[32:35]
	v_mfma_f32_16x16x32_bf16 v[20:23], v[178:181], v[230:233], v[20:23]
	v_mfma_f32_16x16x32_bf16 v[16:19], v[206:209], v[230:233], v[16:19]
	v_mfma_f32_16x16x32_bf16 v[4:7], v[178:181], v[238:241], v[4:7]
	v_mfma_f32_16x16x32_bf16 v[0:3], v[206:209], v[238:241], v[0:3]
	v_mfma_f32_16x16x32_bf16 v[52:55], v[182:185], v[218:221], v[52:55]
	v_mfma_f32_16x16x32_bf16 v[48:51], v[210:213], v[218:221], v[48:51]
	v_mfma_f32_16x16x32_bf16 v[36:39], v[182:185], v[226:229], v[36:39]
	v_mfma_f32_16x16x32_bf16 v[32:35], v[210:213], v[226:229], v[32:35]
	v_mfma_f32_16x16x32_bf16 v[20:23], v[182:185], v[234:237], v[20:23]
	v_mfma_f32_16x16x32_bf16 v[16:19], v[210:213], v[234:237], v[16:19]
	v_mfma_f32_16x16x32_bf16 v[4:7], v[182:185], v[242:245], v[4:7]
	v_mfma_f32_16x16x32_bf16 v[0:3], v[210:213], v[242:245], v[0:3]
	s_setprio 0
	s_barrier
	s_add_i32 s35, 0, 0x18000
	v_add_u32_e32 v148, s35, v164
	s_add_i32 s60, 0, 0x1c000
	ds_read_b128 v[158:161], v148
	ds_read_b128 v[166:169], v148 offset:1024
	ds_read_b128 v[170:173], v148 offset:2048
	ds_read_b128 v[174:177], v148 offset:3072
	v_add_u32_e32 v148, s60, v164
	ds_read_b128 v[178:181], v148
	ds_read_b128 v[182:185], v148 offset:1024
	ds_read_b128 v[206:209], v148 offset:2048
	ds_read_b128 v[210:213], v148 offset:3072
	s_add_u32 s10, s10, 0x40000
	s_addc_u32 s11, s11, 0
	s_mov_b32 m0, s26
	v_lshl_add_u64 v[148:149], s[10:11], 0, v[132:133]
	ds_read_b128 v[214:217], v165 offset:32768
	ds_read_b128 v[218:221], v165 offset:33792
	ds_read_b128 v[222:225], v165 offset:34816
	ds_read_b128 v[226:229], v165 offset:35840
	ds_read_b128 v[230:233], v165 offset:36864
	ds_read_b128 v[234:237], v165 offset:37888
	ds_read_b128 v[238:241], v165 offset:38912
	ds_read_b128 v[242:245], v165 offset:39936
	global_load_lds_dwordx4 v[148:149], off
	v_lshl_add_u64 v[148:149], s[10:11], 0, v[130:131]
	s_mov_b32 m0, s27
	s_nop 0
	global_load_lds_dwordx4 v[148:149], off
	s_waitcnt vmcnt(8)
	s_waitcnt lgkmcnt(0)
	s_barrier
	s_setprio 1
	s_waitcnt lgkmcnt(0)
	v_mfma_f32_16x16x32_bf16 v[124:127], v[158:161], v[214:217], v[124:127]
	v_mfma_f32_16x16x32_bf16 v[120:123], v[170:173], v[214:217], v[120:123]
	v_mfma_f32_16x16x32_bf16 v[108:111], v[158:161], v[222:225], v[108:111]
	v_mfma_f32_16x16x32_bf16 v[104:107], v[170:173], v[222:225], v[104:107]
	v_mfma_f32_16x16x32_bf16 v[92:95], v[158:161], v[230:233], v[92:95]
	v_mfma_f32_16x16x32_bf16 v[88:91], v[170:173], v[230:233], v[88:91]
	v_mfma_f32_16x16x32_bf16 v[76:79], v[158:161], v[238:241], v[76:79]
	v_mfma_f32_16x16x32_bf16 v[72:75], v[170:173], v[238:241], v[72:75]
	v_mfma_f32_16x16x32_bf16 v[124:127], v[166:169], v[218:221], v[124:127]
	v_mfma_f32_16x16x32_bf16 v[120:123], v[174:177], v[218:221], v[120:123]
	v_mfma_f32_16x16x32_bf16 v[108:111], v[166:169], v[226:229], v[108:111]
	v_mfma_f32_16x16x32_bf16 v[104:107], v[174:177], v[226:229], v[104:107]
	v_mfma_f32_16x16x32_bf16 v[92:95], v[166:169], v[234:237], v[92:95]
	v_mfma_f32_16x16x32_bf16 v[88:91], v[174:177], v[234:237], v[88:91]
	v_mfma_f32_16x16x32_bf16 v[76:79], v[166:169], v[242:245], v[76:79]
	v_mfma_f32_16x16x32_bf16 v[72:75], v[174:177], v[242:245], v[72:75]
	v_mfma_f32_16x16x32_bf16 v[116:119], v[178:181], v[214:217], v[116:119]
	v_mfma_f32_16x16x32_bf16 v[112:115], v[206:209], v[214:217], v[112:115]
	v_mfma_f32_16x16x32_bf16 v[100:103], v[178:181], v[222:225], v[100:103]
	v_mfma_f32_16x16x32_bf16 v[96:99], v[206:209], v[222:225], v[96:99]
	v_mfma_f32_16x16x32_bf16 v[84:87], v[178:181], v[230:233], v[84:87]
	v_mfma_f32_16x16x32_bf16 v[80:83], v[206:209], v[230:233], v[80:83]
	v_mfma_f32_16x16x32_bf16 v[68:71], v[178:181], v[238:241], v[68:71]
	v_mfma_f32_16x16x32_bf16 v[64:67], v[206:209], v[238:241], v[64:67]
	v_mfma_f32_16x16x32_bf16 v[116:119], v[182:185], v[218:221], v[116:119]
	v_mfma_f32_16x16x32_bf16 v[112:115], v[210:213], v[218:221], v[112:115]
	v_mfma_f32_16x16x32_bf16 v[100:103], v[182:185], v[226:229], v[100:103]
	v_mfma_f32_16x16x32_bf16 v[96:99], v[210:213], v[226:229], v[96:99]
	v_mfma_f32_16x16x32_bf16 v[84:87], v[182:185], v[234:237], v[84:87]
	v_mfma_f32_16x16x32_bf16 v[80:83], v[210:213], v[234:237], v[80:83]
	v_mfma_f32_16x16x32_bf16 v[68:71], v[182:185], v[242:245], v[68:71]
	v_mfma_f32_16x16x32_bf16 v[64:67], v[210:213], v[242:245], v[64:67]
	s_setprio 0
	s_barrier
	s_add_i32 s10, s35, s14
	v_lshl_add_u64 v[138:139], v[138:139], 0, s[36:37]
	s_mov_b32 m0, s10
	ds_read_b128 v[214:217], v165 offset:49152
	ds_read_b128 v[218:221], v165 offset:50176
	ds_read_b128 v[222:225], v165 offset:51200
	ds_read_b128 v[226:229], v165 offset:52224
	ds_read_b128 v[230:233], v165 offset:53248
	ds_read_b128 v[234:237], v165 offset:54272
	ds_read_b128 v[238:241], v165 offset:55296
	ds_read_b128 v[242:245], v165 offset:56320
	global_load_lds_dwordx4 v[138:139], off
	s_add_i32 m0, s10, 0x2000
	s_add_u32 s8, s8, 0x40080
	v_lshl_add_u64 v[138:139], v[142:143], 0, s[36:37]
	s_addc_u32 s9, s9, 0
	s_add_i32 s10, s60, s14
	global_load_lds_dwordx4 v[138:139], off
	v_lshl_add_u64 v[138:139], s[8:9], 0, v[140:141]
	s_mov_b32 m0, s10
	s_nop 0
	global_load_lds_dwordx4 v[138:139], off
	v_lshl_add_u64 v[138:139], s[8:9], 0, v[128:129]
	s_add_i32 m0, s10, 0x2000
	s_nop 0
	global_load_lds_dwordx4 v[138:139], off
	v_lshl_add_u64 v[138:139], v[144:145], 0, s[36:37]
	s_mov_b32 m0, s28
	s_nop 0
	global_load_lds_dwordx4 v[138:139], off
	v_lshl_add_u64 v[138:139], v[146:147], 0, s[36:37]
	s_mov_b32 m0, s29
	s_nop 0
	global_load_lds_dwordx4 v[138:139], off
	s_waitcnt vmcnt(8)
	s_waitcnt lgkmcnt(0)
	s_barrier
	s_setprio 1
	s_waitcnt lgkmcnt(0)
	v_mfma_f32_16x16x32_bf16 v[60:63], v[158:161], v[214:217], v[60:63]
	v_mfma_f32_16x16x32_bf16 v[56:59], v[170:173], v[214:217], v[56:59]
	v_mfma_f32_16x16x32_bf16 v[44:47], v[158:161], v[222:225], v[44:47]
	v_mfma_f32_16x16x32_bf16 v[40:43], v[170:173], v[222:225], v[40:43]
	v_mfma_f32_16x16x32_bf16 v[28:31], v[158:161], v[230:233], v[28:31]
	v_mfma_f32_16x16x32_bf16 v[24:27], v[170:173], v[230:233], v[24:27]
	v_mfma_f32_16x16x32_bf16 v[12:15], v[158:161], v[238:241], v[12:15]
	v_mfma_f32_16x16x32_bf16 v[8:11], v[170:173], v[238:241], v[8:11]
	v_mfma_f32_16x16x32_bf16 v[60:63], v[166:169], v[218:221], v[60:63]
	v_mfma_f32_16x16x32_bf16 v[56:59], v[174:177], v[218:221], v[56:59]
	v_mfma_f32_16x16x32_bf16 v[44:47], v[166:169], v[226:229], v[44:47]
	v_mfma_f32_16x16x32_bf16 v[40:43], v[174:177], v[226:229], v[40:43]
	v_mfma_f32_16x16x32_bf16 v[28:31], v[166:169], v[234:237], v[28:31]
	v_mfma_f32_16x16x32_bf16 v[24:27], v[174:177], v[234:237], v[24:27]
	v_mfma_f32_16x16x32_bf16 v[12:15], v[166:169], v[242:245], v[12:15]
	v_mfma_f32_16x16x32_bf16 v[8:11], v[174:177], v[242:245], v[8:11]
	v_mfma_f32_16x16x32_bf16 v[52:55], v[178:181], v[214:217], v[52:55]
	v_mfma_f32_16x16x32_bf16 v[48:51], v[206:209], v[214:217], v[48:51]
	v_mfma_f32_16x16x32_bf16 v[36:39], v[178:181], v[222:225], v[36:39]
	v_mfma_f32_16x16x32_bf16 v[32:35], v[206:209], v[222:225], v[32:35]
	v_mfma_f32_16x16x32_bf16 v[20:23], v[178:181], v[230:233], v[20:23]
	v_mfma_f32_16x16x32_bf16 v[16:19], v[206:209], v[230:233], v[16:19]
	v_mfma_f32_16x16x32_bf16 v[4:7], v[178:181], v[238:241], v[4:7]
	v_mfma_f32_16x16x32_bf16 v[0:3], v[206:209], v[238:241], v[0:3]
	v_mfma_f32_16x16x32_bf16 v[52:55], v[182:185], v[218:221], v[52:55]
	v_mfma_f32_16x16x32_bf16 v[48:51], v[210:213], v[218:221], v[48:51]
	v_mfma_f32_16x16x32_bf16 v[36:39], v[182:185], v[226:229], v[36:39]
	v_mfma_f32_16x16x32_bf16 v[32:35], v[210:213], v[226:229], v[32:35]
	v_mfma_f32_16x16x32_bf16 v[20:23], v[182:185], v[234:237], v[20:23]
	v_mfma_f32_16x16x32_bf16 v[16:19], v[210:213], v[234:237], v[16:19]
	v_mfma_f32_16x16x32_bf16 v[4:7], v[182:185], v[242:245], v[4:7]
	v_mfma_f32_16x16x32_bf16 v[0:3], v[210:213], v[242:245], v[0:3]
	s_setprio 0
	s_barrier
	s_add_i32 s59, s59, 2
	s_add_u32 s6, s6, 0x100
	s_addc_u32 s7, s7, 0
	s_add_u32 s57, s57, 0x100
	s_addc_u32 s58, s58, 0
	s_cmp_gt_u32 s59, 13
	s_cbranch_scc0 .LBB0_714
	s_and_b64 vcc, exec, s[46:47]
	s_cbranch_vccz .LBB0_717
	s_barrier
